# e4 stats preload+rsq, ts hoist p12, pre-MFMA barrier moved 8 MFMAs down in all GEMM loops
# baseline (speedup 1.0000x reference)
; #define PG8_STAGE(bufoff, gbase, voff) do { _Pragma("unroll") for (int _i = 0; _i < 2; ++_i) \
;         __builtin_amdgcn_global_load_lds((const unsigned*)((const char*)(gbase) + (voff)[_i]), (LAS unsigned*)(lds + (bufoff) + ldsw + _i * 8192), 16, 0, 0); } while (0)
; #define PG8_LDA(dst, b, h) do { _Pragma("unroll") for (int m = 0; m < 4; ++m) _Pragma("unroll") for (int k = 0; k < 2; ++k) dst[m][k] = *(const LAS bf16x8*)(lds + PG8_SA(b, h) + aoff + m * 2048 + k * 1024); } while (0)
; #define PG8_LDB(dst, b, h) do { _Pragma("unroll") for (int n = 0; n < 2; ++n) _Pragma("unroll") for (int k = 0; k < 2; ++k) dst[n][k] = *(const LAS bf16x8*)(lds + PG8_SB(b, h) + boff + n * 2048 + k * 1024); } while (0)
; #define PG8_WAIT_V(n) asm volatile("s_waitcnt vmcnt(" #n ")" ::: "memory")
; #define PG8_WAIT_L(n) asm volatile("s_waitcnt lgkmcnt(" #n ")" ::: "memory")
; #define PG8_BAR __builtin_amdgcn_s_barrier()
; #define PG8_SCHED __builtin_amdgcn_sched_barrier(0)
;     ...
;         for (int t = 0; t < nt; t += 2) {
;             const bool last = (t == nt - 2);
;             const char* a1 = cA + (size_t)(t + 1) * kstep;
;             const char* a2 = last ? nA : cA + (size_t)(t + 2) * kstep; const char* b2 = last ? nB : cB + (size_t)(t + 2) * kstep;
;             const char* a3 = a2 + kstep; const char* b3 = b2 + kstep;
;             PG8_LDB(B0, 0, 0); PG8_LDB(B1, 0, 1); PG8_SCHED; PG8_LDA(At, 0, 0); PG8_STAGE(PG8_SA(1, 1), a1 + hstep, voffA);
;             PG8_WAIT_V(8); PG8_WAIT_L(0); PG8_BAR; PG8_MMA(0, 0, At, B0); PG8_MMA(0, 1, At, B1); PG8_BAR; PG8_SCHED;
;             PG8_LDA(At, 0, 1); PG8_STAGE(PG8_SB(0, 0), b2, voffB); PG8_STAGE(PG8_SB(0, 1), b2 + hstep, voffB); PG8_STAGE(PG8_SA(0, 0), a2, voffA);
;             PG8_WAIT_V(8); PG8_WAIT_L(0); PG8_BAR; PG8_MMA(1, 0, At, B0); PG8_MMA(1, 1, At, B1); PG8_BAR; PG8_SCHED;
;             PG8_LDB(B0, 1, 0); PG8_LDB(B1, 1, 1); PG8_SCHED; PG8_LDA(At, 1, 0); PG8_STAGE(PG8_SA(0, 1), a2 + hstep, voffA);
;             PG8_WAIT_V(8); PG8_WAIT_L(0); PG8_BAR; PG8_MMA(0, 0, At, B0); PG8_MMA(0, 1, At, B1); PG8_BAR; PG8_SCHED;
;             PG8_LDA(At, 1, 1); PG8_STAGE(PG8_SB(1, 0), b3, voffB); PG8_STAGE(PG8_SB(1, 1), b3 + hstep, voffB); PG8_STAGE(PG8_SA(1, 0), a3, voffA);
;             PG8_WAIT_V(8); PG8_WAIT_L(0); PG8_BAR; PG8_MMA(1, 0, At, B0); PG8_MMA(1, 1, At, B1); PG8_BAR; PG8_SCHED;
.LBB0_1084:
	ds_read_b128 v[128:131], v166
	ds_read_b128 v[132:135], v166 offset:1024
	ds_read_b128 v[158:161], v166 offset:2048
	ds_read_b128 v[172:175], v166 offset:3072
	ds_read_b128 v[176:179], v167
	ds_read_b128 v[180:183], v167 offset:1024
	ds_read_b128 v[184:187], v167 offset:2048
	ds_read_b128 v[188:191], v167 offset:3072
	s_add_u32 s30, s28, 0xfffc0080
	s_addc_u32 s31, s29, -1
	s_cmp_eq_u32 s60, 12
	s_cselect_b32 s37, s7, s31
	s_cselect_b32 s36, s9, s30
	s_cselect_b32 s31, s19, s59
	s_cselect_b32 s30, s21, s58
	v_lshl_add_u64 v[162:163], s[28:29], 0, v[150:151]
	s_add_i32 m0, s42, 0xc000
	ds_read_b128 v[192:195], v168
	ds_read_b128 v[196:199], v168 offset:1024
	ds_read_b128 v[200:203], v168 offset:2048
	ds_read_b128 v[204:207], v168 offset:3072
	ds_read_b128 v[208:211], v168 offset:4096
	ds_read_b128 v[212:215], v168 offset:5120
	ds_read_b128 v[216:219], v168 offset:6144
	ds_read_b128 v[220:223], v168 offset:7168
	global_load_lds_dwordx4 v[162:163], off
	v_lshl_add_u64 v[162:163], s[28:29], 0, v[152:153]
	s_add_i32 m0, s42, 0xe000
	s_nop 0
	global_load_lds_dwordx4 v[162:163], off
	s_waitcnt vmcnt(8)
	s_waitcnt lgkmcnt(0)
	s_setprio 1
	s_waitcnt lgkmcnt(0)
	v_mfma_i32_16x16x64_i8 v[124:127], v[128:131], v[192:195], v[124:127]
	v_mfma_i32_16x16x64_i8 v[120:123], v[158:161], v[192:195], v[120:123]
	v_mfma_i32_16x16x64_i8 v[108:111], v[128:131], v[200:203], v[108:111]
	v_mfma_i32_16x16x64_i8 v[104:107], v[158:161], v[200:203], v[104:107]
	v_mfma_i32_16x16x64_i8 v[92:95], v[128:131], v[208:211], v[92:95]
	v_mfma_i32_16x16x64_i8 v[88:91], v[158:161], v[208:211], v[88:91]
	v_mfma_i32_16x16x64_i8 v[76:79], v[128:131], v[216:219], v[76:79]
	v_mfma_i32_16x16x64_i8 v[72:75], v[158:161], v[216:219], v[72:75]
	s_barrier
	v_mfma_i32_16x16x64_i8 v[124:127], v[132:135], v[196:199], v[124:127]
	v_mfma_i32_16x16x64_i8 v[120:123], v[172:175], v[196:199], v[120:123]
	v_mfma_i32_16x16x64_i8 v[108:111], v[132:135], v[204:207], v[108:111]
	v_mfma_i32_16x16x64_i8 v[104:107], v[172:175], v[204:207], v[104:107]
	v_mfma_i32_16x16x64_i8 v[92:95], v[132:135], v[212:215], v[92:95]
	v_mfma_i32_16x16x64_i8 v[88:91], v[172:175], v[212:215], v[88:91]
	v_mfma_i32_16x16x64_i8 v[76:79], v[132:135], v[220:223], v[76:79]
	v_mfma_i32_16x16x64_i8 v[72:75], v[172:175], v[220:223], v[72:75]
	s_setprio 0
	s_setprio 1
	v_mfma_i32_16x16x64_i8 v[116:119], v[176:179], v[192:195], v[116:119]
	v_mfma_i32_16x16x64_i8 v[112:115], v[184:187], v[192:195], v[112:115]
	v_mfma_i32_16x16x64_i8 v[100:103], v[176:179], v[200:203], v[100:103]
	v_mfma_i32_16x16x64_i8 v[96:99], v[184:187], v[200:203], v[96:99]
	v_mfma_i32_16x16x64_i8 v[84:87], v[176:179], v[208:211], v[84:87]
	v_mfma_i32_16x16x64_i8 v[80:83], v[184:187], v[208:211], v[80:83]
	v_mfma_i32_16x16x64_i8 v[68:71], v[176:179], v[216:219], v[68:71]
	v_mfma_i32_16x16x64_i8 v[64:67], v[184:187], v[216:219], v[64:67]
	v_mfma_i32_16x16x64_i8 v[116:119], v[180:183], v[196:199], v[116:119]
	v_mfma_i32_16x16x64_i8 v[112:115], v[188:191], v[196:199], v[112:115]
	v_mfma_i32_16x16x64_i8 v[100:103], v[180:183], v[204:207], v[100:103]
	v_mfma_i32_16x16x64_i8 v[96:99], v[188:191], v[204:207], v[96:99]
	v_mfma_i32_16x16x64_i8 v[84:87], v[180:183], v[212:215], v[84:87]
	v_mfma_i32_16x16x64_i8 v[80:83], v[188:191], v[212:215], v[80:83]
	v_mfma_i32_16x16x64_i8 v[68:71], v[180:183], v[220:223], v[68:71]
	v_mfma_i32_16x16x64_i8 v[64:67], v[188:191], v[220:223], v[64:67]
	s_setprio 0
	s_barrier
	s_add_i32 s61, s54, s39
	v_lshl_add_u64 v[162:163], s[30:31], 0, v[138:139]
	s_mov_b32 m0, s61
	ds_read_b128 v[192:195], v168 offset:16384
	ds_read_b128 v[196:199], v168 offset:17408
	ds_read_b128 v[200:203], v168 offset:18432
	ds_read_b128 v[204:207], v168 offset:19456
	ds_read_b128 v[208:211], v168 offset:20480
	ds_read_b128 v[212:215], v168 offset:21504
	ds_read_b128 v[216:219], v168 offset:22528
	ds_read_b128 v[220:223], v168 offset:23552
	global_load_lds_dwordx4 v[162:163], off
	s_add_i32 m0, s61, 0x2000
	s_add_u32 s62, s30, 0x40000
	v_lshl_add_u64 v[224:225], s[30:31], 0, v[142:143]
	s_addc_u32 s63, s31, 0
	s_add_i32 s61, s55, s39
	global_load_lds_dwordx4 v[224:225], off
	v_lshl_add_u64 v[226:227], s[62:63], 0, v[138:139]
	s_mov_b32 m0, s61
	v_lshl_add_u64 v[228:229], s[36:37], 0, v[140:141]
	global_load_lds_dwordx4 v[226:227], off
	v_lshl_add_u64 v[226:227], s[62:63], 0, v[142:143]
	s_add_i32 m0, s61, 0x2000
	s_nop 0
	global_load_lds_dwordx4 v[226:227], off
	v_lshl_add_u64 v[226:227], s[36:37], 0, v[136:137]
	s_mov_b32 m0, s42
	s_nop 0
	global_load_lds_dwordx4 v[226:227], off
	s_mov_b32 m0, s43
	s_nop 0
	global_load_lds_dwordx4 v[228:229], off
	s_waitcnt vmcnt(8)
	s_waitcnt lgkmcnt(0)
	s_setprio 1
	s_waitcnt lgkmcnt(0)
	v_mfma_i32_16x16x64_i8 v[60:63], v[128:131], v[192:195], v[60:63]
	v_mfma_i32_16x16x64_i8 v[56:59], v[158:161], v[192:195], v[56:59]
	v_mfma_i32_16x16x64_i8 v[44:47], v[128:131], v[200:203], v[44:47]
	v_mfma_i32_16x16x64_i8 v[40:43], v[158:161], v[200:203], v[40:43]
	v_mfma_i32_16x16x64_i8 v[28:31], v[128:131], v[208:211], v[28:31]
	v_mfma_i32_16x16x64_i8 v[24:27], v[158:161], v[208:211], v[24:27]
	v_mfma_i32_16x16x64_i8 v[12:15], v[128:131], v[216:219], v[12:15]
	v_mfma_i32_16x16x64_i8 v[8:11], v[158:161], v[216:219], v[8:11]
	s_barrier
; #define PG8_STAGE(bufoff, gbase, voff) do { _Pragma("unroll") for (int _i = 0; _i < 2; ++_i) \
;         __builtin_amdgcn_global_load_lds((const unsigned*)((const char*)(gbase) + (voff)[_i]), (LAS unsigned*)(lds + (bufoff) + ldsw + _i * 8192), 16, 0, 0); } while (0)
; #define PG8_LDA(dst, b, h) do { _Pragma("unroll") for (int m = 0; m < 4; ++m) _Pragma("unroll") for (int k = 0; k < 2; ++k) dst[m][k] = *(const LAS bf16x8*)(lds + PG8_SA(b, h) + aoff + m * 2048 + k * 1024); } while (0)
; #define PG8_LDB(dst, b, h) do { _Pragma("unroll") for (int n = 0; n < 2; ++n) _Pragma("unroll") for (int k = 0; k < 2; ++k) dst[n][k] = *(const LAS bf16x8*)(lds + PG8_SB(b, h) + boff + n * 2048 + k * 1024); } while (0)
; #define PG8_WAIT_V(n) asm volatile("s_waitcnt vmcnt(" #n ")" ::: "memory")
; #define PG8_WAIT_L(n) asm volatile("s_waitcnt lgkmcnt(" #n ")" ::: "memory")
; #define PG8_BAR __builtin_amdgcn_s_barrier()
; #define PG8_SCHED __builtin_amdgcn_sched_barrier(0)
;     ...
;         for (int t = 0; t < nt; t += 2) {
;             const bool last = (t == nt - 2);
;             const char* a1 = cA + (size_t)(t + 1) * kstep;
;             const char* a2 = last ? nA : cA + (size_t)(t + 2) * kstep; const char* b2 = last ? nB : cB + (size_t)(t + 2) * kstep;
;             const char* a3 = a2 + kstep; const char* b3 = b2 + kstep;
;             PG8_LDB(B0, 0, 0); PG8_LDB(B1, 0, 1); PG8_SCHED; PG8_LDA(At, 0, 0); PG8_STAGE(PG8_SA(1, 1), a1 + hstep, voffA);
;             PG8_WAIT_V(8); PG8_WAIT_L(0); PG8_BAR; PG8_MMA(0, 0, At, B0); PG8_MMA(0, 1, At, B1); PG8_BAR; PG8_SCHED;
;             PG8_LDA(At, 0, 1); PG8_STAGE(PG8_SB(0, 0), b2, voffB); PG8_STAGE(PG8_SB(0, 1), b2 + hstep, voffB); PG8_STAGE(PG8_SA(0, 0), a2, voffA);
;             PG8_WAIT_V(8); PG8_WAIT_L(0); PG8_BAR; PG8_MMA(1, 0, At, B0); PG8_MMA(1, 1, At, B1); PG8_BAR; PG8_SCHED;
;             PG8_LDB(B0, 1, 0); PG8_LDB(B1, 1, 1); PG8_SCHED; PG8_LDA(At, 1, 0); PG8_STAGE(PG8_SA(0, 1), a2 + hstep, voffA);
;             PG8_WAIT_V(8); PG8_WAIT_L(0); PG8_BAR; PG8_MMA(0, 0, At, B0); PG8_MMA(0, 1, At, B1); PG8_BAR; PG8_SCHED;
;             PG8_LDA(At, 1, 1); PG8_STAGE(PG8_SB(1, 0), b3, voffB); PG8_STAGE(PG8_SB(1, 1), b3 + hstep, voffB); PG8_STAGE(PG8_SA(1, 0), a3, voffA);
;             PG8_WAIT_V(8); PG8_WAIT_L(0); PG8_BAR; PG8_MMA(1, 0, At, B0); PG8_MMA(1, 1, At, B1); PG8_BAR; PG8_SCHED;
	v_mfma_i32_16x16x64_i8 v[60:63], v[132:135], v[196:199], v[60:63]
	v_mfma_i32_16x16x64_i8 v[56:59], v[172:175], v[196:199], v[56:59]
	v_mfma_i32_16x16x64_i8 v[44:47], v[132:135], v[204:207], v[44:47]
	v_mfma_i32_16x16x64_i8 v[40:43], v[172:175], v[204:207], v[40:43]
	v_mfma_i32_16x16x64_i8 v[28:31], v[132:135], v[212:215], v[28:31]
	v_mfma_i32_16x16x64_i8 v[24:27], v[172:175], v[212:215], v[24:27]
	v_mfma_i32_16x16x64_i8 v[12:15], v[132:135], v[220:223], v[12:15]
	v_mfma_i32_16x16x64_i8 v[8:11], v[172:175], v[220:223], v[8:11]
	s_setprio 0
	s_setprio 1
	v_mfma_i32_16x16x64_i8 v[52:55], v[176:179], v[192:195], v[52:55]
	v_mfma_i32_16x16x64_i8 v[48:51], v[184:187], v[192:195], v[48:51]
	v_mfma_i32_16x16x64_i8 v[36:39], v[176:179], v[200:203], v[36:39]
	v_mfma_i32_16x16x64_i8 v[32:35], v[184:187], v[200:203], v[32:35]
	v_mfma_i32_16x16x64_i8 v[20:23], v[176:179], v[208:211], v[20:23]
	v_mfma_i32_16x16x64_i8 v[16:19], v[184:187], v[208:211], v[16:19]
	v_mfma_i32_16x16x64_i8 v[4:7], v[176:179], v[216:219], v[4:7]
	v_mfma_i32_16x16x64_i8 v[0:3], v[184:187], v[216:219], v[0:3]
	v_mfma_i32_16x16x64_i8 v[52:55], v[180:183], v[196:199], v[52:55]
	v_mfma_i32_16x16x64_i8 v[48:51], v[188:191], v[196:199], v[48:51]
	v_mfma_i32_16x16x64_i8 v[36:39], v[180:183], v[204:207], v[36:39]
	v_mfma_i32_16x16x64_i8 v[32:35], v[188:191], v[204:207], v[32:35]
	v_mfma_i32_16x16x64_i8 v[20:23], v[180:183], v[212:215], v[20:23]
	v_mfma_i32_16x16x64_i8 v[16:19], v[188:191], v[212:215], v[16:19]
	v_mfma_i32_16x16x64_i8 v[4:7], v[180:183], v[220:223], v[4:7]
	v_mfma_i32_16x16x64_i8 v[0:3], v[188:191], v[220:223], v[0:3]
	s_setprio 0
	s_barrier
	s_add_i32 s61, 0, 0x18000
	s_add_i32 s62, 0, 0x1c000
	v_add_u32_e32 v172, s61, v165
	v_add_u32_e32 v188, s62, v165
	ds_read_b128 v[128:131], v172
	ds_read_b128 v[132:135], v172 offset:1024
	ds_read_b128 v[158:161], v172 offset:2048
	ds_read_b128 v[172:175], v172 offset:3072
	ds_read_b128 v[176:179], v188
	ds_read_b128 v[180:183], v188 offset:1024
	ds_read_b128 v[184:187], v188 offset:2048
	ds_read_b128 v[188:191], v188 offset:3072
	s_add_u32 s36, s36, 0x40000
	s_addc_u32 s37, s37, 0
	s_mov_b32 m0, s44
	v_lshl_add_u64 v[230:231], s[36:37], 0, v[136:137]
	ds_read_b128 v[192:195], v168 offset:32768
	ds_read_b128 v[196:199], v168 offset:33792
	ds_read_b128 v[200:203], v168 offset:34816
	ds_read_b128 v[204:207], v168 offset:35840
	ds_read_b128 v[208:211], v168 offset:36864
	ds_read_b128 v[212:215], v168 offset:37888
	ds_read_b128 v[216:219], v168 offset:38912
	ds_read_b128 v[220:223], v168 offset:39936
	global_load_lds_dwordx4 v[230:231], off
	v_lshl_add_u64 v[230:231], s[36:37], 0, v[140:141]
	s_mov_b32 m0, s45
	s_nop 0
	global_load_lds_dwordx4 v[230:231], off
	s_waitcnt vmcnt(8)
	s_waitcnt lgkmcnt(0)
	s_setprio 1
	s_waitcnt lgkmcnt(0)
	v_mfma_i32_16x16x64_i8 v[124:127], v[128:131], v[192:195], v[124:127]
	v_mfma_i32_16x16x64_i8 v[120:123], v[158:161], v[192:195], v[120:123]
	v_mfma_i32_16x16x64_i8 v[108:111], v[128:131], v[200:203], v[108:111]
	v_mfma_i32_16x16x64_i8 v[104:107], v[158:161], v[200:203], v[104:107]
	v_mfma_i32_16x16x64_i8 v[92:95], v[128:131], v[208:211], v[92:95]
	v_mfma_i32_16x16x64_i8 v[88:91], v[158:161], v[208:211], v[88:91]
	v_mfma_i32_16x16x64_i8 v[76:79], v[128:131], v[216:219], v[76:79]
	v_mfma_i32_16x16x64_i8 v[72:75], v[158:161], v[216:219], v[72:75]
	s_barrier
	v_mfma_i32_16x16x64_i8 v[124:127], v[132:135], v[196:199], v[124:127]
	v_mfma_i32_16x16x64_i8 v[120:123], v[172:175], v[196:199], v[120:123]
	v_mfma_i32_16x16x64_i8 v[108:111], v[132:135], v[204:207], v[108:111]
	v_mfma_i32_16x16x64_i8 v[104:107], v[172:175], v[204:207], v[104:107]
	v_mfma_i32_16x16x64_i8 v[92:95], v[132:135], v[212:215], v[92:95]
	v_mfma_i32_16x16x64_i8 v[88:91], v[172:175], v[212:215], v[88:91]
	v_mfma_i32_16x16x64_i8 v[76:79], v[132:135], v[220:223], v[76:79]
	v_mfma_i32_16x16x64_i8 v[72:75], v[172:175], v[220:223], v[72:75]
	s_setprio 0
	s_setprio 1
	v_mfma_i32_16x16x64_i8 v[116:119], v[176:179], v[192:195], v[116:119]
	v_mfma_i32_16x16x64_i8 v[112:115], v[184:187], v[192:195], v[112:115]
	v_mfma_i32_16x16x64_i8 v[100:103], v[176:179], v[200:203], v[100:103]
	v_mfma_i32_16x16x64_i8 v[96:99], v[184:187], v[200:203], v[96:99]
	v_mfma_i32_16x16x64_i8 v[84:87], v[176:179], v[208:211], v[84:87]
	v_mfma_i32_16x16x64_i8 v[80:83], v[184:187], v[208:211], v[80:83]
	v_mfma_i32_16x16x64_i8 v[68:71], v[176:179], v[216:219], v[68:71]
	v_mfma_i32_16x16x64_i8 v[64:67], v[184:187], v[216:219], v[64:67]
	v_mfma_i32_16x16x64_i8 v[116:119], v[180:183], v[196:199], v[116:119]
	v_mfma_i32_16x16x64_i8 v[112:115], v[188:191], v[196:199], v[112:115]
	v_mfma_i32_16x16x64_i8 v[100:103], v[180:183], v[204:207], v[100:103]
	v_mfma_i32_16x16x64_i8 v[96:99], v[188:191], v[204:207], v[96:99]
	v_mfma_i32_16x16x64_i8 v[84:87], v[180:183], v[212:215], v[84:87]
	v_mfma_i32_16x16x64_i8 v[80:83], v[188:191], v[212:215], v[80:83]
	v_mfma_i32_16x16x64_i8 v[68:71], v[180:183], v[220:223], v[68:71]
	v_mfma_i32_16x16x64_i8 v[64:67], v[188:191], v[220:223], v[64:67]
	s_setprio 0
	s_barrier
; #define PG8_STAGE(bufoff, gbase, voff) do { _Pragma("unroll") for (int _i = 0; _i < 2; ++_i) \
;         __builtin_amdgcn_global_load_lds((const unsigned*)((const char*)(gbase) + (voff)[_i]), (LAS unsigned*)(lds + (bufoff) + ldsw + _i * 8192), 16, 0, 0); } while (0)
; #define PG8_LDA(dst, b, h) do { _Pragma("unroll") for (int m = 0; m < 4; ++m) _Pragma("unroll") for (int k = 0; k < 2; ++k) dst[m][k] = *(const LAS bf16x8*)(lds + PG8_SA(b, h) + aoff + m * 2048 + k * 1024); } while (0)
; #define PG8_LDB(dst, b, h) do { _Pragma("unroll") for (int n = 0; n < 2; ++n) _Pragma("unroll") for (int k = 0; k < 2; ++k) dst[n][k] = *(const LAS bf16x8*)(lds + PG8_SB(b, h) + boff + n * 2048 + k * 1024); } while (0)
; #define PG8_WAIT_V(n) asm volatile("s_waitcnt vmcnt(" #n ")" ::: "memory")
; #define PG8_WAIT_L(n) asm volatile("s_waitcnt lgkmcnt(" #n ")" ::: "memory")
; #define PG8_BAR __builtin_amdgcn_s_barrier()
; #define PG8_SCHED __builtin_amdgcn_sched_barrier(0)
;     ...
;         for (int t = 0; t < nt; t += 2) {
;             const bool last = (t == nt - 2);
;             const char* a1 = cA + (size_t)(t + 1) * kstep;
;             const char* a2 = last ? nA : cA + (size_t)(t + 2) * kstep; const char* b2 = last ? nB : cB + (size_t)(t + 2) * kstep;
;             const char* a3 = a2 + kstep; const char* b3 = b2 + kstep;
;             PG8_LDB(B0, 0, 0); PG8_LDB(B1, 0, 1); PG8_SCHED; PG8_LDA(At, 0, 0); PG8_STAGE(PG8_SA(1, 1), a1 + hstep, voffA);
;             PG8_WAIT_V(8); PG8_WAIT_L(0); PG8_BAR; PG8_MMA(0, 0, At, B0); PG8_MMA(0, 1, At, B1); PG8_BAR; PG8_SCHED;
;             PG8_LDA(At, 0, 1); PG8_STAGE(PG8_SB(0, 0), b2, voffB); PG8_STAGE(PG8_SB(0, 1), b2 + hstep, voffB); PG8_STAGE(PG8_SA(0, 0), a2, voffA);
;             PG8_WAIT_V(8); PG8_WAIT_L(0); PG8_BAR; PG8_MMA(1, 0, At, B0); PG8_MMA(1, 1, At, B1); PG8_BAR; PG8_SCHED;
;             PG8_LDB(B0, 1, 0); PG8_LDB(B1, 1, 1); PG8_SCHED; PG8_LDA(At, 1, 0); PG8_STAGE(PG8_SA(0, 1), a2 + hstep, voffA);
;             PG8_WAIT_V(8); PG8_WAIT_L(0); PG8_BAR; PG8_MMA(0, 0, At, B0); PG8_MMA(0, 1, At, B1); PG8_BAR; PG8_SCHED;
;             PG8_LDA(At, 1, 1); PG8_STAGE(PG8_SB(1, 0), b3, voffB); PG8_STAGE(PG8_SB(1, 1), b3 + hstep, voffB); PG8_STAGE(PG8_SA(1, 0), a3, voffA);
;             PG8_WAIT_V(8); PG8_WAIT_L(0); PG8_BAR; PG8_MMA(1, 0, At, B0); PG8_MMA(1, 1, At, B1); PG8_BAR; PG8_SCHED;
	s_add_i32 s36, s61, s39
	v_lshl_add_u64 v[162:163], v[162:163], 0, s[12:13]
	s_mov_b32 m0, s36
	ds_read_b128 v[192:195], v168 offset:49152
	ds_read_b128 v[196:199], v168 offset:50176
	ds_read_b128 v[200:203], v168 offset:51200
	ds_read_b128 v[204:207], v168 offset:52224
	ds_read_b128 v[208:211], v168 offset:53248
	ds_read_b128 v[212:215], v168 offset:54272
	ds_read_b128 v[216:219], v168 offset:55296
	ds_read_b128 v[220:223], v168 offset:56320
	global_load_lds_dwordx4 v[162:163], off
	s_add_i32 m0, s36, 0x2000
	s_add_u32 s30, s30, 0x40080
	v_lshl_add_u64 v[162:163], v[224:225], 0, s[12:13]
	s_addc_u32 s31, s31, 0
	s_add_i32 s36, s62, s39
	global_load_lds_dwordx4 v[162:163], off
	v_lshl_add_u64 v[162:163], s[30:31], 0, v[138:139]
	s_mov_b32 m0, s36
	s_nop 0
	global_load_lds_dwordx4 v[162:163], off
	v_lshl_add_u64 v[162:163], s[30:31], 0, v[142:143]
	s_add_i32 m0, s36, 0x2000
	s_nop 0
	global_load_lds_dwordx4 v[162:163], off
	v_lshl_add_u64 v[162:163], v[226:227], 0, s[12:13]
	s_mov_b32 m0, s47
	s_nop 0
	global_load_lds_dwordx4 v[162:163], off
	v_lshl_add_u64 v[162:163], v[228:229], 0, s[12:13]
	s_mov_b32 m0, s48
	s_nop 0
	global_load_lds_dwordx4 v[162:163], off
	s_waitcnt vmcnt(8)
	s_waitcnt lgkmcnt(0)
	s_setprio 1
	s_waitcnt lgkmcnt(0)
	v_mfma_i32_16x16x64_i8 v[60:63], v[128:131], v[192:195], v[60:63]
	v_mfma_i32_16x16x64_i8 v[56:59], v[158:161], v[192:195], v[56:59]
	v_mfma_i32_16x16x64_i8 v[44:47], v[128:131], v[200:203], v[44:47]
	v_mfma_i32_16x16x64_i8 v[40:43], v[158:161], v[200:203], v[40:43]
	v_mfma_i32_16x16x64_i8 v[28:31], v[128:131], v[208:211], v[28:31]
	v_mfma_i32_16x16x64_i8 v[24:27], v[158:161], v[208:211], v[24:27]
	v_mfma_i32_16x16x64_i8 v[12:15], v[128:131], v[216:219], v[12:15]
	v_mfma_i32_16x16x64_i8 v[8:11], v[158:161], v[216:219], v[8:11]
	s_barrier
	v_mfma_i32_16x16x64_i8 v[60:63], v[132:135], v[196:199], v[60:63]
	v_mfma_i32_16x16x64_i8 v[56:59], v[172:175], v[196:199], v[56:59]
	v_mfma_i32_16x16x64_i8 v[44:47], v[132:135], v[204:207], v[44:47]
	v_mfma_i32_16x16x64_i8 v[40:43], v[172:175], v[204:207], v[40:43]
	v_mfma_i32_16x16x64_i8 v[28:31], v[132:135], v[212:215], v[28:31]
	v_mfma_i32_16x16x64_i8 v[24:27], v[172:175], v[212:215], v[24:27]
	v_mfma_i32_16x16x64_i8 v[12:15], v[132:135], v[220:223], v[12:15]
	v_mfma_i32_16x16x64_i8 v[8:11], v[172:175], v[220:223], v[8:11]
	s_setprio 0
	s_setprio 1
	v_mfma_i32_16x16x64_i8 v[52:55], v[176:179], v[192:195], v[52:55]
	v_mfma_i32_16x16x64_i8 v[48:51], v[184:187], v[192:195], v[48:51]
	v_mfma_i32_16x16x64_i8 v[36:39], v[176:179], v[200:203], v[36:39]
	v_mfma_i32_16x16x64_i8 v[32:35], v[184:187], v[200:203], v[32:35]
	v_mfma_i32_16x16x64_i8 v[20:23], v[176:179], v[208:211], v[20:23]
	v_mfma_i32_16x16x64_i8 v[16:19], v[184:187], v[208:211], v[16:19]
	v_mfma_i32_16x16x64_i8 v[4:7], v[176:179], v[216:219], v[4:7]
	v_mfma_i32_16x16x64_i8 v[0:3], v[184:187], v[216:219], v[0:3]
	v_mfma_i32_16x16x64_i8 v[52:55], v[180:183], v[196:199], v[52:55]
	v_mfma_i32_16x16x64_i8 v[48:51], v[188:191], v[196:199], v[48:51]
	v_mfma_i32_16x16x64_i8 v[36:39], v[180:183], v[204:207], v[36:39]
	v_mfma_i32_16x16x64_i8 v[32:35], v[188:191], v[204:207], v[32:35]
	v_mfma_i32_16x16x64_i8 v[20:23], v[180:183], v[212:215], v[20:23]
	v_mfma_i32_16x16x64_i8 v[16:19], v[188:191], v[212:215], v[16:19]
	v_mfma_i32_16x16x64_i8 v[4:7], v[180:183], v[220:223], v[4:7]
	v_mfma_i32_16x16x64_i8 v[0:3], v[188:191], v[220:223], v[0:3]
	s_setprio 0
	s_barrier
	s_add_i32 s60, s60, 2
	s_add_u32 s28, s28, 0x100
	s_addc_u32 s29, s29, 0
	s_add_u32 s58, s58, 0x100
	s_addc_u32 s59, s59, 0
	s_cmp_gt_u32 s60, 13
	s_cbranch_scc0 .LBB0_1084
	s_and_b64 vcc, exec, s[14:15]
	s_cbranch_vccz .LBB0_1087
	s_barrier

; #define PG8_STAGE(bufoff, gbase, voff) do { _Pragma("unroll") for (int _i = 0; _i < 2; ++_i) \
;         __builtin_amdgcn_global_load_lds((const unsigned*)((const char*)(gbase) + (voff)[_i]), (LAS unsigned*)(lds + (bufoff) + ldsw + _i * 8192), 16, 0, 0); } while (0)
; #define PG8_LDA(dst, b, h) do { _Pragma("unroll") for (int m = 0; m < 4; ++m) _Pragma("unroll") for (int k = 0; k < 2; ++k) dst[m][k] = *(const LAS bf16x8*)(lds + PG8_SA(b, h) + aoff + m * 2048 + k * 1024); } while (0)
; #define PG8_LDB(dst, b, h) do { _Pragma("unroll") for (int n = 0; n < 2; ++n) _Pragma("unroll") for (int k = 0; k < 2; ++k) dst[n][k] = *(const LAS bf16x8*)(lds + PG8_SB(b, h) + boff + n * 2048 + k * 1024); } while (0)
; #define PG8_WAIT_V(n) asm volatile("s_waitcnt vmcnt(" #n ")" ::: "memory")
; #define PG8_WAIT_L(n) asm volatile("s_waitcnt lgkmcnt(" #n ")" ::: "memory")
; #define PG8_BAR __builtin_amdgcn_s_barrier()
; #define PG8_SCHED __builtin_amdgcn_sched_barrier(0)
;     ...
;         for (int t = 0; t < nt; t += 2) {
;             const bool last = (t == nt - 2);
;             const char* a1 = cA + (size_t)(t + 1) * kstep;
;             const char* a2 = last ? nA : cA + (size_t)(t + 2) * kstep; const char* b2 = last ? nB : cB + (size_t)(t + 2) * kstep;
;             const char* a3 = a2 + kstep; const char* b3 = b2 + kstep;
;             PG8_LDB(B0, 0, 0); PG8_LDB(B1, 0, 1); PG8_SCHED; PG8_LDA(At, 0, 0); PG8_STAGE(PG8_SA(1, 1), a1 + hstep, voffA);
;             PG8_WAIT_V(8); PG8_WAIT_L(0); PG8_BAR; PG8_MMA(0, 0, At, B0); PG8_MMA(0, 1, At, B1); PG8_BAR; PG8_SCHED;
;             PG8_LDA(At, 0, 1); PG8_STAGE(PG8_SB(0, 0), b2, voffB); PG8_STAGE(PG8_SB(0, 1), b2 + hstep, voffB); PG8_STAGE(PG8_SA(0, 0), a2, voffA);
;             PG8_WAIT_V(8); PG8_WAIT_L(0); PG8_BAR; PG8_MMA(1, 0, At, B0); PG8_MMA(1, 1, At, B1); PG8_BAR; PG8_SCHED;
;             PG8_LDB(B0, 1, 0); PG8_LDB(B1, 1, 1); PG8_SCHED; PG8_LDA(At, 1, 0); PG8_STAGE(PG8_SA(0, 1), a2 + hstep, voffA);
;             PG8_WAIT_V(8); PG8_WAIT_L(0); PG8_BAR; PG8_MMA(0, 0, At, B0); PG8_MMA(0, 1, At, B1); PG8_BAR; PG8_SCHED;
;             PG8_LDA(At, 1, 1); PG8_STAGE(PG8_SB(1, 0), b3, voffB); PG8_STAGE(PG8_SB(1, 1), b3 + hstep, voffB); PG8_STAGE(PG8_SA(1, 0), a3, voffA);
;             PG8_WAIT_V(8); PG8_WAIT_L(0); PG8_BAR; PG8_MMA(1, 0, At, B0); PG8_MMA(1, 1, At, B1); PG8_BAR; PG8_SCHED;
.LBB0_3686:
	ds_read_b128 v[24:27], v187
	ds_read_b128 v[28:31], v187 offset:1024
	ds_read_b128 v[16:19], v187 offset:2048
	ds_read_b128 v[20:23], v187 offset:3072
	ds_read_b128 v[8:11], v188
	ds_read_b128 v[12:15], v188 offset:1024
	s_waitcnt lgkmcnt(0)
	ds_read_b128 v[0:3], v188 offset:2048
	ds_read_b128 v[4:7], v188 offset:3072
	s_add_u32 s46, s44, 0xfffc0080
	s_addc_u32 s47, s45, -1
	s_cmp_eq_u32 s69, 12
	s_cselect_b32 s49, s31, s47
	s_cselect_b32 s48, s41, s46
	s_cselect_b32 s47, s29, s68
	s_cselect_b32 s46, s66, s67
	v_lshl_add_u64 v[218:219], s[44:45], 0, v[168:169]
	s_add_i32 m0, s35, 0xc000
	ds_read_b128 v[176:179], v189
	ds_read_b128 v[180:183], v189 offset:1024
	ds_read_b128 v[194:197], v189 offset:2048
	ds_read_b128 v[198:201], v189 offset:3072
	ds_read_b128 v[202:205], v189 offset:4096
	ds_read_b128 v[206:209], v189 offset:5120
	ds_read_b128 v[210:213], v189 offset:6144
	ds_read_b128 v[214:217], v189 offset:7168
	global_load_lds_dwordx4 v[218:219], off
	v_lshl_add_u64 v[218:219], s[44:45], 0, v[170:171]
	s_add_i32 m0, s35, 0xe000
	s_nop 0
	global_load_lds_dwordx4 v[218:219], off
	s_waitcnt vmcnt(8)
	s_waitcnt lgkmcnt(0)
	s_setprio 1
	s_waitcnt lgkmcnt(0)
	v_mfma_scale_f32_16x16x128_f8f6f4 v[156:159], v[24:31], v[176:183], v[156:159], v190, v190 op_sel_hi:[0,0,0]
	v_mfma_scale_f32_16x16x128_f8f6f4 v[152:155], v[16:23], v[176:183], v[152:155], v190, v190 op_sel_hi:[0,0,0]
	v_mfma_scale_f32_16x16x128_f8f6f4 v[140:143], v[24:31], v[194:201], v[140:143], v190, v190 op_sel_hi:[0,0,0]
	v_mfma_scale_f32_16x16x128_f8f6f4 v[136:139], v[16:23], v[194:201], v[136:139], v190, v190 op_sel_hi:[0,0,0]
	s_barrier
	v_mfma_scale_f32_16x16x128_f8f6f4 v[124:127], v[24:31], v[202:209], v[124:127], v190, v190 op_sel_hi:[0,0,0]
	v_mfma_scale_f32_16x16x128_f8f6f4 v[120:123], v[16:23], v[202:209], v[120:123], v190, v190 op_sel_hi:[0,0,0]
	v_mfma_scale_f32_16x16x128_f8f6f4 v[108:111], v[24:31], v[210:217], v[108:111], v190, v190 op_sel_hi:[0,0,0]
	v_mfma_scale_f32_16x16x128_f8f6f4 v[104:107], v[16:23], v[210:217], v[104:107], v190, v190 op_sel_hi:[0,0,0]
	s_setprio 0
	s_setprio 1
	v_mfma_scale_f32_16x16x128_f8f6f4 v[148:151], v[8:15], v[176:183], v[148:151], v190, v190 op_sel_hi:[0,0,0]
	v_mfma_scale_f32_16x16x128_f8f6f4 v[144:147], v[0:7], v[176:183], v[144:147], v190, v190 op_sel_hi:[0,0,0]
	v_mfma_scale_f32_16x16x128_f8f6f4 v[132:135], v[8:15], v[194:201], v[132:135], v190, v190 op_sel_hi:[0,0,0]
	v_mfma_scale_f32_16x16x128_f8f6f4 v[128:131], v[0:7], v[194:201], v[128:131], v190, v190 op_sel_hi:[0,0,0]
	v_mfma_scale_f32_16x16x128_f8f6f4 v[116:119], v[8:15], v[202:209], v[116:119], v190, v190 op_sel_hi:[0,0,0]
	v_mfma_scale_f32_16x16x128_f8f6f4 v[112:115], v[0:7], v[202:209], v[112:115], v190, v190 op_sel_hi:[0,0,0]
	v_mfma_scale_f32_16x16x128_f8f6f4 v[100:103], v[8:15], v[210:217], v[100:103], v190, v190 op_sel_hi:[0,0,0]
	v_mfma_scale_f32_16x16x128_f8f6f4 v[96:99], v[0:7], v[210:217], v[96:99], v190, v190 op_sel_hi:[0,0,0]
	s_setprio 0
	s_barrier
	s_add_i32 s70, s61, s34
	v_lshl_add_u64 v[176:177], s[46:47], 0, v[162:163]
	s_mov_b32 m0, s70
	ds_read_b128 v[194:197], v189 offset:16384
	ds_read_b128 v[198:201], v189 offset:17408
	ds_read_b128 v[202:205], v189 offset:18432
	ds_read_b128 v[206:209], v189 offset:19456
	ds_read_b128 v[210:213], v189 offset:20480
	ds_read_b128 v[214:217], v189 offset:21504
	ds_read_b128 v[218:221], v189 offset:22528
	ds_read_b128 v[222:225], v189 offset:23552
	global_load_lds_dwordx4 v[176:177], off
	s_add_i32 m0, s70, 0x2000
	s_add_u32 s70, s46, 0x40000
	v_lshl_add_u64 v[178:179], s[46:47], 0, v[166:167]
	s_addc_u32 s71, s47, 0
	s_add_i32 s72, s62, s34
	global_load_lds_dwordx4 v[178:179], off
	v_lshl_add_u64 v[180:181], s[70:71], 0, v[162:163]
	s_mov_b32 m0, s72
	v_lshl_add_u64 v[182:183], s[48:49], 0, v[164:165]
	global_load_lds_dwordx4 v[180:181], off
	v_lshl_add_u64 v[180:181], s[70:71], 0, v[166:167]
	s_add_i32 m0, s72, 0x2000
	s_nop 0
	global_load_lds_dwordx4 v[180:181], off
	v_lshl_add_u64 v[180:181], s[48:49], 0, v[160:161]
	s_mov_b32 m0, s35
	s_nop 0
	global_load_lds_dwordx4 v[180:181], off
	s_mov_b32 m0, s43
	s_nop 0
	global_load_lds_dwordx4 v[182:183], off
	s_waitcnt vmcnt(8)
	s_waitcnt lgkmcnt(0)
	s_setprio 1
	s_waitcnt lgkmcnt(0)
	v_mfma_scale_f32_16x16x128_f8f6f4 v[92:95], v[24:31], v[194:201], v[92:95], v190, v190 op_sel_hi:[0,0,0]
	v_mfma_scale_f32_16x16x128_f8f6f4 v[88:91], v[16:23], v[194:201], v[88:91], v190, v190 op_sel_hi:[0,0,0]
	v_mfma_scale_f32_16x16x128_f8f6f4 v[76:79], v[24:31], v[202:209], v[76:79], v190, v190 op_sel_hi:[0,0,0]
	v_mfma_scale_f32_16x16x128_f8f6f4 v[72:75], v[16:23], v[202:209], v[72:75], v190, v190 op_sel_hi:[0,0,0]
	s_barrier
	v_mfma_scale_f32_16x16x128_f8f6f4 v[60:63], v[24:31], v[210:217], v[60:63], v190, v190 op_sel_hi:[0,0,0]
	v_mfma_scale_f32_16x16x128_f8f6f4 v[56:59], v[16:23], v[210:217], v[56:59], v190, v190 op_sel_hi:[0,0,0]
	v_mfma_scale_f32_16x16x128_f8f6f4 v[44:47], v[24:31], v[218:225], v[44:47], v190, v190 op_sel_hi:[0,0,0]
	v_mfma_scale_f32_16x16x128_f8f6f4 v[40:43], v[16:23], v[218:225], v[40:43], v190, v190 op_sel_hi:[0,0,0]
	s_setprio 0
	s_setprio 1
	v_mfma_scale_f32_16x16x128_f8f6f4 v[84:87], v[8:15], v[194:201], v[84:87], v190, v190 op_sel_hi:[0,0,0]
	v_mfma_scale_f32_16x16x128_f8f6f4 v[80:83], v[0:7], v[194:201], v[80:83], v190, v190 op_sel_hi:[0,0,0]
	v_mfma_scale_f32_16x16x128_f8f6f4 v[68:71], v[8:15], v[202:209], v[68:71], v190, v190 op_sel_hi:[0,0,0]
	v_mfma_scale_f32_16x16x128_f8f6f4 v[64:67], v[0:7], v[202:209], v[64:67], v190, v190 op_sel_hi:[0,0,0]
	v_mfma_scale_f32_16x16x128_f8f6f4 v[52:55], v[8:15], v[210:217], v[52:55], v190, v190 op_sel_hi:[0,0,0]
	v_mfma_scale_f32_16x16x128_f8f6f4 v[48:51], v[0:7], v[210:217], v[48:51], v190, v190 op_sel_hi:[0,0,0]
	v_mfma_scale_f32_16x16x128_f8f6f4 v[36:39], v[8:15], v[218:225], v[36:39], v190, v190 op_sel_hi:[0,0,0]
	v_mfma_scale_f32_16x16x128_f8f6f4 v[32:35], v[0:7], v[218:225], v[32:35], v190, v190 op_sel_hi:[0,0,0]
	s_setprio 0
	s_barrier
; #define PG8_STAGE(bufoff, gbase, voff) do { _Pragma("unroll") for (int _i = 0; _i < 2; ++_i) \
;         __builtin_amdgcn_global_load_lds((const unsigned*)((const char*)(gbase) + (voff)[_i]), (LAS unsigned*)(lds + (bufoff) + ldsw + _i * 8192), 16, 0, 0); } while (0)
; #define PG8_WAIT_V(n) asm volatile("s_waitcnt vmcnt(" #n ")" ::: "memory")
; #define PG8_WAIT_L(n) asm volatile("s_waitcnt lgkmcnt(" #n ")" ::: "memory")
;     ...
;         for (int t = 0; t < nt; t += 2) {
;             const bool last = (t == nt - 2);
;             const char* a1 = cA + (size_t)(t + 1) * kstep;
;             const char* a2 = last ? nA : cA + (size_t)(t + 2) * kstep; const char* b2 = last ? nB : cB + (size_t)(t + 2) * kstep;
;             const char* a3 = a2 + kstep; const char* b3 = b2 + kstep;
;             PG8_LDB(B0, 0, 0); PG8_LDB(B1, 0, 1); PG8_SCHED; PG8_LDA(At, 0, 0); PG8_STAGE(PG8_SA(1, 1), a1 + hstep, voffA);
;             PG8_WAIT_V(8); PG8_WAIT_L(0); PG8_BAR; PG8_MMA(0, 0, At, B0); PG8_MMA(0, 1, At, B1); PG8_BAR; PG8_SCHED;
;             PG8_LDA(At, 0, 1); PG8_STAGE(PG8_SB(0, 0), b2, voffB); PG8_STAGE(PG8_SB(0, 1), b2 + hstep, voffB); PG8_STAGE(PG8_SA(0, 0), a2, voffA);
;             PG8_WAIT_V(8); PG8_WAIT_L(0); PG8_BAR; PG8_MMA(1, 0, At, B0); PG8_MMA(1, 1, At, B1); PG8_BAR; PG8_SCHED;
;             PG8_LDB(B0, 1, 0); PG8_LDB(B1, 1, 1); PG8_SCHED; PG8_LDA(At, 1, 0); PG8_STAGE(PG8_SA(0, 1), a2 + hstep, voffA);
;             PG8_WAIT_V(8); PG8_WAIT_L(0); PG8_BAR; PG8_MMA(0, 0, At, B0); PG8_MMA(0, 1, At, B1); PG8_BAR; PG8_SCHED;
;             PG8_LDA(At, 1, 1); PG8_STAGE(PG8_SB(1, 0), b3, voffB); PG8_STAGE(PG8_SB(1, 1), b3 + hstep, voffB); PG8_STAGE(PG8_SA(1, 0), a3, voffA);
;             PG8_WAIT_V(8); PG8_WAIT_L(0); PG8_BAR; PG8_MMA(1, 0, At, B0); PG8_MMA(1, 1, At, B1); PG8_BAR; PG8_SCHED;
;         }
;         if constexpr (QM == 2) { const float qs0_ = g.qs * E.qscale(cur), qs1_ = qs0_ * g.qs_b1; _Pragma("unroll") for (int a = 0; a < 2; ++a) _Pragma("unroll") for (int b = 0; b < 2; ++b) _Pragma("unroll") for (int m = 0; m < 4; ++m) _Pragma("unroll") for (int n = 0; n < 2; ++n) { const v4i t_ = __builtin_bit_cast(v4i, acc[a][b][m][n]); acc[a][b][m][n] = (f32x4){(float)t_[0], (float)t_[1], (float)t_[2], (float)t_[3]} * (b == 0 ? qs0_ : qs1_); } }
;         if constexpr (QM == 1) asm volatile("s_nop 15\n\ts_nop 15\n\ts_nop 15" ::: "memory");
	s_add_i32 s70, 0, 0x18000
	s_add_i32 s71, 0, 0x1c000
	v_add_u32_e32 v12, s70, v185
	v_add_u32_e32 v28, s71, v185
	ds_read_b128 v[0:3], v12
	ds_read_b128 v[4:7], v12 offset:1024
	ds_read_b128 v[8:11], v12 offset:2048
	ds_read_b128 v[12:15], v12 offset:3072
	ds_read_b128 v[16:19], v28
	ds_read_b128 v[20:23], v28 offset:1024
	ds_read_b128 v[24:27], v28 offset:2048
	ds_read_b128 v[28:31], v28 offset:3072
	s_add_u32 s48, s48, 0x40000
	s_addc_u32 s49, s49, 0
	s_mov_b32 m0, s50
	v_lshl_add_u64 v[226:227], s[48:49], 0, v[160:161]
	ds_read_b128 v[194:197], v189 offset:32768
	ds_read_b128 v[198:201], v189 offset:33792
	ds_read_b128 v[202:205], v189 offset:34816
	ds_read_b128 v[206:209], v189 offset:35840
	ds_read_b128 v[210:213], v189 offset:36864
	ds_read_b128 v[214:217], v189 offset:37888
	ds_read_b128 v[218:221], v189 offset:38912
	ds_read_b128 v[222:225], v189 offset:39936
	global_load_lds_dwordx4 v[226:227], off
	v_lshl_add_u64 v[226:227], s[48:49], 0, v[164:165]
	s_mov_b32 m0, s51
	s_nop 0
	global_load_lds_dwordx4 v[226:227], off
	s_waitcnt vmcnt(8)
	s_waitcnt lgkmcnt(0)
	s_setprio 1
	s_waitcnt lgkmcnt(0)
	v_mfma_scale_f32_16x16x128_f8f6f4 v[156:159], v[0:7], v[194:201], v[156:159], v190, v190 op_sel_hi:[0,0,0]
	v_mfma_scale_f32_16x16x128_f8f6f4 v[152:155], v[8:15], v[194:201], v[152:155], v190, v190 op_sel_hi:[0,0,0]
	v_mfma_scale_f32_16x16x128_f8f6f4 v[140:143], v[0:7], v[202:209], v[140:143], v190, v190 op_sel_hi:[0,0,0]
	v_mfma_scale_f32_16x16x128_f8f6f4 v[136:139], v[8:15], v[202:209], v[136:139], v190, v190 op_sel_hi:[0,0,0]
	s_barrier
	v_mfma_scale_f32_16x16x128_f8f6f4 v[124:127], v[0:7], v[210:217], v[124:127], v190, v190 op_sel_hi:[0,0,0]
	v_mfma_scale_f32_16x16x128_f8f6f4 v[120:123], v[8:15], v[210:217], v[120:123], v190, v190 op_sel_hi:[0,0,0]
	v_mfma_scale_f32_16x16x128_f8f6f4 v[108:111], v[0:7], v[218:225], v[108:111], v190, v190 op_sel_hi:[0,0,0]
	v_mfma_scale_f32_16x16x128_f8f6f4 v[104:107], v[8:15], v[218:225], v[104:107], v190, v190 op_sel_hi:[0,0,0]
	s_setprio 0
	s_setprio 1
	v_mfma_scale_f32_16x16x128_f8f6f4 v[148:151], v[16:23], v[194:201], v[148:151], v190, v190 op_sel_hi:[0,0,0]
	v_mfma_scale_f32_16x16x128_f8f6f4 v[144:147], v[24:31], v[194:201], v[144:147], v190, v190 op_sel_hi:[0,0,0]
	v_mfma_scale_f32_16x16x128_f8f6f4 v[132:135], v[16:23], v[202:209], v[132:135], v190, v190 op_sel_hi:[0,0,0]
	v_mfma_scale_f32_16x16x128_f8f6f4 v[128:131], v[24:31], v[202:209], v[128:131], v190, v190 op_sel_hi:[0,0,0]
	v_mfma_scale_f32_16x16x128_f8f6f4 v[116:119], v[16:23], v[210:217], v[116:119], v190, v190 op_sel_hi:[0,0,0]
	v_mfma_scale_f32_16x16x128_f8f6f4 v[112:115], v[24:31], v[210:217], v[112:115], v190, v190 op_sel_hi:[0,0,0]
	v_mfma_scale_f32_16x16x128_f8f6f4 v[100:103], v[16:23], v[218:225], v[100:103], v190, v190 op_sel_hi:[0,0,0]
	v_mfma_scale_f32_16x16x128_f8f6f4 v[96:99], v[24:31], v[218:225], v[96:99], v190, v190 op_sel_hi:[0,0,0]
	s_setprio 0
	s_barrier
	s_add_i32 s48, s70, s34
	v_lshl_add_u64 v[176:177], v[176:177], 0, s[16:17]
	s_mov_b32 m0, s48
	ds_read_b128 v[194:197], v189 offset:49152
	ds_read_b128 v[198:201], v189 offset:50176
	ds_read_b128 v[202:205], v189 offset:51200
	ds_read_b128 v[206:209], v189 offset:52224
	ds_read_b128 v[210:213], v189 offset:53248
	ds_read_b128 v[214:217], v189 offset:54272
	ds_read_b128 v[218:221], v189 offset:55296
	ds_read_b128 v[222:225], v189 offset:56320
	global_load_lds_dwordx4 v[176:177], off
	s_add_i32 m0, s48, 0x2000
	s_add_u32 s46, s46, 0x40080
	v_lshl_add_u64 v[176:177], v[178:179], 0, s[16:17]
	s_addc_u32 s47, s47, 0
	s_add_i32 s48, s71, s34
	global_load_lds_dwordx4 v[176:177], off
	v_lshl_add_u64 v[176:177], s[46:47], 0, v[162:163]
	s_mov_b32 m0, s48
	s_nop 0
	global_load_lds_dwordx4 v[176:177], off
	v_lshl_add_u64 v[176:177], s[46:47], 0, v[166:167]
	s_add_i32 m0, s48, 0x2000
	s_nop 0
	global_load_lds_dwordx4 v[176:177], off
	v_lshl_add_u64 v[176:177], v[180:181], 0, s[16:17]
	s_mov_b32 m0, s55
	s_nop 0
	global_load_lds_dwordx4 v[176:177], off
	v_lshl_add_u64 v[176:177], v[182:183], 0, s[16:17]
	s_mov_b32 m0, s58
	s_nop 0
	global_load_lds_dwordx4 v[176:177], off
	s_waitcnt vmcnt(8)
	s_waitcnt lgkmcnt(0)
	s_setprio 1
	s_waitcnt lgkmcnt(0)
	v_mfma_scale_f32_16x16x128_f8f6f4 v[92:95], v[0:7], v[194:201], v[92:95], v190, v190 op_sel_hi:[0,0,0]
	v_mfma_scale_f32_16x16x128_f8f6f4 v[88:91], v[8:15], v[194:201], v[88:91], v190, v190 op_sel_hi:[0,0,0]
	v_mfma_scale_f32_16x16x128_f8f6f4 v[76:79], v[0:7], v[202:209], v[76:79], v190, v190 op_sel_hi:[0,0,0]
	v_mfma_scale_f32_16x16x128_f8f6f4 v[72:75], v[8:15], v[202:209], v[72:75], v190, v190 op_sel_hi:[0,0,0]
	s_barrier
	v_mfma_scale_f32_16x16x128_f8f6f4 v[60:63], v[0:7], v[210:217], v[60:63], v190, v190 op_sel_hi:[0,0,0]
	v_mfma_scale_f32_16x16x128_f8f6f4 v[56:59], v[8:15], v[210:217], v[56:59], v190, v190 op_sel_hi:[0,0,0]
	v_mfma_scale_f32_16x16x128_f8f6f4 v[44:47], v[0:7], v[218:225], v[44:47], v190, v190 op_sel_hi:[0,0,0]
	v_mfma_scale_f32_16x16x128_f8f6f4 v[40:43], v[8:15], v[218:225], v[40:43], v190, v190 op_sel_hi:[0,0,0]
	s_setprio 0
	s_setprio 1
	v_mfma_scale_f32_16x16x128_f8f6f4 v[84:87], v[16:23], v[194:201], v[84:87], v190, v190 op_sel_hi:[0,0,0]
	v_mfma_scale_f32_16x16x128_f8f6f4 v[80:83], v[24:31], v[194:201], v[80:83], v190, v190 op_sel_hi:[0,0,0]
	v_mfma_scale_f32_16x16x128_f8f6f4 v[68:71], v[16:23], v[202:209], v[68:71], v190, v190 op_sel_hi:[0,0,0]
	v_mfma_scale_f32_16x16x128_f8f6f4 v[64:67], v[24:31], v[202:209], v[64:67], v190, v190 op_sel_hi:[0,0,0]
	v_mfma_scale_f32_16x16x128_f8f6f4 v[52:55], v[16:23], v[210:217], v[52:55], v190, v190 op_sel_hi:[0,0,0]
	v_mfma_scale_f32_16x16x128_f8f6f4 v[48:51], v[24:31], v[210:217], v[48:51], v190, v190 op_sel_hi:[0,0,0]
	v_mfma_scale_f32_16x16x128_f8f6f4 v[36:39], v[16:23], v[218:225], v[36:39], v190, v190 op_sel_hi:[0,0,0]
	v_mfma_scale_f32_16x16x128_f8f6f4 v[32:35], v[24:31], v[218:225], v[32:35], v190, v190 op_sel_hi:[0,0,0]
	s_setprio 0
	s_barrier
	s_add_i32 s69, s69, 2
	s_add_u32 s44, s44, 0x100
	s_addc_u32 s45, s45, 0
	s_add_u32 s67, s67, 0x100
	s_addc_u32 s68, s68, 0
	s_cmp_gt_u32 s69, 13
	s_cbranch_scc0 .LBB0_3686
	s_nop 15
	s_nop 15
	s_nop 15
	s_and_b64 vcc, exec, s[18:19]
	s_cbranch_vccz .LBB0_3689
	s_barrier

; #define PG8_STAGE(bufoff, gbase, voff) do { _Pragma("unroll") for (int _i = 0; _i < 2; ++_i) \
;         __builtin_amdgcn_global_load_lds((const unsigned*)((const char*)(gbase) + (voff)[_i]), (LAS unsigned*)(lds + (bufoff) + ldsw + _i * 8192), 16, 0, 0); } while (0)
; #define PG8_LDA(dst, b, h) do { _Pragma("unroll") for (int m = 0; m < 4; ++m) _Pragma("unroll") for (int k = 0; k < 2; ++k) dst[m][k] = *(const LAS bf16x8*)(lds + PG8_SA(b, h) + aoff + m * 2048 + k * 1024); } while (0)
; #define PG8_LDB(dst, b, h) do { _Pragma("unroll") for (int n = 0; n < 2; ++n) _Pragma("unroll") for (int k = 0; k < 2; ++k) dst[n][k] = *(const LAS bf16x8*)(lds + PG8_SB(b, h) + boff + n * 2048 + k * 1024); } while (0)
; #define PG8_WAIT_V(n) asm volatile("s_waitcnt vmcnt(" #n ")" ::: "memory")
; #define PG8_WAIT_L(n) asm volatile("s_waitcnt lgkmcnt(" #n ")" ::: "memory")
; #define PG8_BAR __builtin_amdgcn_s_barrier()
; #define PG8_SCHED __builtin_amdgcn_sched_barrier(0)
;     ...
;         for (int t = 0; t < nt; t += 2) {
;             const bool last = (t == nt - 2);
;             const char* a1 = cA + (size_t)(t + 1) * kstep;
;             const char* a2 = last ? nA : cA + (size_t)(t + 2) * kstep; const char* b2 = last ? nB : cB + (size_t)(t + 2) * kstep;
;             const char* a3 = a2 + kstep; const char* b3 = b2 + kstep;
;             PG8_LDB(B0, 0, 0); PG8_LDB(B1, 0, 1); PG8_SCHED; PG8_LDA(At, 0, 0); PG8_STAGE(PG8_SA(1, 1), a1 + hstep, voffA);
;             PG8_WAIT_V(8); PG8_WAIT_L(0); PG8_BAR; PG8_MMA(0, 0, At, B0); PG8_MMA(0, 1, At, B1); PG8_BAR; PG8_SCHED;
;             PG8_LDA(At, 0, 1); PG8_STAGE(PG8_SB(0, 0), b2, voffB); PG8_STAGE(PG8_SB(0, 1), b2 + hstep, voffB); PG8_STAGE(PG8_SA(0, 0), a2, voffA);
;             PG8_WAIT_V(8); PG8_WAIT_L(0); PG8_BAR; PG8_MMA(1, 0, At, B0); PG8_MMA(1, 1, At, B1); PG8_BAR; PG8_SCHED;
;             PG8_LDB(B0, 1, 0); PG8_LDB(B1, 1, 1); PG8_SCHED; PG8_LDA(At, 1, 0); PG8_STAGE(PG8_SA(0, 1), a2 + hstep, voffA);
;             PG8_WAIT_V(8); PG8_WAIT_L(0); PG8_BAR; PG8_MMA(0, 0, At, B0); PG8_MMA(0, 1, At, B1); PG8_BAR; PG8_SCHED;
;             PG8_LDA(At, 1, 1); PG8_STAGE(PG8_SB(1, 0), b3, voffB); PG8_STAGE(PG8_SB(1, 1), b3 + hstep, voffB); PG8_STAGE(PG8_SA(1, 0), a3, voffA);
;             PG8_WAIT_V(8); PG8_WAIT_L(0); PG8_BAR; PG8_MMA(1, 0, At, B0); PG8_MMA(1, 1, At, B1); PG8_BAR; PG8_SCHED;
.LBB0_3776:
	ds_read_b128 v[84:87], v169
	ds_read_b128 v[88:91], v169 offset:1024
	ds_read_b128 v[96:99], v169 offset:2048
	ds_read_b128 v[100:103], v169 offset:3072
	ds_read_b128 v[160:163], v170
	ds_read_b128 v[174:177], v170 offset:1024
	ds_read_b128 v[178:181], v170 offset:2048
	ds_read_b128 v[182:185], v170 offset:3072
	s_add_u32 s42, s40, 0xfffc0080
	s_addc_u32 s43, s41, -1
	s_cmp_eq_u32 s68, 12
	s_cselect_b32 s45, s31, s43
	s_cselect_b32 s44, s64, s42
	s_cselect_b32 s43, s29, s67
	s_cselect_b32 s42, s65, s66
	v_lshl_add_u64 v[164:165], s[40:41], 0, v[152:153]
	s_add_i32 m0, s47, 0xc000
	ds_read_b128 v[186:189], v171
	ds_read_b128 v[190:193], v171 offset:1024
	ds_read_b128 v[194:197], v171 offset:2048
	ds_read_b128 v[198:201], v171 offset:3072
	ds_read_b128 v[202:205], v171 offset:4096
	ds_read_b128 v[206:209], v171 offset:5120
	ds_read_b128 v[210:213], v171 offset:6144
	ds_read_b128 v[214:217], v171 offset:7168
	global_load_lds_dwordx4 v[164:165], off
	v_lshl_add_u64 v[164:165], s[40:41], 0, v[154:155]
	s_add_i32 m0, s47, 0xe000
	s_nop 0
	global_load_lds_dwordx4 v[164:165], off
	s_waitcnt vmcnt(8)
	s_waitcnt lgkmcnt(0)
	s_setprio 1
	s_waitcnt lgkmcnt(0)
	v_mfma_i32_16x16x64_i8 v[140:143], v[84:87], v[186:189], v[140:143]
	v_mfma_i32_16x16x64_i8 v[136:139], v[96:99], v[186:189], v[136:139]
	v_mfma_i32_16x16x64_i8 v[124:127], v[84:87], v[194:197], v[124:127]
	v_mfma_i32_16x16x64_i8 v[120:123], v[96:99], v[194:197], v[120:123]
	v_mfma_i32_16x16x64_i8 v[108:111], v[84:87], v[202:205], v[108:111]
	v_mfma_i32_16x16x64_i8 v[104:107], v[96:99], v[202:205], v[104:107]
	v_mfma_i32_16x16x64_i8 v[76:79], v[84:87], v[210:213], v[76:79]
	v_mfma_i32_16x16x64_i8 v[72:75], v[96:99], v[210:213], v[72:75]
	s_barrier
	v_mfma_i32_16x16x64_i8 v[140:143], v[88:91], v[190:193], v[140:143]
	v_mfma_i32_16x16x64_i8 v[136:139], v[100:103], v[190:193], v[136:139]
	v_mfma_i32_16x16x64_i8 v[124:127], v[88:91], v[198:201], v[124:127]
	v_mfma_i32_16x16x64_i8 v[120:123], v[100:103], v[198:201], v[120:123]
	v_mfma_i32_16x16x64_i8 v[108:111], v[88:91], v[206:209], v[108:111]
	v_mfma_i32_16x16x64_i8 v[104:107], v[100:103], v[206:209], v[104:107]
	v_mfma_i32_16x16x64_i8 v[76:79], v[88:91], v[214:217], v[76:79]
	v_mfma_i32_16x16x64_i8 v[72:75], v[100:103], v[214:217], v[72:75]
	s_setprio 0
	s_setprio 1
	v_mfma_i32_16x16x64_i8 v[132:135], v[160:163], v[186:189], v[132:135]
	v_mfma_i32_16x16x64_i8 v[128:131], v[178:181], v[186:189], v[128:131]
	v_mfma_i32_16x16x64_i8 v[116:119], v[160:163], v[194:197], v[116:119]
	v_mfma_i32_16x16x64_i8 v[112:115], v[178:181], v[194:197], v[112:115]
	v_mfma_i32_16x16x64_i8 v[92:95], v[160:163], v[202:205], v[92:95]
	v_mfma_i32_16x16x64_i8 v[80:83], v[178:181], v[202:205], v[80:83]
	v_mfma_i32_16x16x64_i8 v[68:71], v[160:163], v[210:213], v[68:71]
	v_mfma_i32_16x16x64_i8 v[64:67], v[178:181], v[210:213], v[64:67]
	v_mfma_i32_16x16x64_i8 v[132:135], v[174:177], v[190:193], v[132:135]
	v_mfma_i32_16x16x64_i8 v[128:131], v[182:185], v[190:193], v[128:131]
	v_mfma_i32_16x16x64_i8 v[116:119], v[174:177], v[198:201], v[116:119]
	v_mfma_i32_16x16x64_i8 v[112:115], v[182:185], v[198:201], v[112:115]
	v_mfma_i32_16x16x64_i8 v[92:95], v[174:177], v[206:209], v[92:95]
	v_mfma_i32_16x16x64_i8 v[80:83], v[182:185], v[206:209], v[80:83]
	v_mfma_i32_16x16x64_i8 v[68:71], v[174:177], v[214:217], v[68:71]
	v_mfma_i32_16x16x64_i8 v[64:67], v[182:185], v[214:217], v[64:67]
	s_setprio 0
	s_barrier
	s_add_i32 s69, s59, s34
	v_lshl_add_u64 v[164:165], s[42:43], 0, v[148:149]
	s_mov_b32 m0, s69
	ds_read_b128 v[186:189], v171 offset:16384
	ds_read_b128 v[190:193], v171 offset:17408
	ds_read_b128 v[194:197], v171 offset:18432
	ds_read_b128 v[198:201], v171 offset:19456
	ds_read_b128 v[202:205], v171 offset:20480
	ds_read_b128 v[206:209], v171 offset:21504
	ds_read_b128 v[210:213], v171 offset:22528
	ds_read_b128 v[214:217], v171 offset:23552
	global_load_lds_dwordx4 v[164:165], off
	s_add_i32 m0, s69, 0x2000
	s_add_u32 s70, s42, 0x40000
	v_lshl_add_u64 v[218:219], s[42:43], 0, v[144:145]
	s_addc_u32 s71, s43, 0
	s_add_i32 s69, s60, s34
	global_load_lds_dwordx4 v[218:219], off
	v_lshl_add_u64 v[220:221], s[70:71], 0, v[148:149]
	s_mov_b32 m0, s69
	v_lshl_add_u64 v[222:223], s[44:45], 0, v[146:147]
	global_load_lds_dwordx4 v[220:221], off
	v_lshl_add_u64 v[220:221], s[70:71], 0, v[144:145]
	s_add_i32 m0, s69, 0x2000
	s_nop 0
	global_load_lds_dwordx4 v[220:221], off
	v_lshl_add_u64 v[220:221], s[44:45], 0, v[150:151]
	s_mov_b32 m0, s47
	s_nop 0
	global_load_lds_dwordx4 v[220:221], off
	s_mov_b32 m0, s48
	s_nop 0
	global_load_lds_dwordx4 v[222:223], off
	s_waitcnt vmcnt(8)
	s_waitcnt lgkmcnt(0)
	s_setprio 1
	s_waitcnt lgkmcnt(0)
	v_mfma_i32_16x16x64_i8 v[60:63], v[84:87], v[186:189], v[60:63]
	v_mfma_i32_16x16x64_i8 v[56:59], v[96:99], v[186:189], v[56:59]
	v_mfma_i32_16x16x64_i8 v[44:47], v[84:87], v[194:197], v[44:47]
	v_mfma_i32_16x16x64_i8 v[40:43], v[96:99], v[194:197], v[40:43]
	v_mfma_i32_16x16x64_i8 v[28:31], v[84:87], v[202:205], v[28:31]
	v_mfma_i32_16x16x64_i8 v[24:27], v[96:99], v[202:205], v[24:27]
	v_mfma_i32_16x16x64_i8 v[12:15], v[84:87], v[210:213], v[12:15]
	v_mfma_i32_16x16x64_i8 v[8:11], v[96:99], v[210:213], v[8:11]
	s_barrier
; #define PG8_STAGE(bufoff, gbase, voff) do { _Pragma("unroll") for (int _i = 0; _i < 2; ++_i) \
;         __builtin_amdgcn_global_load_lds((const unsigned*)((const char*)(gbase) + (voff)[_i]), (LAS unsigned*)(lds + (bufoff) + ldsw + _i * 8192), 16, 0, 0); } while (0)
; #define PG8_LDA(dst, b, h) do { _Pragma("unroll") for (int m = 0; m < 4; ++m) _Pragma("unroll") for (int k = 0; k < 2; ++k) dst[m][k] = *(const LAS bf16x8*)(lds + PG8_SA(b, h) + aoff + m * 2048 + k * 1024); } while (0)
; #define PG8_LDB(dst, b, h) do { _Pragma("unroll") for (int n = 0; n < 2; ++n) _Pragma("unroll") for (int k = 0; k < 2; ++k) dst[n][k] = *(const LAS bf16x8*)(lds + PG8_SB(b, h) + boff + n * 2048 + k * 1024); } while (0)
; #define PG8_WAIT_V(n) asm volatile("s_waitcnt vmcnt(" #n ")" ::: "memory")
; #define PG8_WAIT_L(n) asm volatile("s_waitcnt lgkmcnt(" #n ")" ::: "memory")
; #define PG8_BAR __builtin_amdgcn_s_barrier()
; #define PG8_SCHED __builtin_amdgcn_sched_barrier(0)
;     ...
;         for (int t = 0; t < nt; t += 2) {
;             const bool last = (t == nt - 2);
;             const char* a1 = cA + (size_t)(t + 1) * kstep;
;             const char* a2 = last ? nA : cA + (size_t)(t + 2) * kstep; const char* b2 = last ? nB : cB + (size_t)(t + 2) * kstep;
;             const char* a3 = a2 + kstep; const char* b3 = b2 + kstep;
;             PG8_LDB(B0, 0, 0); PG8_LDB(B1, 0, 1); PG8_SCHED; PG8_LDA(At, 0, 0); PG8_STAGE(PG8_SA(1, 1), a1 + hstep, voffA);
;             PG8_WAIT_V(8); PG8_WAIT_L(0); PG8_BAR; PG8_MMA(0, 0, At, B0); PG8_MMA(0, 1, At, B1); PG8_BAR; PG8_SCHED;
;             PG8_LDA(At, 0, 1); PG8_STAGE(PG8_SB(0, 0), b2, voffB); PG8_STAGE(PG8_SB(0, 1), b2 + hstep, voffB); PG8_STAGE(PG8_SA(0, 0), a2, voffA);
;             PG8_WAIT_V(8); PG8_WAIT_L(0); PG8_BAR; PG8_MMA(1, 0, At, B0); PG8_MMA(1, 1, At, B1); PG8_BAR; PG8_SCHED;
;             PG8_LDB(B0, 1, 0); PG8_LDB(B1, 1, 1); PG8_SCHED; PG8_LDA(At, 1, 0); PG8_STAGE(PG8_SA(0, 1), a2 + hstep, voffA);
;             PG8_WAIT_V(8); PG8_WAIT_L(0); PG8_BAR; PG8_MMA(0, 0, At, B0); PG8_MMA(0, 1, At, B1); PG8_BAR; PG8_SCHED;
;             PG8_LDA(At, 1, 1); PG8_STAGE(PG8_SB(1, 0), b3, voffB); PG8_STAGE(PG8_SB(1, 1), b3 + hstep, voffB); PG8_STAGE(PG8_SA(1, 0), a3, voffA);
;             PG8_WAIT_V(8); PG8_WAIT_L(0); PG8_BAR; PG8_MMA(1, 0, At, B0); PG8_MMA(1, 1, At, B1); PG8_BAR; PG8_SCHED;
	v_mfma_i32_16x16x64_i8 v[60:63], v[88:91], v[190:193], v[60:63]
	v_mfma_i32_16x16x64_i8 v[56:59], v[100:103], v[190:193], v[56:59]
	v_mfma_i32_16x16x64_i8 v[44:47], v[88:91], v[198:201], v[44:47]
	v_mfma_i32_16x16x64_i8 v[40:43], v[100:103], v[198:201], v[40:43]
	v_mfma_i32_16x16x64_i8 v[28:31], v[88:91], v[206:209], v[28:31]
	v_mfma_i32_16x16x64_i8 v[24:27], v[100:103], v[206:209], v[24:27]
	v_mfma_i32_16x16x64_i8 v[12:15], v[88:91], v[214:217], v[12:15]
	v_mfma_i32_16x16x64_i8 v[8:11], v[100:103], v[214:217], v[8:11]
	s_setprio 0
	s_setprio 1
	v_mfma_i32_16x16x64_i8 v[52:55], v[160:163], v[186:189], v[52:55]
	v_mfma_i32_16x16x64_i8 v[48:51], v[178:181], v[186:189], v[48:51]
	v_mfma_i32_16x16x64_i8 v[36:39], v[160:163], v[194:197], v[36:39]
	v_mfma_i32_16x16x64_i8 v[32:35], v[178:181], v[194:197], v[32:35]
	v_mfma_i32_16x16x64_i8 v[20:23], v[160:163], v[202:205], v[20:23]
	v_mfma_i32_16x16x64_i8 v[16:19], v[178:181], v[202:205], v[16:19]
	v_mfma_i32_16x16x64_i8 v[4:7], v[160:163], v[210:213], v[4:7]
	v_mfma_i32_16x16x64_i8 v[0:3], v[178:181], v[210:213], v[0:3]
	v_mfma_i32_16x16x64_i8 v[52:55], v[174:177], v[190:193], v[52:55]
	v_mfma_i32_16x16x64_i8 v[48:51], v[182:185], v[190:193], v[48:51]
	v_mfma_i32_16x16x64_i8 v[36:39], v[174:177], v[198:201], v[36:39]
	v_mfma_i32_16x16x64_i8 v[32:35], v[182:185], v[198:201], v[32:35]
	v_mfma_i32_16x16x64_i8 v[20:23], v[174:177], v[206:209], v[20:23]
	v_mfma_i32_16x16x64_i8 v[16:19], v[182:185], v[206:209], v[16:19]
	v_mfma_i32_16x16x64_i8 v[4:7], v[174:177], v[214:217], v[4:7]
	v_mfma_i32_16x16x64_i8 v[0:3], v[182:185], v[214:217], v[0:3]
	s_setprio 0
	s_barrier
	s_add_i32 s69, 0, 0x18000
	s_add_i32 s70, 0, 0x1c000
	v_add_u32_e32 v100, s69, v167
	v_add_u32_e32 v182, s70, v167
	ds_read_b128 v[84:87], v100
	ds_read_b128 v[88:91], v100 offset:1024
	ds_read_b128 v[96:99], v100 offset:2048
	ds_read_b128 v[100:103], v100 offset:3072
	ds_read_b128 v[160:163], v182
	ds_read_b128 v[174:177], v182 offset:1024
	ds_read_b128 v[178:181], v182 offset:2048
	ds_read_b128 v[182:185], v182 offset:3072
	s_add_u32 s44, s44, 0x40000
	s_addc_u32 s45, s45, 0
	s_mov_b32 m0, s49
	v_lshl_add_u64 v[224:225], s[44:45], 0, v[150:151]
	ds_read_b128 v[186:189], v171 offset:32768
	ds_read_b128 v[190:193], v171 offset:33792
	ds_read_b128 v[194:197], v171 offset:34816
	ds_read_b128 v[198:201], v171 offset:35840
	ds_read_b128 v[202:205], v171 offset:36864
	ds_read_b128 v[206:209], v171 offset:37888
	ds_read_b128 v[210:213], v171 offset:38912
	ds_read_b128 v[214:217], v171 offset:39936
	global_load_lds_dwordx4 v[224:225], off
	v_lshl_add_u64 v[224:225], s[44:45], 0, v[146:147]
	s_mov_b32 m0, s50
	s_nop 0
	global_load_lds_dwordx4 v[224:225], off
	s_waitcnt vmcnt(8)
	s_waitcnt lgkmcnt(0)
	s_setprio 1
	s_waitcnt lgkmcnt(0)
	v_mfma_i32_16x16x64_i8 v[140:143], v[84:87], v[186:189], v[140:143]
	v_mfma_i32_16x16x64_i8 v[136:139], v[96:99], v[186:189], v[136:139]
	v_mfma_i32_16x16x64_i8 v[124:127], v[84:87], v[194:197], v[124:127]
	v_mfma_i32_16x16x64_i8 v[120:123], v[96:99], v[194:197], v[120:123]
	v_mfma_i32_16x16x64_i8 v[108:111], v[84:87], v[202:205], v[108:111]
	v_mfma_i32_16x16x64_i8 v[104:107], v[96:99], v[202:205], v[104:107]
	v_mfma_i32_16x16x64_i8 v[76:79], v[84:87], v[210:213], v[76:79]
	v_mfma_i32_16x16x64_i8 v[72:75], v[96:99], v[210:213], v[72:75]
	s_barrier
	v_mfma_i32_16x16x64_i8 v[140:143], v[88:91], v[190:193], v[140:143]
	v_mfma_i32_16x16x64_i8 v[136:139], v[100:103], v[190:193], v[136:139]
	v_mfma_i32_16x16x64_i8 v[124:127], v[88:91], v[198:201], v[124:127]
	v_mfma_i32_16x16x64_i8 v[120:123], v[100:103], v[198:201], v[120:123]
	v_mfma_i32_16x16x64_i8 v[108:111], v[88:91], v[206:209], v[108:111]
	v_mfma_i32_16x16x64_i8 v[104:107], v[100:103], v[206:209], v[104:107]
	v_mfma_i32_16x16x64_i8 v[76:79], v[88:91], v[214:217], v[76:79]
	v_mfma_i32_16x16x64_i8 v[72:75], v[100:103], v[214:217], v[72:75]
	s_setprio 0
	s_setprio 1
	v_mfma_i32_16x16x64_i8 v[132:135], v[160:163], v[186:189], v[132:135]
	v_mfma_i32_16x16x64_i8 v[128:131], v[178:181], v[186:189], v[128:131]
	v_mfma_i32_16x16x64_i8 v[116:119], v[160:163], v[194:197], v[116:119]
	v_mfma_i32_16x16x64_i8 v[112:115], v[178:181], v[194:197], v[112:115]
	v_mfma_i32_16x16x64_i8 v[92:95], v[160:163], v[202:205], v[92:95]
	v_mfma_i32_16x16x64_i8 v[80:83], v[178:181], v[202:205], v[80:83]
	v_mfma_i32_16x16x64_i8 v[68:71], v[160:163], v[210:213], v[68:71]
	v_mfma_i32_16x16x64_i8 v[64:67], v[178:181], v[210:213], v[64:67]
	v_mfma_i32_16x16x64_i8 v[132:135], v[174:177], v[190:193], v[132:135]
	v_mfma_i32_16x16x64_i8 v[128:131], v[182:185], v[190:193], v[128:131]
	v_mfma_i32_16x16x64_i8 v[116:119], v[174:177], v[198:201], v[116:119]
	v_mfma_i32_16x16x64_i8 v[112:115], v[182:185], v[198:201], v[112:115]
	v_mfma_i32_16x16x64_i8 v[92:95], v[174:177], v[206:209], v[92:95]
	v_mfma_i32_16x16x64_i8 v[80:83], v[182:185], v[206:209], v[80:83]
	v_mfma_i32_16x16x64_i8 v[68:71], v[174:177], v[214:217], v[68:71]
	v_mfma_i32_16x16x64_i8 v[64:67], v[182:185], v[214:217], v[64:67]
	s_setprio 0
	s_barrier
; #define PG8_STAGE(bufoff, gbase, voff) do { _Pragma("unroll") for (int _i = 0; _i < 2; ++_i) \
;         __builtin_amdgcn_global_load_lds((const unsigned*)((const char*)(gbase) + (voff)[_i]), (LAS unsigned*)(lds + (bufoff) + ldsw + _i * 8192), 16, 0, 0); } while (0)
; #define PG8_LDA(dst, b, h) do { _Pragma("unroll") for (int m = 0; m < 4; ++m) _Pragma("unroll") for (int k = 0; k < 2; ++k) dst[m][k] = *(const LAS bf16x8*)(lds + PG8_SA(b, h) + aoff + m * 2048 + k * 1024); } while (0)
; #define PG8_LDB(dst, b, h) do { _Pragma("unroll") for (int n = 0; n < 2; ++n) _Pragma("unroll") for (int k = 0; k < 2; ++k) dst[n][k] = *(const LAS bf16x8*)(lds + PG8_SB(b, h) + boff + n * 2048 + k * 1024); } while (0)
; #define PG8_WAIT_V(n) asm volatile("s_waitcnt vmcnt(" #n ")" ::: "memory")
; #define PG8_WAIT_L(n) asm volatile("s_waitcnt lgkmcnt(" #n ")" ::: "memory")
; #define PG8_BAR __builtin_amdgcn_s_barrier()
; #define PG8_SCHED __builtin_amdgcn_sched_barrier(0)
;     ...
;         for (int t = 0; t < nt; t += 2) {
;             const bool last = (t == nt - 2);
;             const char* a1 = cA + (size_t)(t + 1) * kstep;
;             const char* a2 = last ? nA : cA + (size_t)(t + 2) * kstep; const char* b2 = last ? nB : cB + (size_t)(t + 2) * kstep;
;             const char* a3 = a2 + kstep; const char* b3 = b2 + kstep;
;             PG8_LDB(B0, 0, 0); PG8_LDB(B1, 0, 1); PG8_SCHED; PG8_LDA(At, 0, 0); PG8_STAGE(PG8_SA(1, 1), a1 + hstep, voffA);
;             PG8_WAIT_V(8); PG8_WAIT_L(0); PG8_BAR; PG8_MMA(0, 0, At, B0); PG8_MMA(0, 1, At, B1); PG8_BAR; PG8_SCHED;
;             PG8_LDA(At, 0, 1); PG8_STAGE(PG8_SB(0, 0), b2, voffB); PG8_STAGE(PG8_SB(0, 1), b2 + hstep, voffB); PG8_STAGE(PG8_SA(0, 0), a2, voffA);
;             PG8_WAIT_V(8); PG8_WAIT_L(0); PG8_BAR; PG8_MMA(1, 0, At, B0); PG8_MMA(1, 1, At, B1); PG8_BAR; PG8_SCHED;
;             PG8_LDB(B0, 1, 0); PG8_LDB(B1, 1, 1); PG8_SCHED; PG8_LDA(At, 1, 0); PG8_STAGE(PG8_SA(0, 1), a2 + hstep, voffA);
;             PG8_WAIT_V(8); PG8_WAIT_L(0); PG8_BAR; PG8_MMA(0, 0, At, B0); PG8_MMA(0, 1, At, B1); PG8_BAR; PG8_SCHED;
;             PG8_LDA(At, 1, 1); PG8_STAGE(PG8_SB(1, 0), b3, voffB); PG8_STAGE(PG8_SB(1, 1), b3 + hstep, voffB); PG8_STAGE(PG8_SA(1, 0), a3, voffA);
;             PG8_WAIT_V(8); PG8_WAIT_L(0); PG8_BAR; PG8_MMA(1, 0, At, B0); PG8_MMA(1, 1, At, B1); PG8_BAR; PG8_SCHED;
;         }
	s_add_i32 s44, s69, s34
	v_lshl_add_u64 v[164:165], v[164:165], 0, s[16:17]
	s_mov_b32 m0, s44
	ds_read_b128 v[186:189], v171 offset:49152
	ds_read_b128 v[190:193], v171 offset:50176
	ds_read_b128 v[194:197], v171 offset:51200
	ds_read_b128 v[198:201], v171 offset:52224
	ds_read_b128 v[202:205], v171 offset:53248
	ds_read_b128 v[206:209], v171 offset:54272
	ds_read_b128 v[210:213], v171 offset:55296
	ds_read_b128 v[214:217], v171 offset:56320
	global_load_lds_dwordx4 v[164:165], off
	s_add_i32 m0, s44, 0x2000
	s_add_u32 s42, s42, 0x40080
	v_lshl_add_u64 v[164:165], v[218:219], 0, s[16:17]
	s_addc_u32 s43, s43, 0
	s_add_i32 s44, s70, s34
	global_load_lds_dwordx4 v[164:165], off
	v_lshl_add_u64 v[164:165], s[42:43], 0, v[148:149]
	s_mov_b32 m0, s44
	s_nop 0
	global_load_lds_dwordx4 v[164:165], off
	v_lshl_add_u64 v[164:165], s[42:43], 0, v[144:145]
	s_add_i32 m0, s44, 0x2000
	s_nop 0
	global_load_lds_dwordx4 v[164:165], off
	v_lshl_add_u64 v[164:165], v[220:221], 0, s[16:17]
	s_mov_b32 m0, s54
	s_nop 0
	global_load_lds_dwordx4 v[164:165], off
	v_lshl_add_u64 v[164:165], v[222:223], 0, s[16:17]
	s_mov_b32 m0, s55
	s_nop 0
	global_load_lds_dwordx4 v[164:165], off
	s_waitcnt vmcnt(8)
	s_waitcnt lgkmcnt(0)
	s_setprio 1
	s_waitcnt lgkmcnt(0)
	v_mfma_i32_16x16x64_i8 v[60:63], v[84:87], v[186:189], v[60:63]
	v_mfma_i32_16x16x64_i8 v[56:59], v[96:99], v[186:189], v[56:59]
	v_mfma_i32_16x16x64_i8 v[44:47], v[84:87], v[194:197], v[44:47]
	v_mfma_i32_16x16x64_i8 v[40:43], v[96:99], v[194:197], v[40:43]
	v_mfma_i32_16x16x64_i8 v[28:31], v[84:87], v[202:205], v[28:31]
	v_mfma_i32_16x16x64_i8 v[24:27], v[96:99], v[202:205], v[24:27]
	v_mfma_i32_16x16x64_i8 v[12:15], v[84:87], v[210:213], v[12:15]
	v_mfma_i32_16x16x64_i8 v[8:11], v[96:99], v[210:213], v[8:11]
	s_barrier
	v_mfma_i32_16x16x64_i8 v[60:63], v[88:91], v[190:193], v[60:63]
	v_mfma_i32_16x16x64_i8 v[56:59], v[100:103], v[190:193], v[56:59]
	v_mfma_i32_16x16x64_i8 v[44:47], v[88:91], v[198:201], v[44:47]
	v_mfma_i32_16x16x64_i8 v[40:43], v[100:103], v[198:201], v[40:43]
	v_mfma_i32_16x16x64_i8 v[28:31], v[88:91], v[206:209], v[28:31]
	v_mfma_i32_16x16x64_i8 v[24:27], v[100:103], v[206:209], v[24:27]
	v_mfma_i32_16x16x64_i8 v[12:15], v[88:91], v[214:217], v[12:15]
	v_mfma_i32_16x16x64_i8 v[8:11], v[100:103], v[214:217], v[8:11]
	s_setprio 0
	s_setprio 1
	v_mfma_i32_16x16x64_i8 v[52:55], v[160:163], v[186:189], v[52:55]
	v_mfma_i32_16x16x64_i8 v[48:51], v[178:181], v[186:189], v[48:51]
	v_mfma_i32_16x16x64_i8 v[36:39], v[160:163], v[194:197], v[36:39]
	v_mfma_i32_16x16x64_i8 v[32:35], v[178:181], v[194:197], v[32:35]
	v_mfma_i32_16x16x64_i8 v[20:23], v[160:163], v[202:205], v[20:23]
	v_mfma_i32_16x16x64_i8 v[16:19], v[178:181], v[202:205], v[16:19]
	v_mfma_i32_16x16x64_i8 v[4:7], v[160:163], v[210:213], v[4:7]
	v_mfma_i32_16x16x64_i8 v[0:3], v[178:181], v[210:213], v[0:3]
	v_mfma_i32_16x16x64_i8 v[52:55], v[174:177], v[190:193], v[52:55]
	v_mfma_i32_16x16x64_i8 v[48:51], v[182:185], v[190:193], v[48:51]
	v_mfma_i32_16x16x64_i8 v[36:39], v[174:177], v[198:201], v[36:39]
	v_mfma_i32_16x16x64_i8 v[32:35], v[182:185], v[198:201], v[32:35]
	v_mfma_i32_16x16x64_i8 v[20:23], v[174:177], v[206:209], v[20:23]
	v_mfma_i32_16x16x64_i8 v[16:19], v[182:185], v[206:209], v[16:19]
	v_mfma_i32_16x16x64_i8 v[4:7], v[174:177], v[214:217], v[4:7]
	v_mfma_i32_16x16x64_i8 v[0:3], v[182:185], v[214:217], v[0:3]
	s_setprio 0
	s_barrier
	s_add_i32 s68, s68, 2
	s_add_u32 s40, s40, 0x100
	s_addc_u32 s41, s41, 0
	s_add_u32 s66, s66, 0x100
	s_addc_u32 s67, s67, 0
	s_cmp_gt_u32 s68, 13
	s_cbranch_scc0 .LBB0_3776
	s_and_b64 vcc, exec, s[18:19]
	s_cbranch_vccz .LBB0_3779
	s_barrier

; #define PG8_STAGE(bufoff, gbase, voff) do { _Pragma("unroll") for (int _i = 0; _i < 2; ++_i) \
;         __builtin_amdgcn_global_load_lds((const unsigned*)((const char*)(gbase) + (voff)[_i]), (LAS unsigned*)(lds + (bufoff) + ldsw + _i * 8192), 16, 0, 0); } while (0)
; #define PG8_LDA(dst, b, h) do { _Pragma("unroll") for (int m = 0; m < 4; ++m) _Pragma("unroll") for (int k = 0; k < 2; ++k) dst[m][k] = *(const LAS bf16x8*)(lds + PG8_SA(b, h) + aoff + m * 2048 + k * 1024); } while (0)
; #define PG8_LDB(dst, b, h) do { _Pragma("unroll") for (int n = 0; n < 2; ++n) _Pragma("unroll") for (int k = 0; k < 2; ++k) dst[n][k] = *(const LAS bf16x8*)(lds + PG8_SB(b, h) + boff + n * 2048 + k * 1024); } while (0)
; #define PG8_WAIT_V(n) asm volatile("s_waitcnt vmcnt(" #n ")" ::: "memory")
; #define PG8_WAIT_L(n) asm volatile("s_waitcnt lgkmcnt(" #n ")" ::: "memory")
; #define PG8_BAR __builtin_amdgcn_s_barrier()
; #define PG8_SCHED __builtin_amdgcn_sched_barrier(0)
;     ...
;         for (int t = 0; t < nt; t += 2) {
;             const bool last = (t == nt - 2);
;             const char* a1 = cA + (size_t)(t + 1) * kstep;
;             const char* a2 = last ? nA : cA + (size_t)(t + 2) * kstep; const char* b2 = last ? nB : cB + (size_t)(t + 2) * kstep;
;             const char* a3 = a2 + kstep; const char* b3 = b2 + kstep;
;             PG8_LDB(B0, 0, 0); PG8_LDB(B1, 0, 1); PG8_SCHED; PG8_LDA(At, 0, 0); PG8_STAGE(PG8_SA(1, 1), a1 + hstep, voffA);
;             PG8_WAIT_V(8); PG8_WAIT_L(0); PG8_BAR; PG8_MMA(0, 0, At, B0); PG8_MMA(0, 1, At, B1); PG8_BAR; PG8_SCHED;
;             PG8_LDA(At, 0, 1); PG8_STAGE(PG8_SB(0, 0), b2, voffB); PG8_STAGE(PG8_SB(0, 1), b2 + hstep, voffB); PG8_STAGE(PG8_SA(0, 0), a2, voffA);
;             PG8_WAIT_V(8); PG8_WAIT_L(0); PG8_BAR; PG8_MMA(1, 0, At, B0); PG8_MMA(1, 1, At, B1); PG8_BAR; PG8_SCHED;
;             PG8_LDB(B0, 1, 0); PG8_LDB(B1, 1, 1); PG8_SCHED; PG8_LDA(At, 1, 0); PG8_STAGE(PG8_SA(0, 1), a2 + hstep, voffA);
;             PG8_WAIT_V(8); PG8_WAIT_L(0); PG8_BAR; PG8_MMA(0, 0, At, B0); PG8_MMA(0, 1, At, B1); PG8_BAR; PG8_SCHED;
;             PG8_LDA(At, 1, 1); PG8_STAGE(PG8_SB(1, 0), b3, voffB); PG8_STAGE(PG8_SB(1, 1), b3 + hstep, voffB); PG8_STAGE(PG8_SA(1, 0), a3, voffA);
;             PG8_WAIT_V(8); PG8_WAIT_L(0); PG8_BAR; PG8_MMA(1, 0, At, B0); PG8_MMA(1, 1, At, B1); PG8_BAR; PG8_SCHED;
.LBB0_3858:
	ds_read_b128 v[24:27], v189
	ds_read_b128 v[28:31], v189 offset:1024
	ds_read_b128 v[16:19], v189 offset:2048
	ds_read_b128 v[20:23], v189 offset:3072
	ds_read_b128 v[8:11], v190
	ds_read_b128 v[12:15], v190 offset:1024
	s_waitcnt lgkmcnt(0)
	ds_read_b128 v[0:3], v190 offset:2048
	ds_read_b128 v[4:7], v190 offset:3072
	s_add_u32 s6, s44, 0x100
	s_addc_u32 s7, s45, 0
	s_cmp_eq_u32 s73, 40
	s_cselect_b32 s49, s41, s7
	s_cselect_b32 s48, s40, s6
	s_cselect_b32 s47, s43, s72
	s_cselect_b32 s46, s42, s71
	v_lshl_add_u64 v[184:185], s[44:45], 0, v[168:169]
	s_add_i32 m0, s37, 0xc000
	ds_read_b128 v[176:179], v191
	ds_read_b128 v[180:183], v191 offset:1024
	ds_read_b128 v[196:199], v191 offset:2048
	ds_read_b128 v[200:203], v191 offset:3072
	ds_read_b128 v[204:207], v191 offset:4096
	ds_read_b128 v[208:211], v191 offset:5120
	ds_read_b128 v[212:215], v191 offset:6144
	ds_read_b128 v[216:219], v191 offset:7168
	global_load_lds_dwordx4 v[184:185], off
	v_lshl_add_u64 v[184:185], s[44:45], 0, v[170:171]
	s_add_i32 m0, s37, 0xe000
	s_nop 0
	global_load_lds_dwordx4 v[184:185], off
	s_waitcnt vmcnt(8)
	s_waitcnt lgkmcnt(0)
	s_setprio 1
	s_waitcnt lgkmcnt(0)
	v_mfma_scale_f32_16x16x128_f8f6f4 v[156:159], v[24:31], v[176:183], v[156:159], v192, v192 op_sel_hi:[0,0,0]
	v_mfma_scale_f32_16x16x128_f8f6f4 v[152:155], v[16:23], v[176:183], v[152:155], v192, v192 op_sel_hi:[0,0,0]
	v_mfma_scale_f32_16x16x128_f8f6f4 v[140:143], v[24:31], v[196:203], v[140:143], v192, v192 op_sel_hi:[0,0,0]
	v_mfma_scale_f32_16x16x128_f8f6f4 v[136:139], v[16:23], v[196:203], v[136:139], v192, v192 op_sel_hi:[0,0,0]
	s_barrier
	v_mfma_scale_f32_16x16x128_f8f6f4 v[124:127], v[24:31], v[204:211], v[124:127], v192, v192 op_sel_hi:[0,0,0]
	v_mfma_scale_f32_16x16x128_f8f6f4 v[120:123], v[16:23], v[204:211], v[120:123], v192, v192 op_sel_hi:[0,0,0]
	v_mfma_scale_f32_16x16x128_f8f6f4 v[108:111], v[24:31], v[212:219], v[108:111], v192, v192 op_sel_hi:[0,0,0]
	v_mfma_scale_f32_16x16x128_f8f6f4 v[104:107], v[16:23], v[212:219], v[104:107], v192, v192 op_sel_hi:[0,0,0]
	s_setprio 0
	s_setprio 1
	v_mfma_scale_f32_16x16x128_f8f6f4 v[148:151], v[8:15], v[176:183], v[148:151], v192, v192 op_sel_hi:[0,0,0]
	v_mfma_scale_f32_16x16x128_f8f6f4 v[144:147], v[0:7], v[176:183], v[144:147], v192, v192 op_sel_hi:[0,0,0]
	v_mfma_scale_f32_16x16x128_f8f6f4 v[132:135], v[8:15], v[196:203], v[132:135], v192, v192 op_sel_hi:[0,0,0]
	v_mfma_scale_f32_16x16x128_f8f6f4 v[128:131], v[0:7], v[196:203], v[128:131], v192, v192 op_sel_hi:[0,0,0]
	v_mfma_scale_f32_16x16x128_f8f6f4 v[116:119], v[8:15], v[204:211], v[116:119], v192, v192 op_sel_hi:[0,0,0]
	v_mfma_scale_f32_16x16x128_f8f6f4 v[112:115], v[0:7], v[204:211], v[112:115], v192, v192 op_sel_hi:[0,0,0]
	v_mfma_scale_f32_16x16x128_f8f6f4 v[100:103], v[8:15], v[212:219], v[100:103], v192, v192 op_sel_hi:[0,0,0]
	v_mfma_scale_f32_16x16x128_f8f6f4 v[96:99], v[0:7], v[212:219], v[96:99], v192, v192 op_sel_hi:[0,0,0]
	s_setprio 0
	s_barrier
	s_add_i32 s44, s61, s35
	v_lshl_add_u64 v[176:177], s[46:47], 0, v[162:163]
	s_mov_b32 m0, s44
	ds_read_b128 v[196:199], v191 offset:16384
	ds_read_b128 v[200:203], v191 offset:17408
	ds_read_b128 v[204:207], v191 offset:18432
	ds_read_b128 v[208:211], v191 offset:19456
	ds_read_b128 v[212:215], v191 offset:20480
	ds_read_b128 v[216:219], v191 offset:21504
	ds_read_b128 v[220:223], v191 offset:22528
	ds_read_b128 v[224:227], v191 offset:23552
	global_load_lds_dwordx4 v[176:177], off
	s_add_i32 m0, s44, 0x2000
	s_add_u32 s44, s46, 0xb0000
	v_lshl_add_u64 v[178:179], s[46:47], 0, v[166:167]
	s_addc_u32 s45, s47, 0
	s_add_i32 s74, s62, s35
	global_load_lds_dwordx4 v[178:179], off
	v_lshl_add_u64 v[180:181], s[44:45], 0, v[162:163]
	s_mov_b32 m0, s74
	v_lshl_add_u64 v[182:183], s[48:49], 0, v[164:165]
	global_load_lds_dwordx4 v[180:181], off
	v_lshl_add_u64 v[180:181], s[44:45], 0, v[166:167]
	s_add_i32 m0, s74, 0x2000
	s_nop 0
	global_load_lds_dwordx4 v[180:181], off
	v_lshl_add_u64 v[180:181], s[48:49], 0, v[160:161]
	s_mov_b32 m0, s37
	s_nop 0
	global_load_lds_dwordx4 v[180:181], off
	s_mov_b32 m0, s39
	s_nop 0
	global_load_lds_dwordx4 v[182:183], off
	s_waitcnt vmcnt(8)
	s_waitcnt lgkmcnt(0)
	s_setprio 1
	s_waitcnt lgkmcnt(0)
	v_mfma_scale_f32_16x16x128_f8f6f4 v[92:95], v[24:31], v[196:203], v[92:95], v192, v192 op_sel_hi:[0,0,0]
	v_mfma_scale_f32_16x16x128_f8f6f4 v[88:91], v[16:23], v[196:203], v[88:91], v192, v192 op_sel_hi:[0,0,0]
	v_mfma_scale_f32_16x16x128_f8f6f4 v[76:79], v[24:31], v[204:211], v[76:79], v192, v192 op_sel_hi:[0,0,0]
	v_mfma_scale_f32_16x16x128_f8f6f4 v[72:75], v[16:23], v[204:211], v[72:75], v192, v192 op_sel_hi:[0,0,0]
	s_barrier
	v_mfma_scale_f32_16x16x128_f8f6f4 v[60:63], v[24:31], v[212:219], v[60:63], v192, v192 op_sel_hi:[0,0,0]
	v_mfma_scale_f32_16x16x128_f8f6f4 v[56:59], v[16:23], v[212:219], v[56:59], v192, v192 op_sel_hi:[0,0,0]
	v_mfma_scale_f32_16x16x128_f8f6f4 v[44:47], v[24:31], v[220:227], v[44:47], v192, v192 op_sel_hi:[0,0,0]
	v_mfma_scale_f32_16x16x128_f8f6f4 v[40:43], v[16:23], v[220:227], v[40:43], v192, v192 op_sel_hi:[0,0,0]
	s_setprio 0
	s_setprio 1
	v_mfma_scale_f32_16x16x128_f8f6f4 v[84:87], v[8:15], v[196:203], v[84:87], v192, v192 op_sel_hi:[0,0,0]
	v_mfma_scale_f32_16x16x128_f8f6f4 v[80:83], v[0:7], v[196:203], v[80:83], v192, v192 op_sel_hi:[0,0,0]
	v_mfma_scale_f32_16x16x128_f8f6f4 v[68:71], v[8:15], v[204:211], v[68:71], v192, v192 op_sel_hi:[0,0,0]
	v_mfma_scale_f32_16x16x128_f8f6f4 v[64:67], v[0:7], v[204:211], v[64:67], v192, v192 op_sel_hi:[0,0,0]
	v_mfma_scale_f32_16x16x128_f8f6f4 v[52:55], v[8:15], v[212:219], v[52:55], v192, v192 op_sel_hi:[0,0,0]
	v_mfma_scale_f32_16x16x128_f8f6f4 v[48:51], v[0:7], v[212:219], v[48:51], v192, v192 op_sel_hi:[0,0,0]
	v_mfma_scale_f32_16x16x128_f8f6f4 v[36:39], v[8:15], v[220:227], v[36:39], v192, v192 op_sel_hi:[0,0,0]
	v_mfma_scale_f32_16x16x128_f8f6f4 v[32:35], v[0:7], v[220:227], v[32:35], v192, v192 op_sel_hi:[0,0,0]
	s_setprio 0
	s_barrier
; #define PG8_STAGE(bufoff, gbase, voff) do { _Pragma("unroll") for (int _i = 0; _i < 2; ++_i) \
;         __builtin_amdgcn_global_load_lds((const unsigned*)((const char*)(gbase) + (voff)[_i]), (LAS unsigned*)(lds + (bufoff) + ldsw + _i * 8192), 16, 0, 0); } while (0)
; #define PG8_WAIT_V(n) asm volatile("s_waitcnt vmcnt(" #n ")" ::: "memory")
; #define PG8_WAIT_L(n) asm volatile("s_waitcnt lgkmcnt(" #n ")" ::: "memory")
;     ...
;         for (int t = 0; t < nt; t += 2) {
;             const bool last = (t == nt - 2);
;             const char* a1 = cA + (size_t)(t + 1) * kstep;
;             const char* a2 = last ? nA : cA + (size_t)(t + 2) * kstep; const char* b2 = last ? nB : cB + (size_t)(t + 2) * kstep;
;             const char* a3 = a2 + kstep; const char* b3 = b2 + kstep;
;             PG8_LDB(B0, 0, 0); PG8_LDB(B1, 0, 1); PG8_SCHED; PG8_LDA(At, 0, 0); PG8_STAGE(PG8_SA(1, 1), a1 + hstep, voffA);
;             PG8_WAIT_V(8); PG8_WAIT_L(0); PG8_BAR; PG8_MMA(0, 0, At, B0); PG8_MMA(0, 1, At, B1); PG8_BAR; PG8_SCHED;
;             PG8_LDA(At, 0, 1); PG8_STAGE(PG8_SB(0, 0), b2, voffB); PG8_STAGE(PG8_SB(0, 1), b2 + hstep, voffB); PG8_STAGE(PG8_SA(0, 0), a2, voffA);
;             PG8_WAIT_V(8); PG8_WAIT_L(0); PG8_BAR; PG8_MMA(1, 0, At, B0); PG8_MMA(1, 1, At, B1); PG8_BAR; PG8_SCHED;
;             PG8_LDB(B0, 1, 0); PG8_LDB(B1, 1, 1); PG8_SCHED; PG8_LDA(At, 1, 0); PG8_STAGE(PG8_SA(0, 1), a2 + hstep, voffA);
;             PG8_WAIT_V(8); PG8_WAIT_L(0); PG8_BAR; PG8_MMA(0, 0, At, B0); PG8_MMA(0, 1, At, B1); PG8_BAR; PG8_SCHED;
;             PG8_LDA(At, 1, 1); PG8_STAGE(PG8_SB(1, 0), b3, voffB); PG8_STAGE(PG8_SB(1, 1), b3 + hstep, voffB); PG8_STAGE(PG8_SA(1, 0), a3, voffA);
;             PG8_WAIT_V(8); PG8_WAIT_L(0); PG8_BAR; PG8_MMA(1, 0, At, B0); PG8_MMA(1, 1, At, B1); PG8_BAR; PG8_SCHED;
;         }
;         if constexpr (QM == 2) { const float qs0_ = g.qs * E.qscale(cur), qs1_ = qs0_ * g.qs_b1; _Pragma("unroll") for (int a = 0; a < 2; ++a) _Pragma("unroll") for (int b = 0; b < 2; ++b) _Pragma("unroll") for (int m = 0; m < 4; ++m) _Pragma("unroll") for (int n = 0; n < 2; ++n) { const v4i t_ = __builtin_bit_cast(v4i, acc[a][b][m][n]); acc[a][b][m][n] = (f32x4){(float)t_[0], (float)t_[1], (float)t_[2], (float)t_[3]} * (b == 0 ? qs0_ : qs1_); } }
;         if constexpr (QM == 1) asm volatile("s_nop 15\n\ts_nop 15\n\ts_nop 15" ::: "memory");
	s_add_i32 s74, 0, 0x18000
	s_add_i32 s75, 0, 0x1c000
	v_add_u32_e32 v12, s74, v187
	v_add_u32_e32 v28, s75, v187
	ds_read_b128 v[0:3], v12
	ds_read_b128 v[4:7], v12 offset:1024
	ds_read_b128 v[8:11], v12 offset:2048
	ds_read_b128 v[12:15], v12 offset:3072
	ds_read_b128 v[16:19], v28
	ds_read_b128 v[20:23], v28 offset:1024
	ds_read_b128 v[24:27], v28 offset:2048
	ds_read_b128 v[28:31], v28 offset:3072
	s_add_u32 s44, s48, 0xb0000
	s_addc_u32 s45, s49, 0
	s_mov_b32 m0, s50
	v_lshl_add_u64 v[184:185], s[44:45], 0, v[160:161]
	ds_read_b128 v[196:199], v191 offset:32768
	ds_read_b128 v[200:203], v191 offset:33792
	ds_read_b128 v[204:207], v191 offset:34816
	ds_read_b128 v[208:211], v191 offset:35840
	ds_read_b128 v[212:215], v191 offset:36864
	ds_read_b128 v[216:219], v191 offset:37888
	ds_read_b128 v[220:223], v191 offset:38912
	ds_read_b128 v[224:227], v191 offset:39936
	global_load_lds_dwordx4 v[184:185], off
	v_lshl_add_u64 v[184:185], s[44:45], 0, v[164:165]
	s_mov_b32 m0, s51
	s_nop 0
	global_load_lds_dwordx4 v[184:185], off
	s_waitcnt vmcnt(8)
	s_waitcnt lgkmcnt(0)
	s_setprio 1
	s_waitcnt lgkmcnt(0)
	v_mfma_scale_f32_16x16x128_f8f6f4 v[156:159], v[0:7], v[196:203], v[156:159], v192, v192 op_sel_hi:[0,0,0]
	v_mfma_scale_f32_16x16x128_f8f6f4 v[152:155], v[8:15], v[196:203], v[152:155], v192, v192 op_sel_hi:[0,0,0]
	v_mfma_scale_f32_16x16x128_f8f6f4 v[140:143], v[0:7], v[204:211], v[140:143], v192, v192 op_sel_hi:[0,0,0]
	v_mfma_scale_f32_16x16x128_f8f6f4 v[136:139], v[8:15], v[204:211], v[136:139], v192, v192 op_sel_hi:[0,0,0]
	s_barrier
	v_mfma_scale_f32_16x16x128_f8f6f4 v[124:127], v[0:7], v[212:219], v[124:127], v192, v192 op_sel_hi:[0,0,0]
	v_mfma_scale_f32_16x16x128_f8f6f4 v[120:123], v[8:15], v[212:219], v[120:123], v192, v192 op_sel_hi:[0,0,0]
	v_mfma_scale_f32_16x16x128_f8f6f4 v[108:111], v[0:7], v[220:227], v[108:111], v192, v192 op_sel_hi:[0,0,0]
	v_mfma_scale_f32_16x16x128_f8f6f4 v[104:107], v[8:15], v[220:227], v[104:107], v192, v192 op_sel_hi:[0,0,0]
	s_setprio 0
	s_setprio 1
	v_mfma_scale_f32_16x16x128_f8f6f4 v[148:151], v[16:23], v[196:203], v[148:151], v192, v192 op_sel_hi:[0,0,0]
	v_mfma_scale_f32_16x16x128_f8f6f4 v[144:147], v[24:31], v[196:203], v[144:147], v192, v192 op_sel_hi:[0,0,0]
	v_mfma_scale_f32_16x16x128_f8f6f4 v[132:135], v[16:23], v[204:211], v[132:135], v192, v192 op_sel_hi:[0,0,0]
	v_mfma_scale_f32_16x16x128_f8f6f4 v[128:131], v[24:31], v[204:211], v[128:131], v192, v192 op_sel_hi:[0,0,0]
	v_mfma_scale_f32_16x16x128_f8f6f4 v[116:119], v[16:23], v[212:219], v[116:119], v192, v192 op_sel_hi:[0,0,0]
	v_mfma_scale_f32_16x16x128_f8f6f4 v[112:115], v[24:31], v[212:219], v[112:115], v192, v192 op_sel_hi:[0,0,0]
	v_mfma_scale_f32_16x16x128_f8f6f4 v[100:103], v[16:23], v[220:227], v[100:103], v192, v192 op_sel_hi:[0,0,0]
	v_mfma_scale_f32_16x16x128_f8f6f4 v[96:99], v[24:31], v[220:227], v[96:99], v192, v192 op_sel_hi:[0,0,0]
	s_setprio 0
	s_barrier
	s_add_i32 s44, s74, s35
	v_lshl_add_u64 v[176:177], v[176:177], 0, s[24:25]
	s_mov_b32 m0, s44
	ds_read_b128 v[196:199], v191 offset:49152
	ds_read_b128 v[200:203], v191 offset:50176
	ds_read_b128 v[204:207], v191 offset:51200
	ds_read_b128 v[208:211], v191 offset:52224
	ds_read_b128 v[212:215], v191 offset:53248
	ds_read_b128 v[216:219], v191 offset:54272
	ds_read_b128 v[220:223], v191 offset:55296
	ds_read_b128 v[224:227], v191 offset:56320
	global_load_lds_dwordx4 v[176:177], off
	s_add_i32 m0, s44, 0x2000
	s_add_u32 s44, s46, 0xb0080
	v_lshl_add_u64 v[176:177], v[178:179], 0, s[24:25]
	s_addc_u32 s45, s47, 0
	s_add_i32 s46, s75, s35
	global_load_lds_dwordx4 v[176:177], off
	v_lshl_add_u64 v[176:177], s[44:45], 0, v[162:163]
	s_mov_b32 m0, s46
	s_nop 0
	global_load_lds_dwordx4 v[176:177], off
	v_lshl_add_u64 v[176:177], s[44:45], 0, v[166:167]
	s_add_i32 m0, s46, 0x2000
	s_nop 0
	global_load_lds_dwordx4 v[176:177], off
	v_lshl_add_u64 v[176:177], v[180:181], 0, s[24:25]
	s_mov_b32 m0, s55
	s_nop 0
	global_load_lds_dwordx4 v[176:177], off
	v_lshl_add_u64 v[176:177], v[182:183], 0, s[24:25]
	s_mov_b32 m0, s58
	s_nop 0
	global_load_lds_dwordx4 v[176:177], off
	s_waitcnt vmcnt(8)
	s_waitcnt lgkmcnt(0)
	s_setprio 1
	s_waitcnt lgkmcnt(0)
	v_mfma_scale_f32_16x16x128_f8f6f4 v[92:95], v[0:7], v[196:203], v[92:95], v192, v192 op_sel_hi:[0,0,0]
	v_mfma_scale_f32_16x16x128_f8f6f4 v[88:91], v[8:15], v[196:203], v[88:91], v192, v192 op_sel_hi:[0,0,0]
	v_mfma_scale_f32_16x16x128_f8f6f4 v[76:79], v[0:7], v[204:211], v[76:79], v192, v192 op_sel_hi:[0,0,0]
	v_mfma_scale_f32_16x16x128_f8f6f4 v[72:75], v[8:15], v[204:211], v[72:75], v192, v192 op_sel_hi:[0,0,0]
	s_barrier
	v_mfma_scale_f32_16x16x128_f8f6f4 v[60:63], v[0:7], v[212:219], v[60:63], v192, v192 op_sel_hi:[0,0,0]
	v_mfma_scale_f32_16x16x128_f8f6f4 v[56:59], v[8:15], v[212:219], v[56:59], v192, v192 op_sel_hi:[0,0,0]
	v_mfma_scale_f32_16x16x128_f8f6f4 v[44:47], v[0:7], v[220:227], v[44:47], v192, v192 op_sel_hi:[0,0,0]
	v_mfma_scale_f32_16x16x128_f8f6f4 v[40:43], v[8:15], v[220:227], v[40:43], v192, v192 op_sel_hi:[0,0,0]
	s_setprio 0
	s_setprio 1
	v_mfma_scale_f32_16x16x128_f8f6f4 v[84:87], v[16:23], v[196:203], v[84:87], v192, v192 op_sel_hi:[0,0,0]
	v_mfma_scale_f32_16x16x128_f8f6f4 v[80:83], v[24:31], v[196:203], v[80:83], v192, v192 op_sel_hi:[0,0,0]
	v_mfma_scale_f32_16x16x128_f8f6f4 v[68:71], v[16:23], v[204:211], v[68:71], v192, v192 op_sel_hi:[0,0,0]
	v_mfma_scale_f32_16x16x128_f8f6f4 v[64:67], v[24:31], v[204:211], v[64:67], v192, v192 op_sel_hi:[0,0,0]
	v_mfma_scale_f32_16x16x128_f8f6f4 v[52:55], v[16:23], v[212:219], v[52:55], v192, v192 op_sel_hi:[0,0,0]
	v_mfma_scale_f32_16x16x128_f8f6f4 v[48:51], v[24:31], v[212:219], v[48:51], v192, v192 op_sel_hi:[0,0,0]
	v_mfma_scale_f32_16x16x128_f8f6f4 v[36:39], v[16:23], v[220:227], v[36:39], v192, v192 op_sel_hi:[0,0,0]
	v_mfma_scale_f32_16x16x128_f8f6f4 v[32:35], v[24:31], v[220:227], v[32:35], v192, v192 op_sel_hi:[0,0,0]
	s_setprio 0
	s_barrier
	s_add_i32 s73, s73, 2
	s_add_u32 s71, s71, 0x100
	s_addc_u32 s72, s72, 0
	s_cmp_gt_u32 s73, 41
	s_mov_b64 s[44:45], s[6:7]
	s_cbranch_scc0 .LBB0_3858
	s_nop 15
	s_nop 15
	s_nop 15
	s_and_b64 vcc, exec, s[26:27]
	s_cbranch_vccz .LBB0_3861
	s_barrier

; #define PG8_STAGE(bufoff, gbase, voff) do { _Pragma("unroll") for (int _i = 0; _i < 2; ++_i) \
;         __builtin_amdgcn_global_load_lds((const unsigned*)((const char*)(gbase) + (voff)[_i]), (LAS unsigned*)(lds + (bufoff) + ldsw + _i * 8192), 16, 0, 0); } while (0)
; #define PG8_LDA(dst, b, h) do { _Pragma("unroll") for (int m = 0; m < 4; ++m) _Pragma("unroll") for (int k = 0; k < 2; ++k) dst[m][k] = *(const LAS bf16x8*)(lds + PG8_SA(b, h) + aoff + m * 2048 + k * 1024); } while (0)
; #define PG8_LDB(dst, b, h) do { _Pragma("unroll") for (int n = 0; n < 2; ++n) _Pragma("unroll") for (int k = 0; k < 2; ++k) dst[n][k] = *(const LAS bf16x8*)(lds + PG8_SB(b, h) + boff + n * 2048 + k * 1024); } while (0)
; #define PG8_WAIT_V(n) asm volatile("s_waitcnt vmcnt(" #n ")" ::: "memory")
; #define PG8_WAIT_L(n) asm volatile("s_waitcnt lgkmcnt(" #n ")" ::: "memory")
; #define PG8_BAR __builtin_amdgcn_s_barrier()
; #define PG8_SCHED __builtin_amdgcn_sched_barrier(0)
;     ...
;         for (int t = 0; t < nt; t += 2) {
;             const bool last = (t == nt - 2);
;             const char* a1 = cA + (size_t)(t + 1) * kstep;
;             const char* a2 = last ? nA : cA + (size_t)(t + 2) * kstep; const char* b2 = last ? nB : cB + (size_t)(t + 2) * kstep;
;             const char* a3 = a2 + kstep; const char* b3 = b2 + kstep;
;             PG8_LDB(B0, 0, 0); PG8_LDB(B1, 0, 1); PG8_SCHED; PG8_LDA(At, 0, 0); PG8_STAGE(PG8_SA(1, 1), a1 + hstep, voffA);
;             PG8_WAIT_V(8); PG8_WAIT_L(0); PG8_BAR; PG8_MMA(0, 0, At, B0); PG8_MMA(0, 1, At, B1); PG8_BAR; PG8_SCHED;
;             PG8_LDA(At, 0, 1); PG8_STAGE(PG8_SB(0, 0), b2, voffB); PG8_STAGE(PG8_SB(0, 1), b2 + hstep, voffB); PG8_STAGE(PG8_SA(0, 0), a2, voffA);
;             PG8_WAIT_V(8); PG8_WAIT_L(0); PG8_BAR; PG8_MMA(1, 0, At, B0); PG8_MMA(1, 1, At, B1); PG8_BAR; PG8_SCHED;
;             PG8_LDB(B0, 1, 0); PG8_LDB(B1, 1, 1); PG8_SCHED; PG8_LDA(At, 1, 0); PG8_STAGE(PG8_SA(0, 1), a2 + hstep, voffA);
;             PG8_WAIT_V(8); PG8_WAIT_L(0); PG8_BAR; PG8_MMA(0, 0, At, B0); PG8_MMA(0, 1, At, B1); PG8_BAR; PG8_SCHED;
;             PG8_LDA(At, 1, 1); PG8_STAGE(PG8_SB(1, 0), b3, voffB); PG8_STAGE(PG8_SB(1, 1), b3 + hstep, voffB); PG8_STAGE(PG8_SA(1, 0), a3, voffA);
;             PG8_WAIT_V(8); PG8_WAIT_L(0); PG8_BAR; PG8_MMA(1, 0, At, B0); PG8_MMA(1, 1, At, B1); PG8_BAR; PG8_SCHED;
.LBB0_3955:
	ds_read_b128 v[152:155], v183
	ds_read_b128 v[156:159], v183 offset:1024
	ds_read_b128 v[160:163], v183 offset:2048
	ds_read_b128 v[164:167], v183 offset:3072
	ds_read_b128 v[168:171], v184
	ds_read_b128 v[172:175], v184 offset:1024
	ds_read_b128 v[176:179], v184 offset:2048
	ds_read_b128 v[190:193], v184 offset:3072
	s_add_u32 s48, s46, 0xfffc0080
	s_addc_u32 s49, s47, -1
	s_cmp_eq_u32 s75, 12
	s_cselect_b32 s51, s7, s49
	s_cselect_b32 s50, s39, s48
	s_cselect_b32 s49, s37, s74
	s_cselect_b32 s48, s45, s73
	v_lshl_add_u64 v[226:227], s[46:47], 0, v[144:145]
	s_add_i32 m0, s35, 0xc000
	ds_read_b128 v[194:197], v185
	ds_read_b128 v[198:201], v185 offset:1024
	ds_read_b128 v[202:205], v185 offset:2048
	ds_read_b128 v[206:209], v185 offset:3072
	ds_read_b128 v[210:213], v185 offset:4096
	ds_read_b128 v[214:217], v185 offset:5120
	ds_read_b128 v[218:221], v185 offset:6144
	ds_read_b128 v[222:225], v185 offset:7168
	global_load_lds_dwordx4 v[226:227], off
	v_lshl_add_u64 v[226:227], s[46:47], 0, v[146:147]
	s_add_i32 m0, s35, 0xe000
	s_nop 0
	global_load_lds_dwordx4 v[226:227], off
	s_waitcnt vmcnt(8)
	s_waitcnt lgkmcnt(0)
	s_setprio 1
	s_waitcnt lgkmcnt(0)
	v_mfma_i32_16x16x64_i8 v[124:127], v[152:155], v[194:197], v[124:127]
	v_mfma_i32_16x16x64_i8 v[120:123], v[160:163], v[194:197], v[120:123]
	v_mfma_i32_16x16x64_i8 v[116:119], v[152:155], v[202:205], v[116:119]
	v_mfma_i32_16x16x64_i8 v[112:115], v[160:163], v[202:205], v[112:115]
	v_mfma_i32_16x16x64_i8 v[108:111], v[152:155], v[210:213], v[108:111]
	v_mfma_i32_16x16x64_i8 v[104:107], v[160:163], v[210:213], v[104:107]
	v_mfma_i32_16x16x64_i8 v[100:103], v[152:155], v[218:221], v[100:103]
	v_mfma_i32_16x16x64_i8 v[96:99], v[160:163], v[218:221], v[96:99]
	s_barrier
	v_mfma_i32_16x16x64_i8 v[124:127], v[156:159], v[198:201], v[124:127]
	v_mfma_i32_16x16x64_i8 v[120:123], v[164:167], v[198:201], v[120:123]
	v_mfma_i32_16x16x64_i8 v[116:119], v[156:159], v[206:209], v[116:119]
	v_mfma_i32_16x16x64_i8 v[112:115], v[164:167], v[206:209], v[112:115]
	v_mfma_i32_16x16x64_i8 v[108:111], v[156:159], v[214:217], v[108:111]
	v_mfma_i32_16x16x64_i8 v[104:107], v[164:167], v[214:217], v[104:107]
	v_mfma_i32_16x16x64_i8 v[100:103], v[156:159], v[222:225], v[100:103]
	v_mfma_i32_16x16x64_i8 v[96:99], v[164:167], v[222:225], v[96:99]
	s_setprio 0
	s_setprio 1
	v_mfma_i32_16x16x64_i8 v[60:63], v[168:171], v[194:197], v[60:63]
	v_mfma_i32_16x16x64_i8 v[56:59], v[176:179], v[194:197], v[56:59]
	v_mfma_i32_16x16x64_i8 v[52:55], v[168:171], v[202:205], v[52:55]
	v_mfma_i32_16x16x64_i8 v[48:51], v[176:179], v[202:205], v[48:51]
	v_mfma_i32_16x16x64_i8 v[44:47], v[168:171], v[210:213], v[44:47]
	v_mfma_i32_16x16x64_i8 v[40:43], v[176:179], v[210:213], v[40:43]
	v_mfma_i32_16x16x64_i8 v[36:39], v[168:171], v[218:221], v[36:39]
	v_mfma_i32_16x16x64_i8 v[32:35], v[176:179], v[218:221], v[32:35]
	v_mfma_i32_16x16x64_i8 v[60:63], v[172:175], v[198:201], v[60:63]
	v_mfma_i32_16x16x64_i8 v[56:59], v[190:193], v[198:201], v[56:59]
	v_mfma_i32_16x16x64_i8 v[52:55], v[172:175], v[206:209], v[52:55]
	v_mfma_i32_16x16x64_i8 v[48:51], v[190:193], v[206:209], v[48:51]
	v_mfma_i32_16x16x64_i8 v[44:47], v[172:175], v[214:217], v[44:47]
	v_mfma_i32_16x16x64_i8 v[40:43], v[190:193], v[214:217], v[40:43]
	v_mfma_i32_16x16x64_i8 v[36:39], v[172:175], v[222:225], v[36:39]
	v_mfma_i32_16x16x64_i8 v[32:35], v[190:193], v[222:225], v[32:35]
	s_setprio 0
	s_barrier
	s_add_i32 s76, s65, s34
	v_lshl_add_u64 v[226:227], s[48:49], 0, v[130:131]
	s_mov_b32 m0, s76
	ds_read_b128 v[194:197], v185 offset:16384
	ds_read_b128 v[198:201], v185 offset:17408
	ds_read_b128 v[202:205], v185 offset:18432
	ds_read_b128 v[206:209], v185 offset:19456
	ds_read_b128 v[210:213], v185 offset:20480
	ds_read_b128 v[214:217], v185 offset:21504
	ds_read_b128 v[218:221], v185 offset:22528
	ds_read_b128 v[222:225], v185 offset:23552
	global_load_lds_dwordx4 v[226:227], off
	s_add_i32 m0, s76, 0x2000
	s_add_u32 s76, s48, 0x40000
	v_lshl_add_u64 v[228:229], s[48:49], 0, v[134:135]
	s_addc_u32 s77, s49, 0
	s_add_i32 s78, s66, s34
	global_load_lds_dwordx4 v[228:229], off
	v_lshl_add_u64 v[230:231], s[76:77], 0, v[130:131]
	s_mov_b32 m0, s78
	v_lshl_add_u64 v[232:233], s[50:51], 0, v[132:133]
	global_load_lds_dwordx4 v[230:231], off
	v_lshl_add_u64 v[230:231], s[76:77], 0, v[134:135]
	s_add_i32 m0, s78, 0x2000
	s_nop 0
	global_load_lds_dwordx4 v[230:231], off
	v_lshl_add_u64 v[230:231], s[50:51], 0, v[128:129]
	s_mov_b32 m0, s35
	s_nop 0
	global_load_lds_dwordx4 v[230:231], off
	s_mov_b32 m0, s54
	s_nop 0
	global_load_lds_dwordx4 v[232:233], off
	s_waitcnt vmcnt(8)
	s_waitcnt lgkmcnt(0)
	s_setprio 1
	s_waitcnt lgkmcnt(0)
	v_mfma_i32_16x16x64_i8 v[92:95], v[152:155], v[194:197], v[92:95]
	v_mfma_i32_16x16x64_i8 v[88:91], v[160:163], v[194:197], v[88:91]
	v_mfma_i32_16x16x64_i8 v[84:87], v[152:155], v[202:205], v[84:87]
	v_mfma_i32_16x16x64_i8 v[80:83], v[160:163], v[202:205], v[80:83]
	v_mfma_i32_16x16x64_i8 v[76:79], v[152:155], v[210:213], v[76:79]
	v_mfma_i32_16x16x64_i8 v[72:75], v[160:163], v[210:213], v[72:75]
	v_mfma_i32_16x16x64_i8 v[68:71], v[152:155], v[218:221], v[68:71]
	v_mfma_i32_16x16x64_i8 v[64:67], v[160:163], v[218:221], v[64:67]
	s_barrier
; #define PG8_STAGE(bufoff, gbase, voff) do { _Pragma("unroll") for (int _i = 0; _i < 2; ++_i) \
;         __builtin_amdgcn_global_load_lds((const unsigned*)((const char*)(gbase) + (voff)[_i]), (LAS unsigned*)(lds + (bufoff) + ldsw + _i * 8192), 16, 0, 0); } while (0)
; #define PG8_LDA(dst, b, h) do { _Pragma("unroll") for (int m = 0; m < 4; ++m) _Pragma("unroll") for (int k = 0; k < 2; ++k) dst[m][k] = *(const LAS bf16x8*)(lds + PG8_SA(b, h) + aoff + m * 2048 + k * 1024); } while (0)
; #define PG8_LDB(dst, b, h) do { _Pragma("unroll") for (int n = 0; n < 2; ++n) _Pragma("unroll") for (int k = 0; k < 2; ++k) dst[n][k] = *(const LAS bf16x8*)(lds + PG8_SB(b, h) + boff + n * 2048 + k * 1024); } while (0)
; #define PG8_WAIT_V(n) asm volatile("s_waitcnt vmcnt(" #n ")" ::: "memory")
; #define PG8_WAIT_L(n) asm volatile("s_waitcnt lgkmcnt(" #n ")" ::: "memory")
; #define PG8_BAR __builtin_amdgcn_s_barrier()
; #define PG8_SCHED __builtin_amdgcn_sched_barrier(0)
;     ...
;         for (int t = 0; t < nt; t += 2) {
;             const bool last = (t == nt - 2);
;             const char* a1 = cA + (size_t)(t + 1) * kstep;
;             const char* a2 = last ? nA : cA + (size_t)(t + 2) * kstep; const char* b2 = last ? nB : cB + (size_t)(t + 2) * kstep;
;             const char* a3 = a2 + kstep; const char* b3 = b2 + kstep;
;             PG8_LDB(B0, 0, 0); PG8_LDB(B1, 0, 1); PG8_SCHED; PG8_LDA(At, 0, 0); PG8_STAGE(PG8_SA(1, 1), a1 + hstep, voffA);
;             PG8_WAIT_V(8); PG8_WAIT_L(0); PG8_BAR; PG8_MMA(0, 0, At, B0); PG8_MMA(0, 1, At, B1); PG8_BAR; PG8_SCHED;
;             PG8_LDA(At, 0, 1); PG8_STAGE(PG8_SB(0, 0), b2, voffB); PG8_STAGE(PG8_SB(0, 1), b2 + hstep, voffB); PG8_STAGE(PG8_SA(0, 0), a2, voffA);
;             PG8_WAIT_V(8); PG8_WAIT_L(0); PG8_BAR; PG8_MMA(1, 0, At, B0); PG8_MMA(1, 1, At, B1); PG8_BAR; PG8_SCHED;
;             PG8_LDB(B0, 1, 0); PG8_LDB(B1, 1, 1); PG8_SCHED; PG8_LDA(At, 1, 0); PG8_STAGE(PG8_SA(0, 1), a2 + hstep, voffA);
;             PG8_WAIT_V(8); PG8_WAIT_L(0); PG8_BAR; PG8_MMA(0, 0, At, B0); PG8_MMA(0, 1, At, B1); PG8_BAR; PG8_SCHED;
;             PG8_LDA(At, 1, 1); PG8_STAGE(PG8_SB(1, 0), b3, voffB); PG8_STAGE(PG8_SB(1, 1), b3 + hstep, voffB); PG8_STAGE(PG8_SA(1, 0), a3, voffA);
;             PG8_WAIT_V(8); PG8_WAIT_L(0); PG8_BAR; PG8_MMA(1, 0, At, B0); PG8_MMA(1, 1, At, B1); PG8_BAR; PG8_SCHED;
	v_mfma_i32_16x16x64_i8 v[92:95], v[156:159], v[198:201], v[92:95]
	v_mfma_i32_16x16x64_i8 v[88:91], v[164:167], v[198:201], v[88:91]
	v_mfma_i32_16x16x64_i8 v[84:87], v[156:159], v[206:209], v[84:87]
	v_mfma_i32_16x16x64_i8 v[80:83], v[164:167], v[206:209], v[80:83]
	v_mfma_i32_16x16x64_i8 v[76:79], v[156:159], v[214:217], v[76:79]
	v_mfma_i32_16x16x64_i8 v[72:75], v[164:167], v[214:217], v[72:75]
	v_mfma_i32_16x16x64_i8 v[68:71], v[156:159], v[222:225], v[68:71]
	v_mfma_i32_16x16x64_i8 v[64:67], v[164:167], v[222:225], v[64:67]
	s_setprio 0
	s_setprio 1
	v_mfma_i32_16x16x64_i8 v[28:31], v[168:171], v[194:197], v[28:31]
	v_mfma_i32_16x16x64_i8 v[24:27], v[176:179], v[194:197], v[24:27]
	v_mfma_i32_16x16x64_i8 v[20:23], v[168:171], v[202:205], v[20:23]
	v_mfma_i32_16x16x64_i8 v[16:19], v[176:179], v[202:205], v[16:19]
	v_mfma_i32_16x16x64_i8 v[12:15], v[168:171], v[210:213], v[12:15]
	v_mfma_i32_16x16x64_i8 v[8:11], v[176:179], v[210:213], v[8:11]
	v_mfma_i32_16x16x64_i8 v[4:7], v[168:171], v[218:221], v[4:7]
	v_mfma_i32_16x16x64_i8 v[0:3], v[176:179], v[218:221], v[0:3]
	v_mfma_i32_16x16x64_i8 v[28:31], v[172:175], v[198:201], v[28:31]
	v_mfma_i32_16x16x64_i8 v[24:27], v[190:193], v[198:201], v[24:27]
	v_mfma_i32_16x16x64_i8 v[20:23], v[172:175], v[206:209], v[20:23]
	v_mfma_i32_16x16x64_i8 v[16:19], v[190:193], v[206:209], v[16:19]
	v_mfma_i32_16x16x64_i8 v[12:15], v[172:175], v[214:217], v[12:15]
	v_mfma_i32_16x16x64_i8 v[8:11], v[190:193], v[214:217], v[8:11]
	v_mfma_i32_16x16x64_i8 v[4:7], v[172:175], v[222:225], v[4:7]
	v_mfma_i32_16x16x64_i8 v[0:3], v[190:193], v[222:225], v[0:3]
	s_setprio 0
	s_barrier
	s_add_i32 s76, 0, 0x18000
	v_add_u32_e32 v136, s76, v181
	s_add_i32 s77, 0, 0x1c000
	ds_read_b128 v[152:155], v136
	ds_read_b128 v[156:159], v136 offset:1024
	ds_read_b128 v[160:163], v136 offset:2048
	ds_read_b128 v[164:167], v136 offset:3072
	v_add_u32_e32 v136, s77, v181
	ds_read_b128 v[168:171], v136
	ds_read_b128 v[172:175], v136 offset:1024
	ds_read_b128 v[176:179], v136 offset:2048
	ds_read_b128 v[190:193], v136 offset:3072
	s_add_u32 s50, s50, 0x40000
	s_addc_u32 s51, s51, 0
	s_mov_b32 m0, s55
	v_lshl_add_u64 v[234:235], s[50:51], 0, v[128:129]
	ds_read_b128 v[194:197], v185 offset:32768
	ds_read_b128 v[198:201], v185 offset:33792
	ds_read_b128 v[202:205], v185 offset:34816
	ds_read_b128 v[206:209], v185 offset:35840
	ds_read_b128 v[210:213], v185 offset:36864
	ds_read_b128 v[214:217], v185 offset:37888
	ds_read_b128 v[218:221], v185 offset:38912
	ds_read_b128 v[222:225], v185 offset:39936
	global_load_lds_dwordx4 v[234:235], off
	v_lshl_add_u64 v[234:235], s[50:51], 0, v[132:133]
	s_mov_b32 m0, s58
	s_nop 0
	global_load_lds_dwordx4 v[234:235], off
	s_waitcnt vmcnt(8)
	s_waitcnt lgkmcnt(0)
	s_setprio 1
	s_waitcnt lgkmcnt(0)
	v_mfma_i32_16x16x64_i8 v[124:127], v[152:155], v[194:197], v[124:127]
	v_mfma_i32_16x16x64_i8 v[120:123], v[160:163], v[194:197], v[120:123]
	v_mfma_i32_16x16x64_i8 v[116:119], v[152:155], v[202:205], v[116:119]
	v_mfma_i32_16x16x64_i8 v[112:115], v[160:163], v[202:205], v[112:115]
	v_mfma_i32_16x16x64_i8 v[108:111], v[152:155], v[210:213], v[108:111]
	v_mfma_i32_16x16x64_i8 v[104:107], v[160:163], v[210:213], v[104:107]
	v_mfma_i32_16x16x64_i8 v[100:103], v[152:155], v[218:221], v[100:103]
	v_mfma_i32_16x16x64_i8 v[96:99], v[160:163], v[218:221], v[96:99]
	s_barrier
	v_mfma_i32_16x16x64_i8 v[124:127], v[156:159], v[198:201], v[124:127]
	v_mfma_i32_16x16x64_i8 v[120:123], v[164:167], v[198:201], v[120:123]
	v_mfma_i32_16x16x64_i8 v[116:119], v[156:159], v[206:209], v[116:119]
	v_mfma_i32_16x16x64_i8 v[112:115], v[164:167], v[206:209], v[112:115]
	v_mfma_i32_16x16x64_i8 v[108:111], v[156:159], v[214:217], v[108:111]
	v_mfma_i32_16x16x64_i8 v[104:107], v[164:167], v[214:217], v[104:107]
	v_mfma_i32_16x16x64_i8 v[100:103], v[156:159], v[222:225], v[100:103]
	v_mfma_i32_16x16x64_i8 v[96:99], v[164:167], v[222:225], v[96:99]
	s_setprio 0
	s_setprio 1
	v_mfma_i32_16x16x64_i8 v[60:63], v[168:171], v[194:197], v[60:63]
	v_mfma_i32_16x16x64_i8 v[56:59], v[176:179], v[194:197], v[56:59]
	v_mfma_i32_16x16x64_i8 v[52:55], v[168:171], v[202:205], v[52:55]
	v_mfma_i32_16x16x64_i8 v[48:51], v[176:179], v[202:205], v[48:51]
	v_mfma_i32_16x16x64_i8 v[44:47], v[168:171], v[210:213], v[44:47]
	v_mfma_i32_16x16x64_i8 v[40:43], v[176:179], v[210:213], v[40:43]
	v_mfma_i32_16x16x64_i8 v[36:39], v[168:171], v[218:221], v[36:39]
	v_mfma_i32_16x16x64_i8 v[32:35], v[176:179], v[218:221], v[32:35]
	v_mfma_i32_16x16x64_i8 v[60:63], v[172:175], v[198:201], v[60:63]
	v_mfma_i32_16x16x64_i8 v[56:59], v[190:193], v[198:201], v[56:59]
	v_mfma_i32_16x16x64_i8 v[52:55], v[172:175], v[206:209], v[52:55]
	v_mfma_i32_16x16x64_i8 v[48:51], v[190:193], v[206:209], v[48:51]
	v_mfma_i32_16x16x64_i8 v[44:47], v[172:175], v[214:217], v[44:47]
	v_mfma_i32_16x16x64_i8 v[40:43], v[190:193], v[214:217], v[40:43]
	v_mfma_i32_16x16x64_i8 v[36:39], v[172:175], v[222:225], v[36:39]
	v_mfma_i32_16x16x64_i8 v[32:35], v[190:193], v[222:225], v[32:35]
	s_setprio 0
	s_barrier
; #define PG8_STAGE(bufoff, gbase, voff) do { _Pragma("unroll") for (int _i = 0; _i < 2; ++_i) \
;         __builtin_amdgcn_global_load_lds((const unsigned*)((const char*)(gbase) + (voff)[_i]), (LAS unsigned*)(lds + (bufoff) + ldsw + _i * 8192), 16, 0, 0); } while (0)
; #define PG8_LDA(dst, b, h) do { _Pragma("unroll") for (int m = 0; m < 4; ++m) _Pragma("unroll") for (int k = 0; k < 2; ++k) dst[m][k] = *(const LAS bf16x8*)(lds + PG8_SA(b, h) + aoff + m * 2048 + k * 1024); } while (0)
; #define PG8_LDB(dst, b, h) do { _Pragma("unroll") for (int n = 0; n < 2; ++n) _Pragma("unroll") for (int k = 0; k < 2; ++k) dst[n][k] = *(const LAS bf16x8*)(lds + PG8_SB(b, h) + boff + n * 2048 + k * 1024); } while (0)
; #define PG8_WAIT_V(n) asm volatile("s_waitcnt vmcnt(" #n ")" ::: "memory")
; #define PG8_WAIT_L(n) asm volatile("s_waitcnt lgkmcnt(" #n ")" ::: "memory")
; #define PG8_BAR __builtin_amdgcn_s_barrier()
; #define PG8_SCHED __builtin_amdgcn_sched_barrier(0)
;     ...
;         for (int t = 0; t < nt; t += 2) {
;             const bool last = (t == nt - 2);
;             const char* a1 = cA + (size_t)(t + 1) * kstep;
;             const char* a2 = last ? nA : cA + (size_t)(t + 2) * kstep; const char* b2 = last ? nB : cB + (size_t)(t + 2) * kstep;
;             const char* a3 = a2 + kstep; const char* b3 = b2 + kstep;
;             PG8_LDB(B0, 0, 0); PG8_LDB(B1, 0, 1); PG8_SCHED; PG8_LDA(At, 0, 0); PG8_STAGE(PG8_SA(1, 1), a1 + hstep, voffA);
;             PG8_WAIT_V(8); PG8_WAIT_L(0); PG8_BAR; PG8_MMA(0, 0, At, B0); PG8_MMA(0, 1, At, B1); PG8_BAR; PG8_SCHED;
;             PG8_LDA(At, 0, 1); PG8_STAGE(PG8_SB(0, 0), b2, voffB); PG8_STAGE(PG8_SB(0, 1), b2 + hstep, voffB); PG8_STAGE(PG8_SA(0, 0), a2, voffA);
;             PG8_WAIT_V(8); PG8_WAIT_L(0); PG8_BAR; PG8_MMA(1, 0, At, B0); PG8_MMA(1, 1, At, B1); PG8_BAR; PG8_SCHED;
;             PG8_LDB(B0, 1, 0); PG8_LDB(B1, 1, 1); PG8_SCHED; PG8_LDA(At, 1, 0); PG8_STAGE(PG8_SA(0, 1), a2 + hstep, voffA);
;             PG8_WAIT_V(8); PG8_WAIT_L(0); PG8_BAR; PG8_MMA(0, 0, At, B0); PG8_MMA(0, 1, At, B1); PG8_BAR; PG8_SCHED;
;             PG8_LDA(At, 1, 1); PG8_STAGE(PG8_SB(1, 0), b3, voffB); PG8_STAGE(PG8_SB(1, 1), b3 + hstep, voffB); PG8_STAGE(PG8_SA(1, 0), a3, voffA);
;             PG8_WAIT_V(8); PG8_WAIT_L(0); PG8_BAR; PG8_MMA(1, 0, At, B0); PG8_MMA(1, 1, At, B1); PG8_BAR; PG8_SCHED;
;         }
	s_add_i32 s50, s76, s34
	v_lshl_add_u64 v[226:227], v[226:227], 0, s[18:19]
	s_mov_b32 m0, s50
	ds_read_b128 v[194:197], v185 offset:49152
	ds_read_b128 v[198:201], v185 offset:50176
	ds_read_b128 v[202:205], v185 offset:51200
	ds_read_b128 v[206:209], v185 offset:52224
	ds_read_b128 v[210:213], v185 offset:53248
	ds_read_b128 v[214:217], v185 offset:54272
	ds_read_b128 v[218:221], v185 offset:55296
	ds_read_b128 v[222:225], v185 offset:56320
	global_load_lds_dwordx4 v[226:227], off
	s_add_i32 m0, s50, 0x2000
	s_add_u32 s48, s48, 0x40080
	v_lshl_add_u64 v[226:227], v[228:229], 0, s[18:19]
	s_addc_u32 s49, s49, 0
	s_add_i32 s50, s77, s34
	global_load_lds_dwordx4 v[226:227], off
	v_lshl_add_u64 v[226:227], s[48:49], 0, v[130:131]
	s_mov_b32 m0, s50
	s_nop 0
	global_load_lds_dwordx4 v[226:227], off
	v_lshl_add_u64 v[226:227], s[48:49], 0, v[134:135]
	s_add_i32 m0, s50, 0x2000
	s_nop 0
	global_load_lds_dwordx4 v[226:227], off
	v_lshl_add_u64 v[226:227], v[230:231], 0, s[18:19]
	s_mov_b32 m0, s61
	s_nop 0
	global_load_lds_dwordx4 v[226:227], off
	v_lshl_add_u64 v[226:227], v[232:233], 0, s[18:19]
	s_mov_b32 m0, s62
	s_nop 0
	global_load_lds_dwordx4 v[226:227], off
	s_waitcnt vmcnt(8)
	s_waitcnt lgkmcnt(0)
	s_setprio 1
	s_waitcnt lgkmcnt(0)
	v_mfma_i32_16x16x64_i8 v[92:95], v[152:155], v[194:197], v[92:95]
	v_mfma_i32_16x16x64_i8 v[88:91], v[160:163], v[194:197], v[88:91]
	v_mfma_i32_16x16x64_i8 v[84:87], v[152:155], v[202:205], v[84:87]
	v_mfma_i32_16x16x64_i8 v[80:83], v[160:163], v[202:205], v[80:83]
	v_mfma_i32_16x16x64_i8 v[76:79], v[152:155], v[210:213], v[76:79]
	v_mfma_i32_16x16x64_i8 v[72:75], v[160:163], v[210:213], v[72:75]
	v_mfma_i32_16x16x64_i8 v[68:71], v[152:155], v[218:221], v[68:71]
	v_mfma_i32_16x16x64_i8 v[64:67], v[160:163], v[218:221], v[64:67]
	s_barrier
	v_mfma_i32_16x16x64_i8 v[92:95], v[156:159], v[198:201], v[92:95]
	v_mfma_i32_16x16x64_i8 v[88:91], v[164:167], v[198:201], v[88:91]
	v_mfma_i32_16x16x64_i8 v[84:87], v[156:159], v[206:209], v[84:87]
	v_mfma_i32_16x16x64_i8 v[80:83], v[164:167], v[206:209], v[80:83]
	v_mfma_i32_16x16x64_i8 v[76:79], v[156:159], v[214:217], v[76:79]
	v_mfma_i32_16x16x64_i8 v[72:75], v[164:167], v[214:217], v[72:75]
	v_mfma_i32_16x16x64_i8 v[68:71], v[156:159], v[222:225], v[68:71]
	v_mfma_i32_16x16x64_i8 v[64:67], v[164:167], v[222:225], v[64:67]
	s_setprio 0
	s_setprio 1
	v_mfma_i32_16x16x64_i8 v[28:31], v[168:171], v[194:197], v[28:31]
	v_mfma_i32_16x16x64_i8 v[24:27], v[176:179], v[194:197], v[24:27]
	v_mfma_i32_16x16x64_i8 v[20:23], v[168:171], v[202:205], v[20:23]
	v_mfma_i32_16x16x64_i8 v[16:19], v[176:179], v[202:205], v[16:19]
	v_mfma_i32_16x16x64_i8 v[12:15], v[168:171], v[210:213], v[12:15]
	v_mfma_i32_16x16x64_i8 v[8:11], v[176:179], v[210:213], v[8:11]
	v_mfma_i32_16x16x64_i8 v[4:7], v[168:171], v[218:221], v[4:7]
	v_mfma_i32_16x16x64_i8 v[0:3], v[176:179], v[218:221], v[0:3]
	v_mfma_i32_16x16x64_i8 v[28:31], v[172:175], v[198:201], v[28:31]
	v_mfma_i32_16x16x64_i8 v[24:27], v[190:193], v[198:201], v[24:27]
	v_mfma_i32_16x16x64_i8 v[20:23], v[172:175], v[206:209], v[20:23]
	v_mfma_i32_16x16x64_i8 v[16:19], v[190:193], v[206:209], v[16:19]
	v_mfma_i32_16x16x64_i8 v[12:15], v[172:175], v[214:217], v[12:15]
	v_mfma_i32_16x16x64_i8 v[8:11], v[190:193], v[214:217], v[8:11]
	v_mfma_i32_16x16x64_i8 v[4:7], v[172:175], v[222:225], v[4:7]
	v_mfma_i32_16x16x64_i8 v[0:3], v[190:193], v[222:225], v[0:3]
	s_setprio 0
	s_barrier
	s_add_i32 s75, s75, 2
	s_add_u32 s46, s46, 0x100
	s_addc_u32 s47, s47, 0
	s_add_u32 s73, s73, 0x100
	s_addc_u32 s74, s74, 0
	s_cmp_gt_u32 s75, 13
	s_cbranch_scc0 .LBB0_3955
	s_and_b64 vcc, exec, s[20:21]
	s_cbranch_vccz .LBB0_3958
	s_barrier

; #define PG8_STAGE(bufoff, gbase, voff) do { _Pragma("unroll") for (int _i = 0; _i < 2; ++_i) \
;         __builtin_amdgcn_global_load_lds((const unsigned*)((const char*)(gbase) + (voff)[_i]), (LAS unsigned*)(lds + (bufoff) + ldsw + _i * 8192), 16, 0, 0); } while (0)
; #define PG8_LDA(dst, b, h) do { _Pragma("unroll") for (int m = 0; m < 4; ++m) _Pragma("unroll") for (int k = 0; k < 2; ++k) dst[m][k] = *(const LAS bf16x8*)(lds + PG8_SA(b, h) + aoff + m * 2048 + k * 1024); } while (0)
; #define PG8_LDB(dst, b, h) do { _Pragma("unroll") for (int n = 0; n < 2; ++n) _Pragma("unroll") for (int k = 0; k < 2; ++k) dst[n][k] = *(const LAS bf16x8*)(lds + PG8_SB(b, h) + boff + n * 2048 + k * 1024); } while (0)
; #define PG8_WAIT_V(n) asm volatile("s_waitcnt vmcnt(" #n ")" ::: "memory")
; #define PG8_WAIT_L(n) asm volatile("s_waitcnt lgkmcnt(" #n ")" ::: "memory")
; #define PG8_BAR __builtin_amdgcn_s_barrier()
; #define PG8_SCHED __builtin_amdgcn_sched_barrier(0)
;     ...
;         const bool has_next = S.next(ui + 1, nxt);
;         const char* nA = has_next ? (const char*)g.A + (size_t)nxt.pm * tstep + (size_t)nxt.kt0 * kstep : cA; const char* nB = has_next ? (const char*)g.Bt + (size_t)nxt.e * g.estride + (size_t)nxt.pn * tstep + (size_t)nxt.kt0 * kstep : cB;
;         const int nt = cur.nkt;
;         for (int t = 0; t < nt; t += 2) {
;             const bool last = (t == nt - 2);
;             const char* a1 = cA + (size_t)(t + 1) * kstep;
;             const char* a2 = last ? nA : cA + (size_t)(t + 2) * kstep; const char* b2 = last ? nB : cB + (size_t)(t + 2) * kstep;
;             const char* a3 = a2 + kstep; const char* b3 = b2 + kstep;
;             PG8_LDB(B0, 0, 0); PG8_LDB(B1, 0, 1); PG8_SCHED; PG8_LDA(At, 0, 0); PG8_STAGE(PG8_SA(1, 1), a1 + hstep, voffA);
;             PG8_WAIT_V(8); PG8_WAIT_L(0); PG8_BAR; PG8_MMA(0, 0, At, B0); PG8_MMA(0, 1, At, B1); PG8_BAR; PG8_SCHED;
;             PG8_LDA(At, 0, 1); PG8_STAGE(PG8_SB(0, 0), b2, voffB); PG8_STAGE(PG8_SB(0, 1), b2 + hstep, voffB); PG8_STAGE(PG8_SA(0, 0), a2, voffA);
;             PG8_WAIT_V(8); PG8_WAIT_L(0); PG8_BAR; PG8_MMA(1, 0, At, B0); PG8_MMA(1, 1, At, B1); PG8_BAR; PG8_SCHED;
.LBB0_4054:
	s_add_u32 s49, s40, s48
	s_addc_u32 s60, s41, 0
	s_add_u32 s58, s49, 0x100
	s_addc_u32 s59, s60, 0
	s_and_b64 s[50:51], s[46:47], exec
	s_cselect_b32 s51, s5, s59
	s_cselect_b32 s50, s31, s58
	s_add_u32 s48, s6, s48
	s_addc_u32 s58, s7, 0
	s_add_u32 s48, s48, 0x100
	s_addc_u32 s58, s58, 0
	s_and_b64 s[46:47], s[46:47], exec
	s_cselect_b32 s59, s29, s58
	s_cselect_b32 s58, s43, s48
	s_add_u32 s62, s49, 0x10080
	s_addc_u32 s63, s60, 0
	s_add_i32 s89, s78, s65
	s_add_i32 m0, s66, 0xc000
	s_add_i32 s92, s66, 0xe000
	s_add_i32 s86, s89, 0x2000
	v_add_u32_e32 v136, s78, v160
	s_add_u32 s60, s58, 0x10000
	ds_read_b128 v[152:155], v136
	ds_read_b128 v[156:159], v136 offset:1024
	ds_read_b128 v[164:167], v136 offset:2048
	ds_read_b128 v[168:171], v136 offset:3072
	v_add_u32_e32 v136, s79, v160
	s_addc_u32 s61, s59, 0
	s_add_i32 s88, s79, s65
	ds_read_b128 v[172:175], v136
	ds_read_b128 v[176:179], v136 offset:1024
	ds_read_b128 v[180:183], v136 offset:2048
	ds_read_b128 v[184:187], v136 offset:3072
	s_add_i32 s87, s88, 0x2000
	s_add_i32 s85, 0, 0x18000
	s_add_i32 s84, 0, 0x1c000
	s_add_u32 s48, s50, 0x10000
	s_addc_u32 s49, s51, 0
	s_add_i32 s83, s85, s65
	s_add_i32 s82, s83, 0x2000
	s_add_u32 s46, s58, 0x10080
	s_addc_u32 s47, s59, 0
	s_add_i32 s91, s84, s65
	s_add_i32 s90, s91, 0x2000
	v_lshl_add_u64 v[220:221], s[62:63], 0, v[128:129]
	ds_read_b128 v[188:191], v161
	ds_read_b128 v[192:195], v161 offset:1024
	ds_read_b128 v[196:199], v161 offset:2048
	ds_read_b128 v[200:203], v161 offset:3072
	ds_read_b128 v[204:207], v161 offset:4096
	ds_read_b128 v[208:211], v161 offset:5120
	ds_read_b128 v[212:215], v161 offset:6144
	ds_read_b128 v[216:219], v161 offset:7168
	global_load_lds_dwordx4 v[220:221], off
	v_lshl_add_u64 v[220:221], s[62:63], 0, v[132:133]
	s_mov_b32 m0, s92
	s_nop 0
	global_load_lds_dwordx4 v[220:221], off
	s_waitcnt vmcnt(8)
	s_waitcnt lgkmcnt(0)
	s_setprio 1
	s_waitcnt lgkmcnt(0)
	v_mfma_i32_16x16x64_i8 v[124:127], v[152:155], v[188:191], v[124:127]
	v_mfma_i32_16x16x64_i8 v[120:123], v[164:167], v[188:191], v[120:123]
	v_mfma_i32_16x16x64_i8 v[108:111], v[152:155], v[196:199], v[108:111]
	v_mfma_i32_16x16x64_i8 v[104:107], v[164:167], v[196:199], v[104:107]
	v_mfma_i32_16x16x64_i8 v[92:95], v[152:155], v[204:207], v[92:95]
	v_mfma_i32_16x16x64_i8 v[88:91], v[164:167], v[204:207], v[88:91]
	v_mfma_i32_16x16x64_i8 v[76:79], v[152:155], v[212:215], v[76:79]
	v_mfma_i32_16x16x64_i8 v[72:75], v[164:167], v[212:215], v[72:75]
	s_barrier
	v_mfma_i32_16x16x64_i8 v[124:127], v[156:159], v[192:195], v[124:127]
	v_mfma_i32_16x16x64_i8 v[120:123], v[168:171], v[192:195], v[120:123]
	v_mfma_i32_16x16x64_i8 v[108:111], v[156:159], v[200:203], v[108:111]
	v_mfma_i32_16x16x64_i8 v[104:107], v[168:171], v[200:203], v[104:107]
	v_mfma_i32_16x16x64_i8 v[92:95], v[156:159], v[208:211], v[92:95]
	v_mfma_i32_16x16x64_i8 v[88:91], v[168:171], v[208:211], v[88:91]
	v_mfma_i32_16x16x64_i8 v[76:79], v[156:159], v[216:219], v[76:79]
	v_mfma_i32_16x16x64_i8 v[72:75], v[168:171], v[216:219], v[72:75]
	s_setprio 0
	s_setprio 1
	v_mfma_i32_16x16x64_i8 v[116:119], v[172:175], v[188:191], v[116:119]
	v_mfma_i32_16x16x64_i8 v[112:115], v[180:183], v[188:191], v[112:115]
	v_mfma_i32_16x16x64_i8 v[100:103], v[172:175], v[196:199], v[100:103]
	v_mfma_i32_16x16x64_i8 v[96:99], v[180:183], v[196:199], v[96:99]
	v_mfma_i32_16x16x64_i8 v[84:87], v[172:175], v[204:207], v[84:87]
	v_mfma_i32_16x16x64_i8 v[80:83], v[180:183], v[204:207], v[80:83]
	v_mfma_i32_16x16x64_i8 v[68:71], v[172:175], v[212:215], v[68:71]
	v_mfma_i32_16x16x64_i8 v[64:67], v[180:183], v[212:215], v[64:67]
	v_mfma_i32_16x16x64_i8 v[116:119], v[176:179], v[192:195], v[116:119]
	v_mfma_i32_16x16x64_i8 v[112:115], v[184:187], v[192:195], v[112:115]
	v_mfma_i32_16x16x64_i8 v[100:103], v[176:179], v[200:203], v[100:103]
	v_mfma_i32_16x16x64_i8 v[96:99], v[184:187], v[200:203], v[96:99]
	v_mfma_i32_16x16x64_i8 v[84:87], v[176:179], v[208:211], v[84:87]
	v_mfma_i32_16x16x64_i8 v[80:83], v[184:187], v[208:211], v[80:83]
	v_mfma_i32_16x16x64_i8 v[68:71], v[176:179], v[216:219], v[68:71]
	v_mfma_i32_16x16x64_i8 v[64:67], v[184:187], v[216:219], v[64:67]
	s_setprio 0
	s_barrier
	s_mov_b32 m0, s89
	v_lshl_add_u64 v[220:221], s[58:59], 0, v[130:131]
	ds_read_b128 v[188:191], v161 offset:16384
	ds_read_b128 v[192:195], v161 offset:17408
	ds_read_b128 v[196:199], v161 offset:18432
	ds_read_b128 v[200:203], v161 offset:19456
	ds_read_b128 v[204:207], v161 offset:20480
	ds_read_b128 v[208:211], v161 offset:21504
	ds_read_b128 v[212:215], v161 offset:22528
	ds_read_b128 v[216:219], v161 offset:23552
	global_load_lds_dwordx4 v[220:221], off
	v_lshl_add_u64 v[222:223], s[58:59], 0, v[134:135]
	s_mov_b32 m0, s86
	v_lshl_add_u64 v[224:225], s[60:61], 0, v[130:131]
	global_load_lds_dwordx4 v[222:223], off
	s_mov_b32 m0, s88
	v_lshl_add_u64 v[226:227], s[50:51], 0, v[132:133]
	global_load_lds_dwordx4 v[224:225], off
	v_lshl_add_u64 v[224:225], s[60:61], 0, v[134:135]
	s_mov_b32 m0, s87
	s_nop 0
	global_load_lds_dwordx4 v[224:225], off
	v_lshl_add_u64 v[224:225], s[50:51], 0, v[128:129]
	s_mov_b32 m0, s66
	s_nop 0
	global_load_lds_dwordx4 v[224:225], off
	s_mov_b32 m0, s67
	s_nop 0
	global_load_lds_dwordx4 v[226:227], off
	s_waitcnt vmcnt(8)
	s_waitcnt lgkmcnt(0)
	s_setprio 1
	s_waitcnt lgkmcnt(0)
	v_mfma_i32_16x16x64_i8 v[60:63], v[152:155], v[188:191], v[60:63]
	v_mfma_i32_16x16x64_i8 v[56:59], v[164:167], v[188:191], v[56:59]
	v_mfma_i32_16x16x64_i8 v[44:47], v[152:155], v[196:199], v[44:47]
	v_mfma_i32_16x16x64_i8 v[40:43], v[164:167], v[196:199], v[40:43]
	v_mfma_i32_16x16x64_i8 v[28:31], v[152:155], v[204:207], v[28:31]
	v_mfma_i32_16x16x64_i8 v[24:27], v[164:167], v[204:207], v[24:27]
	v_mfma_i32_16x16x64_i8 v[12:15], v[152:155], v[212:215], v[12:15]
	v_mfma_i32_16x16x64_i8 v[8:11], v[164:167], v[212:215], v[8:11]
	s_barrier
; #define PG8_STAGE(bufoff, gbase, voff) do { _Pragma("unroll") for (int _i = 0; _i < 2; ++_i) \
;         __builtin_amdgcn_global_load_lds((const unsigned*)((const char*)(gbase) + (voff)[_i]), (LAS unsigned*)(lds + (bufoff) + ldsw + _i * 8192), 16, 0, 0); } while (0)
; #define PG8_LDA(dst, b, h) do { _Pragma("unroll") for (int m = 0; m < 4; ++m) _Pragma("unroll") for (int k = 0; k < 2; ++k) dst[m][k] = *(const LAS bf16x8*)(lds + PG8_SA(b, h) + aoff + m * 2048 + k * 1024); } while (0)
; #define PG8_LDB(dst, b, h) do { _Pragma("unroll") for (int n = 0; n < 2; ++n) _Pragma("unroll") for (int k = 0; k < 2; ++k) dst[n][k] = *(const LAS bf16x8*)(lds + PG8_SB(b, h) + boff + n * 2048 + k * 1024); } while (0)
; #define PG8_WAIT_V(n) asm volatile("s_waitcnt vmcnt(" #n ")" ::: "memory")
; #define PG8_WAIT_L(n) asm volatile("s_waitcnt lgkmcnt(" #n ")" ::: "memory")
; #define PG8_BAR __builtin_amdgcn_s_barrier()
; #define PG8_SCHED __builtin_amdgcn_sched_barrier(0)
;     ...
;             PG8_LDA(At, 0, 1); PG8_STAGE(PG8_SB(0, 0), b2, voffB); PG8_STAGE(PG8_SB(0, 1), b2 + hstep, voffB); PG8_STAGE(PG8_SA(0, 0), a2, voffA);
;             PG8_WAIT_V(8); PG8_WAIT_L(0); PG8_BAR; PG8_MMA(1, 0, At, B0); PG8_MMA(1, 1, At, B1); PG8_BAR; PG8_SCHED;
;             PG8_LDB(B0, 1, 0); PG8_LDB(B1, 1, 1); PG8_SCHED; PG8_LDA(At, 1, 0); PG8_STAGE(PG8_SA(0, 1), a2 + hstep, voffA);
;             PG8_WAIT_V(8); PG8_WAIT_L(0); PG8_BAR; PG8_MMA(0, 0, At, B0); PG8_MMA(0, 1, At, B1); PG8_BAR; PG8_SCHED;
;             PG8_LDA(At, 1, 1); PG8_STAGE(PG8_SB(1, 0), b3, voffB); PG8_STAGE(PG8_SB(1, 1), b3 + hstep, voffB); PG8_STAGE(PG8_SA(1, 0), a3, voffA);
	v_mfma_i32_16x16x64_i8 v[60:63], v[156:159], v[192:195], v[60:63]
	v_mfma_i32_16x16x64_i8 v[56:59], v[168:171], v[192:195], v[56:59]
	v_mfma_i32_16x16x64_i8 v[44:47], v[156:159], v[200:203], v[44:47]
	v_mfma_i32_16x16x64_i8 v[40:43], v[168:171], v[200:203], v[40:43]
	v_mfma_i32_16x16x64_i8 v[28:31], v[156:159], v[208:211], v[28:31]
	v_mfma_i32_16x16x64_i8 v[24:27], v[168:171], v[208:211], v[24:27]
	v_mfma_i32_16x16x64_i8 v[12:15], v[156:159], v[216:219], v[12:15]
	v_mfma_i32_16x16x64_i8 v[8:11], v[168:171], v[216:219], v[8:11]
	s_setprio 0
	s_setprio 1
	v_mfma_i32_16x16x64_i8 v[52:55], v[172:175], v[188:191], v[52:55]
	v_mfma_i32_16x16x64_i8 v[48:51], v[180:183], v[188:191], v[48:51]
	v_mfma_i32_16x16x64_i8 v[36:39], v[172:175], v[196:199], v[36:39]
	v_mfma_i32_16x16x64_i8 v[32:35], v[180:183], v[196:199], v[32:35]
	v_mfma_i32_16x16x64_i8 v[20:23], v[172:175], v[204:207], v[20:23]
	v_mfma_i32_16x16x64_i8 v[16:19], v[180:183], v[204:207], v[16:19]
	v_mfma_i32_16x16x64_i8 v[4:7], v[172:175], v[212:215], v[4:7]
	v_mfma_i32_16x16x64_i8 v[0:3], v[180:183], v[212:215], v[0:3]
	v_mfma_i32_16x16x64_i8 v[52:55], v[176:179], v[192:195], v[52:55]
	v_mfma_i32_16x16x64_i8 v[48:51], v[184:187], v[192:195], v[48:51]
	v_mfma_i32_16x16x64_i8 v[36:39], v[176:179], v[200:203], v[36:39]
	v_mfma_i32_16x16x64_i8 v[32:35], v[184:187], v[200:203], v[32:35]
	v_mfma_i32_16x16x64_i8 v[20:23], v[176:179], v[208:211], v[20:23]
	v_mfma_i32_16x16x64_i8 v[16:19], v[184:187], v[208:211], v[16:19]
	v_mfma_i32_16x16x64_i8 v[4:7], v[176:179], v[216:219], v[4:7]
	v_mfma_i32_16x16x64_i8 v[0:3], v[184:187], v[216:219], v[0:3]
	s_setprio 0
	s_barrier
	v_add_u32_e32 v136, s85, v160
	ds_read_b128 v[152:155], v136
	ds_read_b128 v[156:159], v136 offset:1024
	ds_read_b128 v[164:167], v136 offset:2048
	ds_read_b128 v[168:171], v136 offset:3072
	v_add_u32_e32 v136, s84, v160
	ds_read_b128 v[172:175], v136
	ds_read_b128 v[176:179], v136 offset:1024
	ds_read_b128 v[180:183], v136 offset:2048
	ds_read_b128 v[184:187], v136 offset:3072
	s_mov_b32 m0, s68
	v_lshl_add_u64 v[228:229], s[48:49], 0, v[128:129]
	ds_read_b128 v[188:191], v161 offset:32768
	ds_read_b128 v[192:195], v161 offset:33792
	ds_read_b128 v[196:199], v161 offset:34816
	ds_read_b128 v[200:203], v161 offset:35840
	ds_read_b128 v[204:207], v161 offset:36864
	ds_read_b128 v[208:211], v161 offset:37888
	ds_read_b128 v[212:215], v161 offset:38912
	ds_read_b128 v[216:219], v161 offset:39936
	global_load_lds_dwordx4 v[228:229], off
	v_lshl_add_u64 v[228:229], s[48:49], 0, v[132:133]
	s_mov_b32 m0, s69
	s_nop 0
	global_load_lds_dwordx4 v[228:229], off
	s_waitcnt vmcnt(8)
	s_waitcnt lgkmcnt(0)
	s_setprio 1
	s_waitcnt lgkmcnt(0)
	v_mfma_i32_16x16x64_i8 v[124:127], v[152:155], v[188:191], v[124:127]
	v_mfma_i32_16x16x64_i8 v[120:123], v[164:167], v[188:191], v[120:123]
	v_mfma_i32_16x16x64_i8 v[108:111], v[152:155], v[196:199], v[108:111]
	v_mfma_i32_16x16x64_i8 v[104:107], v[164:167], v[196:199], v[104:107]
	v_mfma_i32_16x16x64_i8 v[92:95], v[152:155], v[204:207], v[92:95]
	v_mfma_i32_16x16x64_i8 v[88:91], v[164:167], v[204:207], v[88:91]
	v_mfma_i32_16x16x64_i8 v[76:79], v[152:155], v[212:215], v[76:79]
	v_mfma_i32_16x16x64_i8 v[72:75], v[164:167], v[212:215], v[72:75]
	s_barrier
	v_mfma_i32_16x16x64_i8 v[124:127], v[156:159], v[192:195], v[124:127]
	v_mfma_i32_16x16x64_i8 v[120:123], v[168:171], v[192:195], v[120:123]
	v_mfma_i32_16x16x64_i8 v[108:111], v[156:159], v[200:203], v[108:111]
	v_mfma_i32_16x16x64_i8 v[104:107], v[168:171], v[200:203], v[104:107]
	v_mfma_i32_16x16x64_i8 v[92:95], v[156:159], v[208:211], v[92:95]
	v_mfma_i32_16x16x64_i8 v[88:91], v[168:171], v[208:211], v[88:91]
	v_mfma_i32_16x16x64_i8 v[76:79], v[156:159], v[216:219], v[76:79]
	v_mfma_i32_16x16x64_i8 v[72:75], v[168:171], v[216:219], v[72:75]
	s_setprio 0
	s_setprio 1
	v_mfma_i32_16x16x64_i8 v[116:119], v[172:175], v[188:191], v[116:119]
	v_mfma_i32_16x16x64_i8 v[112:115], v[180:183], v[188:191], v[112:115]
	v_mfma_i32_16x16x64_i8 v[100:103], v[172:175], v[196:199], v[100:103]
	v_mfma_i32_16x16x64_i8 v[96:99], v[180:183], v[196:199], v[96:99]
	v_mfma_i32_16x16x64_i8 v[84:87], v[172:175], v[204:207], v[84:87]
	v_mfma_i32_16x16x64_i8 v[80:83], v[180:183], v[204:207], v[80:83]
	v_mfma_i32_16x16x64_i8 v[68:71], v[172:175], v[212:215], v[68:71]
	v_mfma_i32_16x16x64_i8 v[64:67], v[180:183], v[212:215], v[64:67]
	v_mfma_i32_16x16x64_i8 v[116:119], v[176:179], v[192:195], v[116:119]
	v_mfma_i32_16x16x64_i8 v[112:115], v[184:187], v[192:195], v[112:115]
	v_mfma_i32_16x16x64_i8 v[100:103], v[176:179], v[200:203], v[100:103]
	v_mfma_i32_16x16x64_i8 v[96:99], v[184:187], v[200:203], v[96:99]
	v_mfma_i32_16x16x64_i8 v[84:87], v[176:179], v[208:211], v[84:87]
	v_mfma_i32_16x16x64_i8 v[80:83], v[184:187], v[208:211], v[80:83]
	v_mfma_i32_16x16x64_i8 v[68:71], v[176:179], v[216:219], v[68:71]
	v_mfma_i32_16x16x64_i8 v[64:67], v[184:187], v[216:219], v[64:67]
	s_setprio 0
	s_barrier
; #define PG8_STAGE(bufoff, gbase, voff) do { _Pragma("unroll") for (int _i = 0; _i < 2; ++_i) \
;         __builtin_amdgcn_global_load_lds((const unsigned*)((const char*)(gbase) + (voff)[_i]), (LAS unsigned*)(lds + (bufoff) + ldsw + _i * 8192), 16, 0, 0); } while (0)
; #define PG8_LDA(dst, b, h) do { _Pragma("unroll") for (int m = 0; m < 4; ++m) _Pragma("unroll") for (int k = 0; k < 2; ++k) dst[m][k] = *(const LAS bf16x8*)(lds + PG8_SA(b, h) + aoff + m * 2048 + k * 1024); } while (0)
; #define PG8_WAIT_V(n) asm volatile("s_waitcnt vmcnt(" #n ")" ::: "memory")
; #define PG8_WAIT_L(n) asm volatile("s_waitcnt lgkmcnt(" #n ")" ::: "memory")
; #define PG8_BAR __builtin_amdgcn_s_barrier()
; #define PG8_SCHED __builtin_amdgcn_sched_barrier(0)
;     __device__ __forceinline__ float qscale(const Unit& u) const { return ((u.pn >= 8 && u.pn <= 11) || u.pn == 17) ? 0.5f : 1.0f; }
;     ...
;             PG8_LDA(At, 1, 1); PG8_STAGE(PG8_SB(1, 0), b3, voffB); PG8_STAGE(PG8_SB(1, 1), b3 + hstep, voffB); PG8_STAGE(PG8_SA(1, 0), a3, voffA);
;             PG8_WAIT_V(8); PG8_WAIT_L(0); PG8_BAR; PG8_MMA(1, 0, At, B0); PG8_MMA(1, 1, At, B1); PG8_BAR; PG8_SCHED;
;         }
;         if constexpr (QM == 2) { const float qs0_ = g.qs * E.qscale(cur), qs1_ = qs0_ * g.qs_b1; _Pragma("unroll") for (int a = 0; a < 2; ++a) _Pragma("unroll") for (int b = 0; b < 2; ++b) _Pragma("unroll") for (int m = 0; m < 4; ++m) _Pragma("unroll") for (int n = 0; n < 2; ++n) { const v4i t_ = __builtin_bit_cast(v4i, acc[a][b][m][n]); acc[a][b][m][n] = (f32x4){(float)t_[0], (float)t_[1], (float)t_[2], (float)t_[3]} * (b == 0 ? qs0_ : qs1_); } }
;         if constexpr (QM == 1) asm volatile("s_nop 15\n\ts_nop 15\n\ts_nop 15" ::: "memory");
;         if (wr == 0) PG8_BAR;
	s_mov_b32 m0, s83
	v_lshl_add_u64 v[220:221], v[220:221], 0, s[14:15]
	ds_read_b128 v[188:191], v161 offset:49152
	ds_read_b128 v[192:195], v161 offset:50176
	ds_read_b128 v[196:199], v161 offset:51200
	ds_read_b128 v[200:203], v161 offset:52224
	ds_read_b128 v[204:207], v161 offset:53248
	ds_read_b128 v[208:211], v161 offset:54272
	ds_read_b128 v[212:215], v161 offset:55296
	ds_read_b128 v[216:219], v161 offset:56320
	global_load_lds_dwordx4 v[220:221], off
	v_lshl_add_u64 v[220:221], v[222:223], 0, s[14:15]
	s_mov_b32 m0, s82
	s_nop 0
	global_load_lds_dwordx4 v[220:221], off
	v_lshl_add_u64 v[220:221], s[46:47], 0, v[130:131]
	s_mov_b32 m0, s91
	s_nop 0
	global_load_lds_dwordx4 v[220:221], off
	v_lshl_add_u64 v[220:221], s[46:47], 0, v[134:135]
	s_mov_b32 m0, s90
	s_nop 0
	global_load_lds_dwordx4 v[220:221], off
	v_lshl_add_u64 v[220:221], v[224:225], 0, s[14:15]
	s_mov_b32 m0, s72
	s_nop 0
	global_load_lds_dwordx4 v[220:221], off
	v_lshl_add_u64 v[220:221], v[226:227], 0, s[14:15]
	s_mov_b32 m0, s73
	s_nop 0
	global_load_lds_dwordx4 v[220:221], off
	s_waitcnt vmcnt(8)
	s_waitcnt lgkmcnt(0)
	s_setprio 1
	s_waitcnt lgkmcnt(0)
	v_mfma_i32_16x16x64_i8 v[60:63], v[152:155], v[188:191], v[60:63]
	v_mfma_i32_16x16x64_i8 v[56:59], v[164:167], v[188:191], v[56:59]
	v_mfma_i32_16x16x64_i8 v[44:47], v[152:155], v[196:199], v[44:47]
	v_mfma_i32_16x16x64_i8 v[40:43], v[164:167], v[196:199], v[40:43]
	v_mfma_i32_16x16x64_i8 v[28:31], v[152:155], v[204:207], v[28:31]
	v_mfma_i32_16x16x64_i8 v[24:27], v[164:167], v[204:207], v[24:27]
	v_mfma_i32_16x16x64_i8 v[12:15], v[152:155], v[212:215], v[12:15]
	v_mfma_i32_16x16x64_i8 v[8:11], v[164:167], v[212:215], v[8:11]
	s_barrier
	v_mfma_i32_16x16x64_i8 v[60:63], v[156:159], v[192:195], v[60:63]
	v_mfma_i32_16x16x64_i8 v[56:59], v[168:171], v[192:195], v[56:59]
	v_mfma_i32_16x16x64_i8 v[44:47], v[156:159], v[200:203], v[44:47]
	v_mfma_i32_16x16x64_i8 v[40:43], v[168:171], v[200:203], v[40:43]
	v_mfma_i32_16x16x64_i8 v[28:31], v[156:159], v[208:211], v[28:31]
	v_mfma_i32_16x16x64_i8 v[24:27], v[168:171], v[208:211], v[24:27]
	v_mfma_i32_16x16x64_i8 v[12:15], v[156:159], v[216:219], v[12:15]
	v_mfma_i32_16x16x64_i8 v[8:11], v[168:171], v[216:219], v[8:11]
	s_setprio 0
	s_setprio 1
	v_mfma_i32_16x16x64_i8 v[52:55], v[172:175], v[188:191], v[52:55]
	v_mfma_i32_16x16x64_i8 v[48:51], v[180:183], v[188:191], v[48:51]
	v_mfma_i32_16x16x64_i8 v[36:39], v[172:175], v[196:199], v[36:39]
	v_mfma_i32_16x16x64_i8 v[32:35], v[180:183], v[196:199], v[32:35]
	v_mfma_i32_16x16x64_i8 v[20:23], v[172:175], v[204:207], v[20:23]
	v_mfma_i32_16x16x64_i8 v[16:19], v[180:183], v[204:207], v[16:19]
	v_mfma_i32_16x16x64_i8 v[4:7], v[172:175], v[212:215], v[4:7]
	v_mfma_i32_16x16x64_i8 v[0:3], v[180:183], v[212:215], v[0:3]
	v_mfma_i32_16x16x64_i8 v[52:55], v[176:179], v[192:195], v[52:55]
	v_mfma_i32_16x16x64_i8 v[48:51], v[184:187], v[192:195], v[48:51]
	v_mfma_i32_16x16x64_i8 v[36:39], v[176:179], v[200:203], v[36:39]
	v_mfma_i32_16x16x64_i8 v[32:35], v[184:187], v[200:203], v[32:35]
	v_mfma_i32_16x16x64_i8 v[20:23], v[176:179], v[208:211], v[20:23]
	v_mfma_i32_16x16x64_i8 v[16:19], v[184:187], v[208:211], v[16:19]
	v_mfma_i32_16x16x64_i8 v[4:7], v[176:179], v[216:219], v[4:7]
	v_mfma_i32_16x16x64_i8 v[0:3], v[184:187], v[216:219], v[0:3]
	s_setprio 0
	s_barrier
	s_movk_i32 s48, 0x100
	s_andn2_b64 vcc, exec, s[44:45]
	s_mov_b64 s[46:47], -1
	s_mov_b64 s[44:45], 0
	s_cbranch_vccz .LBB0_4054
	s_and_b64 vcc, exec, s[16:17]
	s_cbranch_vccz .LBB0_4057
	s_barrier

; #define PG8_STAGE(bufoff, gbase, voff) do { _Pragma("unroll") for (int _i = 0; _i < 2; ++_i) \
;         __builtin_amdgcn_global_load_lds((const unsigned*)((const char*)(gbase) + (voff)[_i]), (LAS unsigned*)(lds + (bufoff) + ldsw + _i * 8192), 16, 0, 0); } while (0)
; #define PG8_LDA(dst, b, h) do { _Pragma("unroll") for (int m = 0; m < 4; ++m) _Pragma("unroll") for (int k = 0; k < 2; ++k) dst[m][k] = *(const LAS bf16x8*)(lds + PG8_SA(b, h) + aoff + m * 2048 + k * 1024); } while (0)
; #define PG8_LDB(dst, b, h) do { _Pragma("unroll") for (int n = 0; n < 2; ++n) _Pragma("unroll") for (int k = 0; k < 2; ++k) dst[n][k] = *(const LAS bf16x8*)(lds + PG8_SB(b, h) + boff + n * 2048 + k * 1024); } while (0)
; #define PG8_WAIT_V(n) asm volatile("s_waitcnt vmcnt(" #n ")" ::: "memory")
; #define PG8_WAIT_L(n) asm volatile("s_waitcnt lgkmcnt(" #n ")" ::: "memory")
; #define PG8_BAR __builtin_amdgcn_s_barrier()
; #define PG8_SCHED __builtin_amdgcn_sched_barrier(0)
;     ...
;         for (int t = 0; t < nt; t += 2) {
;             const bool last = (t == nt - 2);
;             const char* a1 = cA + (size_t)(t + 1) * kstep;
;             const char* a2 = last ? nA : cA + (size_t)(t + 2) * kstep; const char* b2 = last ? nB : cB + (size_t)(t + 2) * kstep;
;             const char* a3 = a2 + kstep; const char* b3 = b2 + kstep;
;             PG8_LDB(B0, 0, 0); PG8_LDB(B1, 0, 1); PG8_SCHED; PG8_LDA(At, 0, 0); PG8_STAGE(PG8_SA(1, 1), a1 + hstep, voffA);
;             PG8_WAIT_V(8); PG8_WAIT_L(0); PG8_BAR; PG8_MMA(0, 0, At, B0); PG8_MMA(0, 1, At, B1); PG8_BAR; PG8_SCHED;
;             PG8_LDA(At, 0, 1); PG8_STAGE(PG8_SB(0, 0), b2, voffB); PG8_STAGE(PG8_SB(0, 1), b2 + hstep, voffB); PG8_STAGE(PG8_SA(0, 0), a2, voffA);
;             PG8_WAIT_V(8); PG8_WAIT_L(0); PG8_BAR; PG8_MMA(1, 0, At, B0); PG8_MMA(1, 1, At, B1); PG8_BAR; PG8_SCHED;
.LBB0_4112:
	ds_read_b128 v[24:27], v106
	ds_read_b128 v[28:31], v106 offset:1024
	ds_read_b128 v[32:35], v106 offset:2048
	ds_read_b128 v[36:39], v106 offset:3072
	s_add_u32 s38, s36, 0xfffc0080
	s_addc_u32 s39, s37, -1
	s_cmp_eq_u32 s65, 12
	s_cselect_b32 s41, s3, s39
	s_cselect_b32 s40, s27, s38
	s_cselect_b32 s39, s25, s64
	s_cselect_b32 s38, s62, s63
	v_lshl_add_u64 v[102:103], s[36:37], 0, v[98:99]
	s_add_i32 m0, s42, 0xc000
	ds_read_b128 v[110:113], v107
	ds_read_b128 v[114:117], v107 offset:1024
	ds_read_b128 v[118:121], v107 offset:2048
	ds_read_b128 v[122:125], v107 offset:3072
	ds_read_b128 v[126:129], v107 offset:4096
	ds_read_b128 v[130:133], v107 offset:5120
	ds_read_b128 v[134:137], v107 offset:6144
	ds_read_b128 v[138:141], v107 offset:7168
	global_load_lds_dwordx4 v[102:103], off
	v_lshl_add_u64 v[102:103], s[36:37], 0, v[100:101]
	s_add_i32 m0, s42, 0xe000
	s_nop 0
	global_load_lds_dwordx4 v[102:103], off
	s_waitcnt vmcnt(8)
	s_waitcnt lgkmcnt(0)
	s_setprio 1
	s_waitcnt lgkmcnt(0)
	v_mfma_i32_16x16x64_i8 v[76:79], v[24:27], v[110:113], v[76:79]
	v_mfma_i32_16x16x64_i8 v[72:75], v[32:35], v[110:113], v[72:75]
	v_mfma_i32_16x16x64_i8 v[68:71], v[24:27], v[118:121], v[68:71]
	v_mfma_i32_16x16x64_i8 v[64:67], v[32:35], v[118:121], v[64:67]
	s_barrier
	v_mfma_i32_16x16x64_i8 v[60:63], v[24:27], v[126:129], v[60:63]
	v_mfma_i32_16x16x64_i8 v[56:59], v[32:35], v[126:129], v[56:59]
	v_mfma_i32_16x16x64_i8 v[52:55], v[24:27], v[134:137], v[52:55]
	v_mfma_i32_16x16x64_i8 v[48:51], v[32:35], v[134:137], v[48:51]
	v_mfma_i32_16x16x64_i8 v[76:79], v[28:31], v[114:117], v[76:79]
	v_mfma_i32_16x16x64_i8 v[72:75], v[36:39], v[114:117], v[72:75]
	v_mfma_i32_16x16x64_i8 v[68:71], v[28:31], v[122:125], v[68:71]
	v_mfma_i32_16x16x64_i8 v[64:67], v[36:39], v[122:125], v[64:67]
	v_mfma_i32_16x16x64_i8 v[60:63], v[28:31], v[130:133], v[60:63]
	v_mfma_i32_16x16x64_i8 v[56:59], v[36:39], v[130:133], v[56:59]
	v_mfma_i32_16x16x64_i8 v[52:55], v[28:31], v[138:141], v[52:55]
	v_mfma_i32_16x16x64_i8 v[48:51], v[36:39], v[138:141], v[48:51]
	s_setprio 0
	s_setprio 1
	s_setprio 0
	s_barrier
	s_add_i32 s66, s59, s35
	v_lshl_add_u64 v[102:103], s[38:39], 0, v[82:83]
	s_mov_b32 m0, s66
	ds_read_b128 v[110:113], v107 offset:16384
	ds_read_b128 v[114:117], v107 offset:17408
	ds_read_b128 v[118:121], v107 offset:18432
	ds_read_b128 v[122:125], v107 offset:19456
	ds_read_b128 v[126:129], v107 offset:20480
	ds_read_b128 v[130:133], v107 offset:21504
	ds_read_b128 v[134:137], v107 offset:22528
	ds_read_b128 v[138:141], v107 offset:23552
	global_load_lds_dwordx4 v[102:103], off
	s_add_i32 m0, s66, 0x2000
	s_add_u32 s66, s38, 0x40000
	v_lshl_add_u64 v[142:143], s[38:39], 0, v[86:87]
	s_addc_u32 s67, s39, 0
	global_load_lds_dwordx4 v[142:143], off
	v_lshl_add_u64 v[144:145], s[66:67], 0, v[82:83]
	s_mov_b32 m0, s43
	v_lshl_add_u64 v[146:147], s[40:41], 0, v[84:85]
	global_load_lds_dwordx4 v[144:145], off
	v_lshl_add_u64 v[144:145], s[66:67], 0, v[86:87]
	s_mov_b32 m0, s44
	s_nop 0
	global_load_lds_dwordx4 v[144:145], off
	v_lshl_add_u64 v[144:145], s[40:41], 0, v[80:81]
	s_mov_b32 m0, s42
	s_nop 0
	global_load_lds_dwordx4 v[144:145], off
	s_mov_b32 m0, s45
	s_nop 0
	global_load_lds_dwordx4 v[146:147], off
	s_waitcnt vmcnt(8)
	s_waitcnt lgkmcnt(0)
	s_setprio 1
	s_waitcnt lgkmcnt(0)
	v_mfma_i32_16x16x64_i8 v[44:47], v[24:27], v[110:113], v[44:47]
	v_mfma_i32_16x16x64_i8 v[40:43], v[32:35], v[110:113], v[40:43]
	v_mfma_i32_16x16x64_i8 v[20:23], v[24:27], v[118:121], v[20:23]
	v_mfma_i32_16x16x64_i8 v[16:19], v[32:35], v[118:121], v[16:19]
	s_barrier
	v_mfma_i32_16x16x64_i8 v[12:15], v[24:27], v[126:129], v[12:15]
	v_mfma_i32_16x16x64_i8 v[8:11], v[32:35], v[126:129], v[8:11]
	v_mfma_i32_16x16x64_i8 v[4:7], v[24:27], v[134:137], v[4:7]
	v_mfma_i32_16x16x64_i8 v[0:3], v[32:35], v[134:137], v[0:3]
	v_mfma_i32_16x16x64_i8 v[44:47], v[28:31], v[114:117], v[44:47]
	v_mfma_i32_16x16x64_i8 v[40:43], v[36:39], v[114:117], v[40:43]
	v_mfma_i32_16x16x64_i8 v[20:23], v[28:31], v[122:125], v[20:23]
	v_mfma_i32_16x16x64_i8 v[16:19], v[36:39], v[122:125], v[16:19]
	v_mfma_i32_16x16x64_i8 v[12:15], v[28:31], v[130:133], v[12:15]
	v_mfma_i32_16x16x64_i8 v[8:11], v[36:39], v[130:133], v[8:11]
	v_mfma_i32_16x16x64_i8 v[4:7], v[28:31], v[138:141], v[4:7]
	v_mfma_i32_16x16x64_i8 v[0:3], v[36:39], v[138:141], v[0:3]
	s_setprio 0
	s_setprio 1
	s_setprio 0
	s_barrier
; #define PG8_STAGE(bufoff, gbase, voff) do { _Pragma("unroll") for (int _i = 0; _i < 2; ++_i) \
;         __builtin_amdgcn_global_load_lds((const unsigned*)((const char*)(gbase) + (voff)[_i]), (LAS unsigned*)(lds + (bufoff) + ldsw + _i * 8192), 16, 0, 0); } while (0)
; #define PG8_LDA(dst, b, h) do { _Pragma("unroll") for (int m = 0; m < 4; ++m) _Pragma("unroll") for (int k = 0; k < 2; ++k) dst[m][k] = *(const LAS bf16x8*)(lds + PG8_SA(b, h) + aoff + m * 2048 + k * 1024); } while (0)
; #define PG8_LDB(dst, b, h) do { _Pragma("unroll") for (int n = 0; n < 2; ++n) _Pragma("unroll") for (int k = 0; k < 2; ++k) dst[n][k] = *(const LAS bf16x8*)(lds + PG8_SB(b, h) + boff + n * 2048 + k * 1024); } while (0)
; #define PG8_WAIT_V(n) asm volatile("s_waitcnt vmcnt(" #n ")" ::: "memory")
; #define PG8_WAIT_L(n) asm volatile("s_waitcnt lgkmcnt(" #n ")" ::: "memory")
; #define PG8_BAR __builtin_amdgcn_s_barrier()
; #define PG8_SCHED __builtin_amdgcn_sched_barrier(0)
;     __device__ __forceinline__ float qscale(const Unit& u) const { return ((u.pn >= 8 && u.pn <= 11) || u.pn == 17) ? 0.5f : 1.0f; }
;     ...
;             PG8_LDB(B0, 1, 0); PG8_LDB(B1, 1, 1); PG8_SCHED; PG8_LDA(At, 1, 0); PG8_STAGE(PG8_SA(0, 1), a2 + hstep, voffA);
;             PG8_WAIT_V(8); PG8_WAIT_L(0); PG8_BAR; PG8_MMA(0, 0, At, B0); PG8_MMA(0, 1, At, B1); PG8_BAR; PG8_SCHED;
;             PG8_LDA(At, 1, 1); PG8_STAGE(PG8_SB(1, 0), b3, voffB); PG8_STAGE(PG8_SB(1, 1), b3 + hstep, voffB); PG8_STAGE(PG8_SA(1, 0), a3, voffA);
;             PG8_WAIT_V(8); PG8_WAIT_L(0); PG8_BAR; PG8_MMA(1, 0, At, B0); PG8_MMA(1, 1, At, B1); PG8_BAR; PG8_SCHED;
;         }
;         if constexpr (QM == 2) { const float qs0_ = g.qs * E.qscale(cur), qs1_ = qs0_ * g.qs_b1; _Pragma("unroll") for (int a = 0; a < 2; ++a) _Pragma("unroll") for (int b = 0; b < 2; ++b) _Pragma("unroll") for (int m = 0; m < 4; ++m) _Pragma("unroll") for (int n = 0; n < 2; ++n) { const v4i t_ = __builtin_bit_cast(v4i, acc[a][b][m][n]); acc[a][b][m][n] = (f32x4){(float)t_[0], (float)t_[1], (float)t_[2], (float)t_[3]} * (b == 0 ? qs0_ : qs1_); } }
;         if constexpr (QM == 1) asm volatile("s_nop 15\n\ts_nop 15\n\ts_nop 15" ::: "memory");
;         if (wr == 0) PG8_BAR;
	s_add_i32 s66, 0, 0x18000
	v_add_u32_e32 v36, s66, v105
	ds_read_b128 v[24:27], v36
	ds_read_b128 v[28:31], v36 offset:1024
	ds_read_b128 v[32:35], v36 offset:2048
	ds_read_b128 v[36:39], v36 offset:3072
	s_add_u32 s40, s40, 0x40000
	s_addc_u32 s41, s41, 0
	s_mov_b32 m0, s46
	v_lshl_add_u64 v[148:149], s[40:41], 0, v[80:81]
	ds_read_b128 v[110:113], v107 offset:32768
	ds_read_b128 v[114:117], v107 offset:33792
	ds_read_b128 v[118:121], v107 offset:34816
	ds_read_b128 v[122:125], v107 offset:35840
	ds_read_b128 v[126:129], v107 offset:36864
	ds_read_b128 v[130:133], v107 offset:37888
	ds_read_b128 v[134:137], v107 offset:38912
	ds_read_b128 v[138:141], v107 offset:39936
	global_load_lds_dwordx4 v[148:149], off
	v_lshl_add_u64 v[148:149], s[40:41], 0, v[84:85]
	s_mov_b32 m0, s47
	s_nop 0
	global_load_lds_dwordx4 v[148:149], off
	s_waitcnt vmcnt(8)
	s_waitcnt lgkmcnt(0)
	s_setprio 1
	s_waitcnt lgkmcnt(0)
	v_mfma_i32_16x16x64_i8 v[76:79], v[24:27], v[110:113], v[76:79]
	v_mfma_i32_16x16x64_i8 v[72:75], v[32:35], v[110:113], v[72:75]
	v_mfma_i32_16x16x64_i8 v[68:71], v[24:27], v[118:121], v[68:71]
	v_mfma_i32_16x16x64_i8 v[64:67], v[32:35], v[118:121], v[64:67]
	s_barrier
	v_mfma_i32_16x16x64_i8 v[60:63], v[24:27], v[126:129], v[60:63]
	v_mfma_i32_16x16x64_i8 v[56:59], v[32:35], v[126:129], v[56:59]
	v_mfma_i32_16x16x64_i8 v[52:55], v[24:27], v[134:137], v[52:55]
	v_mfma_i32_16x16x64_i8 v[48:51], v[32:35], v[134:137], v[48:51]
	v_mfma_i32_16x16x64_i8 v[76:79], v[28:31], v[114:117], v[76:79]
	v_mfma_i32_16x16x64_i8 v[72:75], v[36:39], v[114:117], v[72:75]
	v_mfma_i32_16x16x64_i8 v[68:71], v[28:31], v[122:125], v[68:71]
	v_mfma_i32_16x16x64_i8 v[64:67], v[36:39], v[122:125], v[64:67]
	v_mfma_i32_16x16x64_i8 v[60:63], v[28:31], v[130:133], v[60:63]
	v_mfma_i32_16x16x64_i8 v[56:59], v[36:39], v[130:133], v[56:59]
	v_mfma_i32_16x16x64_i8 v[52:55], v[28:31], v[138:141], v[52:55]
	v_mfma_i32_16x16x64_i8 v[48:51], v[36:39], v[138:141], v[48:51]
	s_setprio 0
	s_setprio 1
	s_setprio 0
	s_barrier
	s_add_i32 s40, s66, s35
	v_lshl_add_u64 v[102:103], v[102:103], 0, s[8:9]
	s_mov_b32 m0, s40
	ds_read_b128 v[110:113], v107 offset:49152
	ds_read_b128 v[114:117], v107 offset:50176
	ds_read_b128 v[118:121], v107 offset:51200
	ds_read_b128 v[122:125], v107 offset:52224
	ds_read_b128 v[126:129], v107 offset:53248
	ds_read_b128 v[130:133], v107 offset:54272
	ds_read_b128 v[134:137], v107 offset:55296
	ds_read_b128 v[138:141], v107 offset:56320
	global_load_lds_dwordx4 v[102:103], off
	s_add_i32 m0, s40, 0x2000
	s_add_u32 s38, s38, 0x40080
	v_lshl_add_u64 v[102:103], v[142:143], 0, s[8:9]
	s_addc_u32 s39, s39, 0
	global_load_lds_dwordx4 v[102:103], off
	v_lshl_add_u64 v[102:103], s[38:39], 0, v[82:83]
	s_mov_b32 m0, s51
	s_nop 0
	global_load_lds_dwordx4 v[102:103], off
	v_lshl_add_u64 v[102:103], s[38:39], 0, v[86:87]
	s_mov_b32 m0, s55
	s_nop 0
	global_load_lds_dwordx4 v[102:103], off
	v_lshl_add_u64 v[102:103], v[144:145], 0, s[8:9]
	s_mov_b32 m0, s49
	s_nop 0
	global_load_lds_dwordx4 v[102:103], off
	v_lshl_add_u64 v[102:103], v[146:147], 0, s[8:9]
	s_mov_b32 m0, s50
	s_nop 0
	global_load_lds_dwordx4 v[102:103], off
	s_waitcnt vmcnt(8)
	s_waitcnt lgkmcnt(0)
	s_setprio 1
	s_waitcnt lgkmcnt(0)
	v_mfma_i32_16x16x64_i8 v[44:47], v[24:27], v[110:113], v[44:47]
	v_mfma_i32_16x16x64_i8 v[40:43], v[32:35], v[110:113], v[40:43]
	v_mfma_i32_16x16x64_i8 v[20:23], v[24:27], v[118:121], v[20:23]
	v_mfma_i32_16x16x64_i8 v[16:19], v[32:35], v[118:121], v[16:19]
	s_barrier
	v_mfma_i32_16x16x64_i8 v[12:15], v[24:27], v[126:129], v[12:15]
	v_mfma_i32_16x16x64_i8 v[8:11], v[32:35], v[126:129], v[8:11]
	v_mfma_i32_16x16x64_i8 v[4:7], v[24:27], v[134:137], v[4:7]
	v_mfma_i32_16x16x64_i8 v[0:3], v[32:35], v[134:137], v[0:3]
	v_mfma_i32_16x16x64_i8 v[44:47], v[28:31], v[114:117], v[44:47]
	v_mfma_i32_16x16x64_i8 v[40:43], v[36:39], v[114:117], v[40:43]
	v_mfma_i32_16x16x64_i8 v[20:23], v[28:31], v[122:125], v[20:23]
	v_mfma_i32_16x16x64_i8 v[16:19], v[36:39], v[122:125], v[16:19]
	v_mfma_i32_16x16x64_i8 v[12:15], v[28:31], v[130:133], v[12:15]
	v_mfma_i32_16x16x64_i8 v[8:11], v[36:39], v[130:133], v[8:11]
	v_mfma_i32_16x16x64_i8 v[4:7], v[28:31], v[138:141], v[4:7]
	v_mfma_i32_16x16x64_i8 v[0:3], v[36:39], v[138:141], v[0:3]
	s_setprio 0
	s_setprio 1
	s_setprio 0
	s_barrier
	s_add_i32 s65, s65, 2
	s_add_u32 s36, s36, 0x100
	s_addc_u32 s37, s37, 0
	s_add_u32 s63, s63, 0x100
	s_addc_u32 s64, s64, 0
	s_cmp_gt_u32 s65, 13
	s_cbranch_scc0 .LBB0_4112
	s_and_b64 vcc, exec, s[10:11]
	s_cbranch_vccz .LBB0_4116
	s_barrier
	s_andn2_b64 vcc, exec, s[14:15]
	s_cbranch_vccz .LBB0_4117

; #define PG8_STAGE(bufoff, gbase, voff) do { _Pragma("unroll") for (int _i = 0; _i < 2; ++_i) \
;         __builtin_amdgcn_global_load_lds((const unsigned*)((const char*)(gbase) + (voff)[_i]), (LAS unsigned*)(lds + (bufoff) + ldsw + _i * 8192), 16, 0, 0); } while (0)
; #define PG8_LDA(dst, b, h) do { _Pragma("unroll") for (int m = 0; m < 4; ++m) _Pragma("unroll") for (int k = 0; k < 2; ++k) dst[m][k] = *(const LAS bf16x8*)(lds + PG8_SA(b, h) + aoff + m * 2048 + k * 1024); } while (0)
; #define PG8_LDB(dst, b, h) do { _Pragma("unroll") for (int n = 0; n < 2; ++n) _Pragma("unroll") for (int k = 0; k < 2; ++k) dst[n][k] = *(const LAS bf16x8*)(lds + PG8_SB(b, h) + boff + n * 2048 + k * 1024); } while (0)
; #define PG8_WAIT_V(n) asm volatile("s_waitcnt vmcnt(" #n ")" ::: "memory")
; #define PG8_WAIT_L(n) asm volatile("s_waitcnt lgkmcnt(" #n ")" ::: "memory")
; #define PG8_BAR __builtin_amdgcn_s_barrier()
; #define PG8_SCHED __builtin_amdgcn_sched_barrier(0)
;     ...
;         for (int t = 0; t < nt; t += 2) {
;             const bool last = (t == nt - 2);
;             const char* a1 = cA + (size_t)(t + 1) * kstep;
;             const char* a2 = last ? nA : cA + (size_t)(t + 2) * kstep; const char* b2 = last ? nB : cB + (size_t)(t + 2) * kstep;
;             const char* a3 = a2 + kstep; const char* b3 = b2 + kstep;
;             PG8_LDB(B0, 0, 0); PG8_LDB(B1, 0, 1); PG8_SCHED; PG8_LDA(At, 0, 0); PG8_STAGE(PG8_SA(1, 1), a1 + hstep, voffA);
;             PG8_WAIT_V(8); PG8_WAIT_L(0); PG8_BAR; PG8_MMA(0, 0, At, B0); PG8_MMA(0, 1, At, B1); PG8_BAR; PG8_SCHED;
;             PG8_LDA(At, 0, 1); PG8_STAGE(PG8_SB(0, 0), b2, voffB); PG8_STAGE(PG8_SB(0, 1), b2 + hstep, voffB); PG8_STAGE(PG8_SA(0, 0), a2, voffA);
;             PG8_WAIT_V(8); PG8_WAIT_L(0); PG8_BAR; PG8_MMA(1, 0, At, B0); PG8_MMA(1, 1, At, B1); PG8_BAR; PG8_SCHED;
.LBB0_4138:
	s_add_u32 s45, s38, s44
	s_addc_u32 s50, s39, 0
	s_add_u32 s48, s45, 0x100
	s_addc_u32 s49, s50, 0
	s_and_b64 s[46:47], s[42:43], exec
	s_cselect_b32 s47, s14, s49
	s_cselect_b32 s46, s27, s48
	s_add_u32 s44, s36, s44
	s_addc_u32 s48, s37, 0
	s_add_u32 s44, s44, 0x100
	s_addc_u32 s48, s48, 0
	s_and_b64 s[42:43], s[42:43], exec
	s_cselect_b32 s49, s25, s48
	s_cselect_b32 s48, s76, s44
	s_add_u32 s58, s45, 0x10080
	s_addc_u32 s59, s50, 0
	s_add_i32 s84, s71, s61
	s_add_i32 m0, s62, 0xc000
	s_add_i32 s87, s62, 0xe000
	s_add_i32 s81, s84, 0x2000
	v_add_u32_e32 v144, s71, v147
	s_add_u32 s50, s48, 0x10000
	ds_read_b128 v[154:157], v144
	ds_read_b128 v[158:161], v144 offset:1024
	ds_read_b128 v[162:165], v144 offset:2048
	ds_read_b128 v[166:169], v144 offset:3072
	v_add_u32_e32 v144, s72, v147
	s_addc_u32 s51, s49, 0
	s_add_i32 s83, s72, s61
	ds_read_b128 v[170:173], v144
	ds_read_b128 v[174:177], v144 offset:1024
	ds_read_b128 v[178:181], v144 offset:2048
	ds_read_b128 v[182:185], v144 offset:3072
	s_add_i32 s82, s83, 0x2000
	s_add_i32 s80, 0, 0x18000
	s_add_i32 s79, 0, 0x1c000
	s_add_u32 s44, s46, 0x10000
	s_addc_u32 s45, s47, 0
	s_add_i32 s78, s80, s61
	s_add_i32 s77, s78, 0x2000
	s_add_u32 s42, s48, 0x10080
	s_addc_u32 s43, s49, 0
	s_add_i32 s86, s79, s61
	s_add_i32 s85, s86, 0x2000
	v_lshl_add_u64 v[144:145], s[58:59], 0, v[128:129]
	ds_read_b128 v[186:189], v148
	ds_read_b128 v[190:193], v148 offset:1024
	ds_read_b128 v[194:197], v148 offset:2048
	ds_read_b128 v[198:201], v148 offset:3072
	ds_read_b128 v[202:205], v148 offset:4096
	ds_read_b128 v[206:209], v148 offset:5120
	ds_read_b128 v[210:213], v148 offset:6144
	ds_read_b128 v[214:217], v148 offset:7168
	global_load_lds_dwordx4 v[144:145], off
	v_lshl_add_u64 v[144:145], s[58:59], 0, v[132:133]
	s_mov_b32 m0, s87
	s_nop 0
	global_load_lds_dwordx4 v[144:145], off
	s_waitcnt vmcnt(8)
	s_waitcnt lgkmcnt(0)
	s_setprio 1
	s_waitcnt lgkmcnt(0)
	v_mfma_i32_16x16x64_i8 v[124:127], v[154:157], v[186:189], v[124:127]
	v_mfma_i32_16x16x64_i8 v[120:123], v[162:165], v[186:189], v[120:123]
	v_mfma_i32_16x16x64_i8 v[108:111], v[154:157], v[194:197], v[108:111]
	v_mfma_i32_16x16x64_i8 v[104:107], v[162:165], v[194:197], v[104:107]
	v_mfma_i32_16x16x64_i8 v[92:95], v[154:157], v[202:205], v[92:95]
	v_mfma_i32_16x16x64_i8 v[88:91], v[162:165], v[202:205], v[88:91]
	v_mfma_i32_16x16x64_i8 v[76:79], v[154:157], v[210:213], v[76:79]
	v_mfma_i32_16x16x64_i8 v[72:75], v[162:165], v[210:213], v[72:75]
	s_barrier
	v_mfma_i32_16x16x64_i8 v[124:127], v[158:161], v[190:193], v[124:127]
	v_mfma_i32_16x16x64_i8 v[120:123], v[166:169], v[190:193], v[120:123]
	v_mfma_i32_16x16x64_i8 v[108:111], v[158:161], v[198:201], v[108:111]
	v_mfma_i32_16x16x64_i8 v[104:107], v[166:169], v[198:201], v[104:107]
	v_mfma_i32_16x16x64_i8 v[92:95], v[158:161], v[206:209], v[92:95]
	v_mfma_i32_16x16x64_i8 v[88:91], v[166:169], v[206:209], v[88:91]
	v_mfma_i32_16x16x64_i8 v[76:79], v[158:161], v[214:217], v[76:79]
	v_mfma_i32_16x16x64_i8 v[72:75], v[166:169], v[214:217], v[72:75]
	s_setprio 0
	s_setprio 1
	v_mfma_i32_16x16x64_i8 v[116:119], v[170:173], v[186:189], v[116:119]
	v_mfma_i32_16x16x64_i8 v[112:115], v[178:181], v[186:189], v[112:115]
	v_mfma_i32_16x16x64_i8 v[100:103], v[170:173], v[194:197], v[100:103]
	v_mfma_i32_16x16x64_i8 v[96:99], v[178:181], v[194:197], v[96:99]
	v_mfma_i32_16x16x64_i8 v[84:87], v[170:173], v[202:205], v[84:87]
	v_mfma_i32_16x16x64_i8 v[80:83], v[178:181], v[202:205], v[80:83]
	v_mfma_i32_16x16x64_i8 v[68:71], v[170:173], v[210:213], v[68:71]
	v_mfma_i32_16x16x64_i8 v[64:67], v[178:181], v[210:213], v[64:67]
	v_mfma_i32_16x16x64_i8 v[116:119], v[174:177], v[190:193], v[116:119]
	v_mfma_i32_16x16x64_i8 v[112:115], v[182:185], v[190:193], v[112:115]
	v_mfma_i32_16x16x64_i8 v[100:103], v[174:177], v[198:201], v[100:103]
	v_mfma_i32_16x16x64_i8 v[96:99], v[182:185], v[198:201], v[96:99]
	v_mfma_i32_16x16x64_i8 v[84:87], v[174:177], v[206:209], v[84:87]
	v_mfma_i32_16x16x64_i8 v[80:83], v[182:185], v[206:209], v[80:83]
	v_mfma_i32_16x16x64_i8 v[68:71], v[174:177], v[214:217], v[68:71]
	v_mfma_i32_16x16x64_i8 v[64:67], v[182:185], v[214:217], v[64:67]
	s_setprio 0
	s_barrier
	s_mov_b32 m0, s84
	v_lshl_add_u64 v[144:145], s[48:49], 0, v[130:131]
	ds_read_b128 v[186:189], v148 offset:16384
	ds_read_b128 v[190:193], v148 offset:17408
	ds_read_b128 v[194:197], v148 offset:18432
	ds_read_b128 v[198:201], v148 offset:19456
	ds_read_b128 v[202:205], v148 offset:20480
	ds_read_b128 v[206:209], v148 offset:21504
	ds_read_b128 v[210:213], v148 offset:22528
	ds_read_b128 v[214:217], v148 offset:23552
	global_load_lds_dwordx4 v[144:145], off
	v_lshl_add_u64 v[218:219], s[48:49], 0, v[134:135]
	s_mov_b32 m0, s81
	v_lshl_add_u64 v[220:221], s[50:51], 0, v[130:131]
	global_load_lds_dwordx4 v[218:219], off
	s_mov_b32 m0, s83
	v_lshl_add_u64 v[222:223], s[46:47], 0, v[132:133]
	global_load_lds_dwordx4 v[220:221], off
	v_lshl_add_u64 v[220:221], s[50:51], 0, v[134:135]
	s_mov_b32 m0, s82
	s_nop 0
	global_load_lds_dwordx4 v[220:221], off
	v_lshl_add_u64 v[220:221], s[46:47], 0, v[128:129]
	s_mov_b32 m0, s62
	s_nop 0
	global_load_lds_dwordx4 v[220:221], off
	s_mov_b32 m0, s63
	s_nop 0
	global_load_lds_dwordx4 v[222:223], off
	s_waitcnt vmcnt(8)
	s_waitcnt lgkmcnt(0)
	s_setprio 1
	s_waitcnt lgkmcnt(0)
	v_mfma_i32_16x16x64_i8 v[60:63], v[154:157], v[186:189], v[60:63]
	v_mfma_i32_16x16x64_i8 v[56:59], v[162:165], v[186:189], v[56:59]
	v_mfma_i32_16x16x64_i8 v[44:47], v[154:157], v[194:197], v[44:47]
	v_mfma_i32_16x16x64_i8 v[40:43], v[162:165], v[194:197], v[40:43]
	v_mfma_i32_16x16x64_i8 v[28:31], v[154:157], v[202:205], v[28:31]
	v_mfma_i32_16x16x64_i8 v[24:27], v[162:165], v[202:205], v[24:27]
	v_mfma_i32_16x16x64_i8 v[12:15], v[154:157], v[210:213], v[12:15]
	v_mfma_i32_16x16x64_i8 v[8:11], v[162:165], v[210:213], v[8:11]
	s_barrier
; #define PG8_STAGE(bufoff, gbase, voff) do { _Pragma("unroll") for (int _i = 0; _i < 2; ++_i) \
;         __builtin_amdgcn_global_load_lds((const unsigned*)((const char*)(gbase) + (voff)[_i]), (LAS unsigned*)(lds + (bufoff) + ldsw + _i * 8192), 16, 0, 0); } while (0)
; #define PG8_LDA(dst, b, h) do { _Pragma("unroll") for (int m = 0; m < 4; ++m) _Pragma("unroll") for (int k = 0; k < 2; ++k) dst[m][k] = *(const LAS bf16x8*)(lds + PG8_SA(b, h) + aoff + m * 2048 + k * 1024); } while (0)
; #define PG8_LDB(dst, b, h) do { _Pragma("unroll") for (int n = 0; n < 2; ++n) _Pragma("unroll") for (int k = 0; k < 2; ++k) dst[n][k] = *(const LAS bf16x8*)(lds + PG8_SB(b, h) + boff + n * 2048 + k * 1024); } while (0)
; #define PG8_WAIT_V(n) asm volatile("s_waitcnt vmcnt(" #n ")" ::: "memory")
; #define PG8_WAIT_L(n) asm volatile("s_waitcnt lgkmcnt(" #n ")" ::: "memory")
; #define PG8_BAR __builtin_amdgcn_s_barrier()
; #define PG8_SCHED __builtin_amdgcn_sched_barrier(0)
;     ...
;             PG8_WAIT_V(8); PG8_WAIT_L(0); PG8_BAR; PG8_MMA(1, 0, At, B0); PG8_MMA(1, 1, At, B1); PG8_BAR; PG8_SCHED;
;             PG8_LDB(B0, 1, 0); PG8_LDB(B1, 1, 1); PG8_SCHED; PG8_LDA(At, 1, 0); PG8_STAGE(PG8_SA(0, 1), a2 + hstep, voffA);
;             PG8_WAIT_V(8); PG8_WAIT_L(0); PG8_BAR; PG8_MMA(0, 0, At, B0); PG8_MMA(0, 1, At, B1); PG8_BAR; PG8_SCHED;
	v_mfma_i32_16x16x64_i8 v[60:63], v[158:161], v[190:193], v[60:63]
	v_mfma_i32_16x16x64_i8 v[56:59], v[166:169], v[190:193], v[56:59]
	v_mfma_i32_16x16x64_i8 v[44:47], v[158:161], v[198:201], v[44:47]
	v_mfma_i32_16x16x64_i8 v[40:43], v[166:169], v[198:201], v[40:43]
	v_mfma_i32_16x16x64_i8 v[28:31], v[158:161], v[206:209], v[28:31]
	v_mfma_i32_16x16x64_i8 v[24:27], v[166:169], v[206:209], v[24:27]
	v_mfma_i32_16x16x64_i8 v[12:15], v[158:161], v[214:217], v[12:15]
	v_mfma_i32_16x16x64_i8 v[8:11], v[166:169], v[214:217], v[8:11]
	s_setprio 0
	s_setprio 1
	v_mfma_i32_16x16x64_i8 v[52:55], v[170:173], v[186:189], v[52:55]
	v_mfma_i32_16x16x64_i8 v[48:51], v[178:181], v[186:189], v[48:51]
	v_mfma_i32_16x16x64_i8 v[36:39], v[170:173], v[194:197], v[36:39]
	v_mfma_i32_16x16x64_i8 v[32:35], v[178:181], v[194:197], v[32:35]
	v_mfma_i32_16x16x64_i8 v[20:23], v[170:173], v[202:205], v[20:23]
	v_mfma_i32_16x16x64_i8 v[16:19], v[178:181], v[202:205], v[16:19]
	v_mfma_i32_16x16x64_i8 v[4:7], v[170:173], v[210:213], v[4:7]
	v_mfma_i32_16x16x64_i8 v[0:3], v[178:181], v[210:213], v[0:3]
	v_mfma_i32_16x16x64_i8 v[52:55], v[174:177], v[190:193], v[52:55]
	v_mfma_i32_16x16x64_i8 v[48:51], v[182:185], v[190:193], v[48:51]
	v_mfma_i32_16x16x64_i8 v[36:39], v[174:177], v[198:201], v[36:39]
	v_mfma_i32_16x16x64_i8 v[32:35], v[182:185], v[198:201], v[32:35]
	v_mfma_i32_16x16x64_i8 v[20:23], v[174:177], v[206:209], v[20:23]
	v_mfma_i32_16x16x64_i8 v[16:19], v[182:185], v[206:209], v[16:19]
	v_mfma_i32_16x16x64_i8 v[4:7], v[174:177], v[214:217], v[4:7]
	v_mfma_i32_16x16x64_i8 v[0:3], v[182:185], v[214:217], v[0:3]
	s_setprio 0
	s_barrier
	v_add_u32_e32 v166, s80, v147
	v_add_u32_e32 v182, s79, v147
	ds_read_b128 v[154:157], v166
	ds_read_b128 v[158:161], v166 offset:1024
	ds_read_b128 v[162:165], v166 offset:2048
	ds_read_b128 v[166:169], v166 offset:3072
	ds_read_b128 v[170:173], v182
	ds_read_b128 v[174:177], v182 offset:1024
	ds_read_b128 v[178:181], v182 offset:2048
	ds_read_b128 v[182:185], v182 offset:3072
	s_mov_b32 m0, s64
	v_lshl_add_u64 v[224:225], s[44:45], 0, v[128:129]
	ds_read_b128 v[186:189], v148 offset:32768
	ds_read_b128 v[190:193], v148 offset:33792
	ds_read_b128 v[194:197], v148 offset:34816
	ds_read_b128 v[198:201], v148 offset:35840
	ds_read_b128 v[202:205], v148 offset:36864
	ds_read_b128 v[206:209], v148 offset:37888
	ds_read_b128 v[210:213], v148 offset:38912
	ds_read_b128 v[214:217], v148 offset:39936
	global_load_lds_dwordx4 v[224:225], off
	v_lshl_add_u64 v[224:225], s[44:45], 0, v[132:133]
	s_mov_b32 m0, s65
	s_nop 0
	global_load_lds_dwordx4 v[224:225], off
	s_waitcnt vmcnt(8)
	s_waitcnt lgkmcnt(0)
	s_setprio 1
	s_waitcnt lgkmcnt(0)
	v_mfma_i32_16x16x64_i8 v[124:127], v[154:157], v[186:189], v[124:127]
	v_mfma_i32_16x16x64_i8 v[120:123], v[162:165], v[186:189], v[120:123]
	v_mfma_i32_16x16x64_i8 v[108:111], v[154:157], v[194:197], v[108:111]
	v_mfma_i32_16x16x64_i8 v[104:107], v[162:165], v[194:197], v[104:107]
	v_mfma_i32_16x16x64_i8 v[92:95], v[154:157], v[202:205], v[92:95]
	v_mfma_i32_16x16x64_i8 v[88:91], v[162:165], v[202:205], v[88:91]
	v_mfma_i32_16x16x64_i8 v[76:79], v[154:157], v[210:213], v[76:79]
	v_mfma_i32_16x16x64_i8 v[72:75], v[162:165], v[210:213], v[72:75]
	s_barrier
	v_mfma_i32_16x16x64_i8 v[124:127], v[158:161], v[190:193], v[124:127]
	v_mfma_i32_16x16x64_i8 v[120:123], v[166:169], v[190:193], v[120:123]
	v_mfma_i32_16x16x64_i8 v[108:111], v[158:161], v[198:201], v[108:111]
	v_mfma_i32_16x16x64_i8 v[104:107], v[166:169], v[198:201], v[104:107]
	v_mfma_i32_16x16x64_i8 v[92:95], v[158:161], v[206:209], v[92:95]
	v_mfma_i32_16x16x64_i8 v[88:91], v[166:169], v[206:209], v[88:91]
	v_mfma_i32_16x16x64_i8 v[76:79], v[158:161], v[214:217], v[76:79]
	v_mfma_i32_16x16x64_i8 v[72:75], v[166:169], v[214:217], v[72:75]
	s_setprio 0
	s_setprio 1
	v_mfma_i32_16x16x64_i8 v[116:119], v[170:173], v[186:189], v[116:119]
	v_mfma_i32_16x16x64_i8 v[112:115], v[178:181], v[186:189], v[112:115]
	v_mfma_i32_16x16x64_i8 v[100:103], v[170:173], v[194:197], v[100:103]
	v_mfma_i32_16x16x64_i8 v[96:99], v[178:181], v[194:197], v[96:99]
	v_mfma_i32_16x16x64_i8 v[84:87], v[170:173], v[202:205], v[84:87]
	v_mfma_i32_16x16x64_i8 v[80:83], v[178:181], v[202:205], v[80:83]
	v_mfma_i32_16x16x64_i8 v[68:71], v[170:173], v[210:213], v[68:71]
	v_mfma_i32_16x16x64_i8 v[64:67], v[178:181], v[210:213], v[64:67]
	v_mfma_i32_16x16x64_i8 v[116:119], v[174:177], v[190:193], v[116:119]
	v_mfma_i32_16x16x64_i8 v[112:115], v[182:185], v[190:193], v[112:115]
	v_mfma_i32_16x16x64_i8 v[100:103], v[174:177], v[198:201], v[100:103]
	v_mfma_i32_16x16x64_i8 v[96:99], v[182:185], v[198:201], v[96:99]
	v_mfma_i32_16x16x64_i8 v[84:87], v[174:177], v[206:209], v[84:87]
	v_mfma_i32_16x16x64_i8 v[80:83], v[182:185], v[206:209], v[80:83]
	v_mfma_i32_16x16x64_i8 v[68:71], v[174:177], v[214:217], v[68:71]
	v_mfma_i32_16x16x64_i8 v[64:67], v[182:185], v[214:217], v[64:67]
	s_setprio 0
	s_barrier
; #define PG8_STAGE(bufoff, gbase, voff) do { _Pragma("unroll") for (int _i = 0; _i < 2; ++_i) \
;         __builtin_amdgcn_global_load_lds((const unsigned*)((const char*)(gbase) + (voff)[_i]), (LAS unsigned*)(lds + (bufoff) + ldsw + _i * 8192), 16, 0, 0); } while (0)
; #define PG8_LDA(dst, b, h) do { _Pragma("unroll") for (int m = 0; m < 4; ++m) _Pragma("unroll") for (int k = 0; k < 2; ++k) dst[m][k] = *(const LAS bf16x8*)(lds + PG8_SA(b, h) + aoff + m * 2048 + k * 1024); } while (0)
; #define PG8_WAIT_V(n) asm volatile("s_waitcnt vmcnt(" #n ")" ::: "memory")
; #define PG8_WAIT_L(n) asm volatile("s_waitcnt lgkmcnt(" #n ")" ::: "memory")
; #define PG8_BAR __builtin_amdgcn_s_barrier()
; #define PG8_SCHED __builtin_amdgcn_sched_barrier(0)
;     __device__ __forceinline__ float qscale(const Unit& u) const { return ((u.pn >= 8 && u.pn <= 11) || u.pn == 17) ? 0.5f : 1.0f; }
;     ...
;             PG8_LDA(At, 1, 1); PG8_STAGE(PG8_SB(1, 0), b3, voffB); PG8_STAGE(PG8_SB(1, 1), b3 + hstep, voffB); PG8_STAGE(PG8_SA(1, 0), a3, voffA);
;             PG8_WAIT_V(8); PG8_WAIT_L(0); PG8_BAR; PG8_MMA(1, 0, At, B0); PG8_MMA(1, 1, At, B1); PG8_BAR; PG8_SCHED;
;         }
;         if constexpr (QM == 2) { const float qs0_ = g.qs * E.qscale(cur), qs1_ = qs0_ * g.qs_b1; _Pragma("unroll") for (int a = 0; a < 2; ++a) _Pragma("unroll") for (int b = 0; b < 2; ++b) _Pragma("unroll") for (int m = 0; m < 4; ++m) _Pragma("unroll") for (int n = 0; n < 2; ++n) { const v4i t_ = __builtin_bit_cast(v4i, acc[a][b][m][n]); acc[a][b][m][n] = (f32x4){(float)t_[0], (float)t_[1], (float)t_[2], (float)t_[3]} * (b == 0 ? qs0_ : qs1_); } }
;         if constexpr (QM == 1) asm volatile("s_nop 15\n\ts_nop 15\n\ts_nop 15" ::: "memory");
;         if (wr == 0) PG8_BAR;
	s_mov_b32 m0, s78
	v_lshl_add_u64 v[144:145], v[144:145], 0, s[18:19]
	ds_read_b128 v[186:189], v148 offset:49152
	ds_read_b128 v[190:193], v148 offset:50176
	ds_read_b128 v[194:197], v148 offset:51200
	ds_read_b128 v[198:201], v148 offset:52224
	ds_read_b128 v[202:205], v148 offset:53248
	ds_read_b128 v[206:209], v148 offset:54272
	ds_read_b128 v[210:213], v148 offset:55296
	ds_read_b128 v[214:217], v148 offset:56320
	global_load_lds_dwordx4 v[144:145], off
	v_lshl_add_u64 v[144:145], v[218:219], 0, s[18:19]
	s_mov_b32 m0, s77
	s_nop 0
	global_load_lds_dwordx4 v[144:145], off
	v_lshl_add_u64 v[144:145], s[42:43], 0, v[130:131]
	s_mov_b32 m0, s86
	s_nop 0
	global_load_lds_dwordx4 v[144:145], off
	v_lshl_add_u64 v[144:145], s[42:43], 0, v[134:135]
	s_mov_b32 m0, s85
	s_nop 0
	global_load_lds_dwordx4 v[144:145], off
	v_lshl_add_u64 v[144:145], v[220:221], 0, s[18:19]
	s_mov_b32 m0, s68
	s_nop 0
	global_load_lds_dwordx4 v[144:145], off
	v_lshl_add_u64 v[144:145], v[222:223], 0, s[18:19]
	s_mov_b32 m0, s69
	s_nop 0
	global_load_lds_dwordx4 v[144:145], off
	s_waitcnt vmcnt(8)
	s_waitcnt lgkmcnt(0)
	s_setprio 1
	s_waitcnt lgkmcnt(0)
	v_mfma_i32_16x16x64_i8 v[60:63], v[154:157], v[186:189], v[60:63]
	v_mfma_i32_16x16x64_i8 v[56:59], v[162:165], v[186:189], v[56:59]
	v_mfma_i32_16x16x64_i8 v[44:47], v[154:157], v[194:197], v[44:47]
	v_mfma_i32_16x16x64_i8 v[40:43], v[162:165], v[194:197], v[40:43]
	v_mfma_i32_16x16x64_i8 v[28:31], v[154:157], v[202:205], v[28:31]
	v_mfma_i32_16x16x64_i8 v[24:27], v[162:165], v[202:205], v[24:27]
	v_mfma_i32_16x16x64_i8 v[12:15], v[154:157], v[210:213], v[12:15]
	v_mfma_i32_16x16x64_i8 v[8:11], v[162:165], v[210:213], v[8:11]
	s_barrier
	v_mfma_i32_16x16x64_i8 v[60:63], v[158:161], v[190:193], v[60:63]
	v_mfma_i32_16x16x64_i8 v[56:59], v[166:169], v[190:193], v[56:59]
	v_mfma_i32_16x16x64_i8 v[44:47], v[158:161], v[198:201], v[44:47]
	v_mfma_i32_16x16x64_i8 v[40:43], v[166:169], v[198:201], v[40:43]
	v_mfma_i32_16x16x64_i8 v[28:31], v[158:161], v[206:209], v[28:31]
	v_mfma_i32_16x16x64_i8 v[24:27], v[166:169], v[206:209], v[24:27]
	v_mfma_i32_16x16x64_i8 v[12:15], v[158:161], v[214:217], v[12:15]
	v_mfma_i32_16x16x64_i8 v[8:11], v[166:169], v[214:217], v[8:11]
	s_setprio 0
	s_setprio 1
	v_mfma_i32_16x16x64_i8 v[52:55], v[170:173], v[186:189], v[52:55]
	v_mfma_i32_16x16x64_i8 v[48:51], v[178:181], v[186:189], v[48:51]
	v_mfma_i32_16x16x64_i8 v[36:39], v[170:173], v[194:197], v[36:39]
	v_mfma_i32_16x16x64_i8 v[32:35], v[178:181], v[194:197], v[32:35]
	v_mfma_i32_16x16x64_i8 v[20:23], v[170:173], v[202:205], v[20:23]
	v_mfma_i32_16x16x64_i8 v[16:19], v[178:181], v[202:205], v[16:19]
	v_mfma_i32_16x16x64_i8 v[4:7], v[170:173], v[210:213], v[4:7]
	v_mfma_i32_16x16x64_i8 v[0:3], v[178:181], v[210:213], v[0:3]
	v_mfma_i32_16x16x64_i8 v[52:55], v[174:177], v[190:193], v[52:55]
	v_mfma_i32_16x16x64_i8 v[48:51], v[182:185], v[190:193], v[48:51]
	v_mfma_i32_16x16x64_i8 v[36:39], v[174:177], v[198:201], v[36:39]
	v_mfma_i32_16x16x64_i8 v[32:35], v[182:185], v[198:201], v[32:35]
	v_mfma_i32_16x16x64_i8 v[20:23], v[174:177], v[206:209], v[20:23]
	v_mfma_i32_16x16x64_i8 v[16:19], v[182:185], v[206:209], v[16:19]
	v_mfma_i32_16x16x64_i8 v[4:7], v[174:177], v[214:217], v[4:7]
	v_mfma_i32_16x16x64_i8 v[0:3], v[182:185], v[214:217], v[0:3]
	s_setprio 0
	s_barrier
	s_movk_i32 s44, 0x100
	s_andn2_b64 vcc, exec, s[40:41]
	s_mov_b64 s[42:43], -1
	s_mov_b64 s[40:41], 0
	s_cbranch_vccz .LBB0_4138
	s_and_b64 vcc, exec, s[20:21]
	s_cbranch_vccz .LBB0_4141
	s_barrier

; #define PG8_STAGE(bufoff, gbase, voff) do { _Pragma("unroll") for (int _i = 0; _i < 2; ++_i) \
;         __builtin_amdgcn_global_load_lds((const unsigned*)((const char*)(gbase) + (voff)[_i]), (LAS unsigned*)(lds + (bufoff) + ldsw + _i * 8192), 16, 0, 0); } while (0)
; #define PG8_LDA(dst, b, h) do { _Pragma("unroll") for (int m = 0; m < 4; ++m) _Pragma("unroll") for (int k = 0; k < 2; ++k) dst[m][k] = *(const LAS bf16x8*)(lds + PG8_SA(b, h) + aoff + m * 2048 + k * 1024); } while (0)
; #define PG8_LDB(dst, b, h) do { _Pragma("unroll") for (int n = 0; n < 2; ++n) _Pragma("unroll") for (int k = 0; k < 2; ++k) dst[n][k] = *(const LAS bf16x8*)(lds + PG8_SB(b, h) + boff + n * 2048 + k * 1024); } while (0)
; #define PG8_WAIT_V(n) asm volatile("s_waitcnt vmcnt(" #n ")" ::: "memory")
; #define PG8_WAIT_L(n) asm volatile("s_waitcnt lgkmcnt(" #n ")" ::: "memory")
; #define PG8_BAR __builtin_amdgcn_s_barrier()
; #define PG8_SCHED __builtin_amdgcn_sched_barrier(0)
;     ...
;         for (int t = 0; t < nt; t += 2) {
;             const bool last = (t == nt - 2);
;             const char* a1 = cA + (size_t)(t + 1) * kstep;
;             const char* a2 = last ? nA : cA + (size_t)(t + 2) * kstep; const char* b2 = last ? nB : cB + (size_t)(t + 2) * kstep;
;             const char* a3 = a2 + kstep; const char* b3 = b2 + kstep;
;             PG8_LDB(B0, 0, 0); PG8_LDB(B1, 0, 1); PG8_SCHED; PG8_LDA(At, 0, 0); PG8_STAGE(PG8_SA(1, 1), a1 + hstep, voffA);
;             PG8_WAIT_V(8); PG8_WAIT_L(0); PG8_BAR; PG8_MMA(0, 0, At, B0); PG8_MMA(0, 1, At, B1); PG8_BAR; PG8_SCHED;
;             PG8_LDA(At, 0, 1); PG8_STAGE(PG8_SB(0, 0), b2, voffB); PG8_STAGE(PG8_SB(0, 1), b2 + hstep, voffB); PG8_STAGE(PG8_SA(0, 0), a2, voffA);
;             PG8_WAIT_V(8); PG8_WAIT_L(0); PG8_BAR; PG8_MMA(1, 0, At, B0); PG8_MMA(1, 1, At, B1); PG8_BAR; PG8_SCHED;
.LBB0_4162:
	s_add_u32 s43, s38, s42
	s_addc_u32 s48, s39, 0
	s_add_u32 s46, s43, 0x100
	s_addc_u32 s47, s48, 0
	s_and_b64 s[44:45], s[40:41], exec
	s_cselect_b32 s45, s27, s47
	s_cselect_b32 s44, s70, s46
	s_add_u32 s42, s36, s42
	s_addc_u32 s46, s37, 0
	s_add_u32 s42, s42, 0x100
	s_addc_u32 s46, s46, 0
	s_and_b64 s[40:41], s[40:41], exec
	s_cselect_b32 s47, s25, s46
	s_cselect_b32 s46, s71, s42
	s_add_u32 s50, s43, 0x10080
	s_addc_u32 s51, s48, 0
	s_add_i32 s79, s66, s55
	s_add_i32 m0, s58, 0xc000
	s_add_i32 s82, s58, 0xe000
	s_add_i32 s76, s79, 0x2000
	v_add_u32_e32 v142, s66, v144
	s_add_u32 s48, s46, 0x10000
	ds_read_b128 v[152:155], v142
	ds_read_b128 v[156:159], v142 offset:1024
	ds_read_b128 v[160:163], v142 offset:2048
	ds_read_b128 v[164:167], v142 offset:3072
	v_add_u32_e32 v142, s67, v144
	s_addc_u32 s49, s47, 0
	s_add_i32 s78, s67, s55
	ds_read_b128 v[168:171], v142
	ds_read_b128 v[172:175], v142 offset:1024
	ds_read_b128 v[176:179], v142 offset:2048
	ds_read_b128 v[180:183], v142 offset:3072
	s_add_i32 s77, s78, 0x2000
	s_add_i32 s75, 0, 0x18000
	s_add_i32 s74, 0, 0x1c000
	s_add_u32 s42, s44, 0x10000
	s_addc_u32 s43, s45, 0
	s_add_i32 s73, s75, s55
	s_add_i32 s72, s73, 0x2000
	s_add_u32 s40, s46, 0x10080
	s_addc_u32 s41, s47, 0
	s_add_i32 s81, s74, s55
	s_add_i32 s80, s81, 0x2000
	v_lshl_add_u64 v[142:143], s[50:51], 0, v[128:129]
	ds_read_b128 v[184:187], v147
	ds_read_b128 v[188:191], v147 offset:1024
	ds_read_b128 v[192:195], v147 offset:2048
	ds_read_b128 v[196:199], v147 offset:3072
	ds_read_b128 v[200:203], v147 offset:4096
	ds_read_b128 v[204:207], v147 offset:5120
	ds_read_b128 v[208:211], v147 offset:6144
	ds_read_b128 v[212:215], v147 offset:7168
	global_load_lds_dwordx4 v[142:143], off
	v_lshl_add_u64 v[142:143], s[50:51], 0, v[132:133]
	s_mov_b32 m0, s82
	s_nop 0
	global_load_lds_dwordx4 v[142:143], off
	s_waitcnt vmcnt(8)
	s_waitcnt lgkmcnt(0)
	s_setprio 1
	s_waitcnt lgkmcnt(0)
	v_mfma_i32_16x16x64_i8 v[124:127], v[184:187], v[152:155], v[124:127]
	v_mfma_i32_16x16x64_i8 v[120:123], v[184:187], v[160:163], v[120:123]
	v_mfma_i32_16x16x64_i8 v[108:111], v[192:195], v[152:155], v[108:111]
	v_mfma_i32_16x16x64_i8 v[104:107], v[192:195], v[160:163], v[104:107]
	v_mfma_i32_16x16x64_i8 v[92:95], v[200:203], v[152:155], v[92:95]
	v_mfma_i32_16x16x64_i8 v[88:91], v[200:203], v[160:163], v[88:91]
	v_mfma_i32_16x16x64_i8 v[76:79], v[208:211], v[152:155], v[76:79]
	v_mfma_i32_16x16x64_i8 v[72:75], v[208:211], v[160:163], v[72:75]
	s_barrier
	v_mfma_i32_16x16x64_i8 v[124:127], v[188:191], v[156:159], v[124:127]
	v_mfma_i32_16x16x64_i8 v[120:123], v[188:191], v[164:167], v[120:123]
	v_mfma_i32_16x16x64_i8 v[108:111], v[196:199], v[156:159], v[108:111]
	v_mfma_i32_16x16x64_i8 v[104:107], v[196:199], v[164:167], v[104:107]
	v_mfma_i32_16x16x64_i8 v[92:95], v[204:207], v[156:159], v[92:95]
	v_mfma_i32_16x16x64_i8 v[88:91], v[204:207], v[164:167], v[88:91]
	v_mfma_i32_16x16x64_i8 v[76:79], v[212:215], v[156:159], v[76:79]
	v_mfma_i32_16x16x64_i8 v[72:75], v[212:215], v[164:167], v[72:75]
	s_setprio 0
	s_setprio 1
	v_mfma_i32_16x16x64_i8 v[116:119], v[184:187], v[168:171], v[116:119]
	v_mfma_i32_16x16x64_i8 v[112:115], v[184:187], v[176:179], v[112:115]
	v_mfma_i32_16x16x64_i8 v[100:103], v[192:195], v[168:171], v[100:103]
	v_mfma_i32_16x16x64_i8 v[96:99], v[192:195], v[176:179], v[96:99]
	v_mfma_i32_16x16x64_i8 v[84:87], v[200:203], v[168:171], v[84:87]
	v_mfma_i32_16x16x64_i8 v[80:83], v[200:203], v[176:179], v[80:83]
	v_mfma_i32_16x16x64_i8 v[68:71], v[208:211], v[168:171], v[68:71]
	v_mfma_i32_16x16x64_i8 v[64:67], v[208:211], v[176:179], v[64:67]
	v_mfma_i32_16x16x64_i8 v[116:119], v[188:191], v[172:175], v[116:119]
	v_mfma_i32_16x16x64_i8 v[112:115], v[188:191], v[180:183], v[112:115]
	v_mfma_i32_16x16x64_i8 v[100:103], v[196:199], v[172:175], v[100:103]
	v_mfma_i32_16x16x64_i8 v[96:99], v[196:199], v[180:183], v[96:99]
	v_mfma_i32_16x16x64_i8 v[84:87], v[204:207], v[172:175], v[84:87]
	v_mfma_i32_16x16x64_i8 v[80:83], v[204:207], v[180:183], v[80:83]
	v_mfma_i32_16x16x64_i8 v[68:71], v[212:215], v[172:175], v[68:71]
	v_mfma_i32_16x16x64_i8 v[64:67], v[212:215], v[180:183], v[64:67]
	s_setprio 0
	s_barrier
	s_mov_b32 m0, s79
	v_lshl_add_u64 v[142:143], s[46:47], 0, v[130:131]
	ds_read_b128 v[184:187], v147 offset:16384
	ds_read_b128 v[188:191], v147 offset:17408
	ds_read_b128 v[192:195], v147 offset:18432
	ds_read_b128 v[196:199], v147 offset:19456
	ds_read_b128 v[200:203], v147 offset:20480
	ds_read_b128 v[204:207], v147 offset:21504
	ds_read_b128 v[208:211], v147 offset:22528
	ds_read_b128 v[212:215], v147 offset:23552
	global_load_lds_dwordx4 v[142:143], off
	v_lshl_add_u64 v[216:217], s[46:47], 0, v[134:135]
	s_mov_b32 m0, s76
	v_lshl_add_u64 v[218:219], s[48:49], 0, v[130:131]
	global_load_lds_dwordx4 v[216:217], off
	s_mov_b32 m0, s78
	v_lshl_add_u64 v[220:221], s[44:45], 0, v[132:133]
	global_load_lds_dwordx4 v[218:219], off
	v_lshl_add_u64 v[218:219], s[48:49], 0, v[134:135]
	s_mov_b32 m0, s77
	s_nop 0
	global_load_lds_dwordx4 v[218:219], off
	v_lshl_add_u64 v[218:219], s[44:45], 0, v[128:129]
	s_mov_b32 m0, s58
	s_nop 0
	global_load_lds_dwordx4 v[218:219], off
	s_mov_b32 m0, s59
	s_nop 0
	global_load_lds_dwordx4 v[220:221], off
	s_waitcnt vmcnt(8)
	s_waitcnt lgkmcnt(0)
	s_setprio 1
	s_waitcnt lgkmcnt(0)
	v_mfma_i32_16x16x64_i8 v[60:63], v[184:187], v[152:155], v[60:63]
	v_mfma_i32_16x16x64_i8 v[56:59], v[184:187], v[160:163], v[56:59]
	v_mfma_i32_16x16x64_i8 v[44:47], v[192:195], v[152:155], v[44:47]
	v_mfma_i32_16x16x64_i8 v[40:43], v[192:195], v[160:163], v[40:43]
	v_mfma_i32_16x16x64_i8 v[28:31], v[200:203], v[152:155], v[28:31]
	v_mfma_i32_16x16x64_i8 v[24:27], v[200:203], v[160:163], v[24:27]
	v_mfma_i32_16x16x64_i8 v[12:15], v[208:211], v[152:155], v[12:15]
	v_mfma_i32_16x16x64_i8 v[8:11], v[208:211], v[160:163], v[8:11]
	s_barrier
; #define PG8_STAGE(bufoff, gbase, voff) do { _Pragma("unroll") for (int _i = 0; _i < 2; ++_i) \
;         __builtin_amdgcn_global_load_lds((const unsigned*)((const char*)(gbase) + (voff)[_i]), (LAS unsigned*)(lds + (bufoff) + ldsw + _i * 8192), 16, 0, 0); } while (0)
; #define PG8_LDA(dst, b, h) do { _Pragma("unroll") for (int m = 0; m < 4; ++m) _Pragma("unroll") for (int k = 0; k < 2; ++k) dst[m][k] = *(const LAS bf16x8*)(lds + PG8_SA(b, h) + aoff + m * 2048 + k * 1024); } while (0)
; #define PG8_LDB(dst, b, h) do { _Pragma("unroll") for (int n = 0; n < 2; ++n) _Pragma("unroll") for (int k = 0; k < 2; ++k) dst[n][k] = *(const LAS bf16x8*)(lds + PG8_SB(b, h) + boff + n * 2048 + k * 1024); } while (0)
; #define PG8_WAIT_V(n) asm volatile("s_waitcnt vmcnt(" #n ")" ::: "memory")
; #define PG8_WAIT_L(n) asm volatile("s_waitcnt lgkmcnt(" #n ")" ::: "memory")
; #define PG8_BAR __builtin_amdgcn_s_barrier()
; #define PG8_SCHED __builtin_amdgcn_sched_barrier(0)
;     ...
;             PG8_WAIT_V(8); PG8_WAIT_L(0); PG8_BAR; PG8_MMA(1, 0, At, B0); PG8_MMA(1, 1, At, B1); PG8_BAR; PG8_SCHED;
;             PG8_LDB(B0, 1, 0); PG8_LDB(B1, 1, 1); PG8_SCHED; PG8_LDA(At, 1, 0); PG8_STAGE(PG8_SA(0, 1), a2 + hstep, voffA);
;             PG8_WAIT_V(8); PG8_WAIT_L(0); PG8_BAR; PG8_MMA(0, 0, At, B0); PG8_MMA(0, 1, At, B1); PG8_BAR; PG8_SCHED;
	v_mfma_i32_16x16x64_i8 v[60:63], v[188:191], v[156:159], v[60:63]
	v_mfma_i32_16x16x64_i8 v[56:59], v[188:191], v[164:167], v[56:59]
	v_mfma_i32_16x16x64_i8 v[44:47], v[196:199], v[156:159], v[44:47]
	v_mfma_i32_16x16x64_i8 v[40:43], v[196:199], v[164:167], v[40:43]
	v_mfma_i32_16x16x64_i8 v[28:31], v[204:207], v[156:159], v[28:31]
	v_mfma_i32_16x16x64_i8 v[24:27], v[204:207], v[164:167], v[24:27]
	v_mfma_i32_16x16x64_i8 v[12:15], v[212:215], v[156:159], v[12:15]
	v_mfma_i32_16x16x64_i8 v[8:11], v[212:215], v[164:167], v[8:11]
	s_setprio 0
	s_setprio 1
	v_mfma_i32_16x16x64_i8 v[52:55], v[184:187], v[168:171], v[52:55]
	v_mfma_i32_16x16x64_i8 v[48:51], v[184:187], v[176:179], v[48:51]
	v_mfma_i32_16x16x64_i8 v[36:39], v[192:195], v[168:171], v[36:39]
	v_mfma_i32_16x16x64_i8 v[32:35], v[192:195], v[176:179], v[32:35]
	v_mfma_i32_16x16x64_i8 v[20:23], v[200:203], v[168:171], v[20:23]
	v_mfma_i32_16x16x64_i8 v[16:19], v[200:203], v[176:179], v[16:19]
	v_mfma_i32_16x16x64_i8 v[4:7], v[208:211], v[168:171], v[4:7]
	v_mfma_i32_16x16x64_i8 v[0:3], v[208:211], v[176:179], v[0:3]
	v_mfma_i32_16x16x64_i8 v[52:55], v[188:191], v[172:175], v[52:55]
	v_mfma_i32_16x16x64_i8 v[48:51], v[188:191], v[180:183], v[48:51]
	v_mfma_i32_16x16x64_i8 v[36:39], v[196:199], v[172:175], v[36:39]
	v_mfma_i32_16x16x64_i8 v[32:35], v[196:199], v[180:183], v[32:35]
	v_mfma_i32_16x16x64_i8 v[20:23], v[204:207], v[172:175], v[20:23]
	v_mfma_i32_16x16x64_i8 v[16:19], v[204:207], v[180:183], v[16:19]
	v_mfma_i32_16x16x64_i8 v[4:7], v[212:215], v[172:175], v[4:7]
	v_mfma_i32_16x16x64_i8 v[0:3], v[212:215], v[180:183], v[0:3]
	s_setprio 0
	s_barrier
	v_add_u32_e32 v151, s75, v144
	ds_read_b128 v[152:155], v151
	ds_read_b128 v[156:159], v151 offset:1024
	ds_read_b128 v[160:163], v151 offset:2048
	ds_read_b128 v[164:167], v151 offset:3072
	v_add_u32_e32 v151, s74, v144
	ds_read_b128 v[168:171], v151
	ds_read_b128 v[172:175], v151 offset:1024
	ds_read_b128 v[176:179], v151 offset:2048
	ds_read_b128 v[180:183], v151 offset:3072
	s_mov_b32 m0, s60
	v_lshl_add_u64 v[222:223], s[42:43], 0, v[128:129]
	ds_read_b128 v[184:187], v147 offset:32768
	ds_read_b128 v[188:191], v147 offset:33792
	ds_read_b128 v[192:195], v147 offset:34816
	ds_read_b128 v[196:199], v147 offset:35840
	ds_read_b128 v[200:203], v147 offset:36864
	ds_read_b128 v[204:207], v147 offset:37888
	ds_read_b128 v[208:211], v147 offset:38912
	ds_read_b128 v[212:215], v147 offset:39936
	global_load_lds_dwordx4 v[222:223], off
	v_lshl_add_u64 v[222:223], s[42:43], 0, v[132:133]
	s_mov_b32 m0, s61
	s_nop 0
	global_load_lds_dwordx4 v[222:223], off
	s_waitcnt vmcnt(8)
	s_waitcnt lgkmcnt(0)
	s_setprio 1
	s_waitcnt lgkmcnt(0)
	v_mfma_i32_16x16x64_i8 v[124:127], v[184:187], v[152:155], v[124:127]
	v_mfma_i32_16x16x64_i8 v[120:123], v[184:187], v[160:163], v[120:123]
	v_mfma_i32_16x16x64_i8 v[108:111], v[192:195], v[152:155], v[108:111]
	v_mfma_i32_16x16x64_i8 v[104:107], v[192:195], v[160:163], v[104:107]
	v_mfma_i32_16x16x64_i8 v[92:95], v[200:203], v[152:155], v[92:95]
	v_mfma_i32_16x16x64_i8 v[88:91], v[200:203], v[160:163], v[88:91]
	v_mfma_i32_16x16x64_i8 v[76:79], v[208:211], v[152:155], v[76:79]
	v_mfma_i32_16x16x64_i8 v[72:75], v[208:211], v[160:163], v[72:75]
	s_barrier
	v_mfma_i32_16x16x64_i8 v[124:127], v[188:191], v[156:159], v[124:127]
	v_mfma_i32_16x16x64_i8 v[120:123], v[188:191], v[164:167], v[120:123]
	v_mfma_i32_16x16x64_i8 v[108:111], v[196:199], v[156:159], v[108:111]
	v_mfma_i32_16x16x64_i8 v[104:107], v[196:199], v[164:167], v[104:107]
	v_mfma_i32_16x16x64_i8 v[92:95], v[204:207], v[156:159], v[92:95]
	v_mfma_i32_16x16x64_i8 v[88:91], v[204:207], v[164:167], v[88:91]
	v_mfma_i32_16x16x64_i8 v[76:79], v[212:215], v[156:159], v[76:79]
	v_mfma_i32_16x16x64_i8 v[72:75], v[212:215], v[164:167], v[72:75]
	s_setprio 0
	s_setprio 1
	v_mfma_i32_16x16x64_i8 v[116:119], v[184:187], v[168:171], v[116:119]
	v_mfma_i32_16x16x64_i8 v[112:115], v[184:187], v[176:179], v[112:115]
	v_mfma_i32_16x16x64_i8 v[100:103], v[192:195], v[168:171], v[100:103]
	v_mfma_i32_16x16x64_i8 v[96:99], v[192:195], v[176:179], v[96:99]
	v_mfma_i32_16x16x64_i8 v[84:87], v[200:203], v[168:171], v[84:87]
	v_mfma_i32_16x16x64_i8 v[80:83], v[200:203], v[176:179], v[80:83]
	v_mfma_i32_16x16x64_i8 v[68:71], v[208:211], v[168:171], v[68:71]
	v_mfma_i32_16x16x64_i8 v[64:67], v[208:211], v[176:179], v[64:67]
	v_mfma_i32_16x16x64_i8 v[116:119], v[188:191], v[172:175], v[116:119]
	v_mfma_i32_16x16x64_i8 v[112:115], v[188:191], v[180:183], v[112:115]
	v_mfma_i32_16x16x64_i8 v[100:103], v[196:199], v[172:175], v[100:103]
	v_mfma_i32_16x16x64_i8 v[96:99], v[196:199], v[180:183], v[96:99]
	v_mfma_i32_16x16x64_i8 v[84:87], v[204:207], v[172:175], v[84:87]
	v_mfma_i32_16x16x64_i8 v[80:83], v[204:207], v[180:183], v[80:83]
	v_mfma_i32_16x16x64_i8 v[68:71], v[212:215], v[172:175], v[68:71]
	v_mfma_i32_16x16x64_i8 v[64:67], v[212:215], v[180:183], v[64:67]
	s_setprio 0
	s_barrier
; #define PG8_STAGE(bufoff, gbase, voff) do { _Pragma("unroll") for (int _i = 0; _i < 2; ++_i) \
;         __builtin_amdgcn_global_load_lds((const unsigned*)((const char*)(gbase) + (voff)[_i]), (LAS unsigned*)(lds + (bufoff) + ldsw + _i * 8192), 16, 0, 0); } while (0)
; #define PG8_LDA(dst, b, h) do { _Pragma("unroll") for (int m = 0; m < 4; ++m) _Pragma("unroll") for (int k = 0; k < 2; ++k) dst[m][k] = *(const LAS bf16x8*)(lds + PG8_SA(b, h) + aoff + m * 2048 + k * 1024); } while (0)
; #define PG8_WAIT_V(n) asm volatile("s_waitcnt vmcnt(" #n ")" ::: "memory")
; #define PG8_WAIT_L(n) asm volatile("s_waitcnt lgkmcnt(" #n ")" ::: "memory")
; #define PG8_BAR __builtin_amdgcn_s_barrier()
; #define PG8_SCHED __builtin_amdgcn_sched_barrier(0)
;     __device__ __forceinline__ float qscale(const Unit& u) const { return ((u.pn >= 8 && u.pn <= 11) || u.pn == 17) ? 0.5f : 1.0f; }
;     ...
;             PG8_LDA(At, 1, 1); PG8_STAGE(PG8_SB(1, 0), b3, voffB); PG8_STAGE(PG8_SB(1, 1), b3 + hstep, voffB); PG8_STAGE(PG8_SA(1, 0), a3, voffA);
;             PG8_WAIT_V(8); PG8_WAIT_L(0); PG8_BAR; PG8_MMA(1, 0, At, B0); PG8_MMA(1, 1, At, B1); PG8_BAR; PG8_SCHED;
;         }
;         if constexpr (QM == 2) { const float qs0_ = g.qs * E.qscale(cur), qs1_ = qs0_ * g.qs_b1; _Pragma("unroll") for (int a = 0; a < 2; ++a) _Pragma("unroll") for (int b = 0; b < 2; ++b) _Pragma("unroll") for (int m = 0; m < 4; ++m) _Pragma("unroll") for (int n = 0; n < 2; ++n) { const v4i t_ = __builtin_bit_cast(v4i, acc[a][b][m][n]); acc[a][b][m][n] = (f32x4){(float)t_[0], (float)t_[1], (float)t_[2], (float)t_[3]} * (b == 0 ? qs0_ : qs1_); } }
;         if constexpr (QM == 1) asm volatile("s_nop 15\n\ts_nop 15\n\ts_nop 15" ::: "memory");
;         if (wr == 0) PG8_BAR;
	s_mov_b32 m0, s73
	v_lshl_add_u64 v[142:143], v[142:143], 0, s[14:15]
	ds_read_b128 v[184:187], v147 offset:49152
	ds_read_b128 v[188:191], v147 offset:50176
	ds_read_b128 v[192:195], v147 offset:51200
	ds_read_b128 v[196:199], v147 offset:52224
	ds_read_b128 v[200:203], v147 offset:53248
	ds_read_b128 v[204:207], v147 offset:54272
	ds_read_b128 v[208:211], v147 offset:55296
	ds_read_b128 v[212:215], v147 offset:56320
	global_load_lds_dwordx4 v[142:143], off
	v_lshl_add_u64 v[142:143], v[216:217], 0, s[14:15]
	s_mov_b32 m0, s72
	s_nop 0
	global_load_lds_dwordx4 v[142:143], off
	v_lshl_add_u64 v[142:143], s[40:41], 0, v[130:131]
	s_mov_b32 m0, s81
	s_nop 0
	global_load_lds_dwordx4 v[142:143], off
	v_lshl_add_u64 v[142:143], s[40:41], 0, v[134:135]
	s_mov_b32 m0, s80
	s_nop 0
	global_load_lds_dwordx4 v[142:143], off
	v_lshl_add_u64 v[142:143], v[218:219], 0, s[14:15]
	s_mov_b32 m0, s64
	s_nop 0
	global_load_lds_dwordx4 v[142:143], off
	v_lshl_add_u64 v[142:143], v[220:221], 0, s[14:15]
	s_mov_b32 m0, s65
	s_nop 0
	global_load_lds_dwordx4 v[142:143], off
	s_waitcnt vmcnt(8)
	s_waitcnt lgkmcnt(0)
	s_setprio 1
	s_waitcnt lgkmcnt(0)
	v_mfma_i32_16x16x64_i8 v[60:63], v[184:187], v[152:155], v[60:63]
	v_mfma_i32_16x16x64_i8 v[56:59], v[184:187], v[160:163], v[56:59]
	v_mfma_i32_16x16x64_i8 v[44:47], v[192:195], v[152:155], v[44:47]
	v_mfma_i32_16x16x64_i8 v[40:43], v[192:195], v[160:163], v[40:43]
	v_mfma_i32_16x16x64_i8 v[28:31], v[200:203], v[152:155], v[28:31]
	v_mfma_i32_16x16x64_i8 v[24:27], v[200:203], v[160:163], v[24:27]
	v_mfma_i32_16x16x64_i8 v[12:15], v[208:211], v[152:155], v[12:15]
	v_mfma_i32_16x16x64_i8 v[8:11], v[208:211], v[160:163], v[8:11]
	s_barrier
	v_mfma_i32_16x16x64_i8 v[60:63], v[188:191], v[156:159], v[60:63]
	v_mfma_i32_16x16x64_i8 v[56:59], v[188:191], v[164:167], v[56:59]
	v_mfma_i32_16x16x64_i8 v[44:47], v[196:199], v[156:159], v[44:47]
	v_mfma_i32_16x16x64_i8 v[40:43], v[196:199], v[164:167], v[40:43]
	v_mfma_i32_16x16x64_i8 v[28:31], v[204:207], v[156:159], v[28:31]
	v_mfma_i32_16x16x64_i8 v[24:27], v[204:207], v[164:167], v[24:27]
	v_mfma_i32_16x16x64_i8 v[12:15], v[212:215], v[156:159], v[12:15]
	v_mfma_i32_16x16x64_i8 v[8:11], v[212:215], v[164:167], v[8:11]
	s_setprio 0
	s_setprio 1
	v_mfma_i32_16x16x64_i8 v[52:55], v[184:187], v[168:171], v[52:55]
	v_mfma_i32_16x16x64_i8 v[48:51], v[184:187], v[176:179], v[48:51]
	v_mfma_i32_16x16x64_i8 v[36:39], v[192:195], v[168:171], v[36:39]
	v_mfma_i32_16x16x64_i8 v[32:35], v[192:195], v[176:179], v[32:35]
	v_mfma_i32_16x16x64_i8 v[20:23], v[200:203], v[168:171], v[20:23]
	v_mfma_i32_16x16x64_i8 v[16:19], v[200:203], v[176:179], v[16:19]
	v_mfma_i32_16x16x64_i8 v[4:7], v[208:211], v[168:171], v[4:7]
	v_mfma_i32_16x16x64_i8 v[0:3], v[208:211], v[176:179], v[0:3]
	v_mfma_i32_16x16x64_i8 v[52:55], v[188:191], v[172:175], v[52:55]
	v_mfma_i32_16x16x64_i8 v[48:51], v[188:191], v[180:183], v[48:51]
	v_mfma_i32_16x16x64_i8 v[36:39], v[196:199], v[172:175], v[36:39]
	v_mfma_i32_16x16x64_i8 v[32:35], v[196:199], v[180:183], v[32:35]
	v_mfma_i32_16x16x64_i8 v[20:23], v[204:207], v[172:175], v[20:23]
	v_mfma_i32_16x16x64_i8 v[16:19], v[204:207], v[180:183], v[16:19]
	v_mfma_i32_16x16x64_i8 v[4:7], v[212:215], v[172:175], v[4:7]
	v_mfma_i32_16x16x64_i8 v[0:3], v[212:215], v[180:183], v[0:3]
	s_setprio 0
	s_barrier
	s_movk_i32 s42, 0x100
	s_andn2_b64 vcc, exec, s[6:7]
	s_mov_b64 s[40:41], -1
	s_mov_b64 s[6:7], 0
	s_cbranch_vccz .LBB0_4162
	s_and_b64 vcc, exec, s[16:17]
	s_cbranch_vccz .LBB0_4165
	s_barrier

; #define PG8_STAGE(bufoff, gbase, voff) do { _Pragma("unroll") for (int _i = 0; _i < 2; ++_i) \
;         __builtin_amdgcn_global_load_lds((const unsigned*)((const char*)(gbase) + (voff)[_i]), (LAS unsigned*)(lds + (bufoff) + ldsw + _i * 8192), 16, 0, 0); } while (0)
; #define PG8_LDA(dst, b, h) do { _Pragma("unroll") for (int m = 0; m < 4; ++m) _Pragma("unroll") for (int k = 0; k < 2; ++k) dst[m][k] = *(const LAS bf16x8*)(lds + PG8_SA(b, h) + aoff + m * 2048 + k * 1024); } while (0)
; #define PG8_LDB(dst, b, h) do { _Pragma("unroll") for (int n = 0; n < 2; ++n) _Pragma("unroll") for (int k = 0; k < 2; ++k) dst[n][k] = *(const LAS bf16x8*)(lds + PG8_SB(b, h) + boff + n * 2048 + k * 1024); } while (0)
; #define PG8_WAIT_V(n) asm volatile("s_waitcnt vmcnt(" #n ")" ::: "memory")
; #define PG8_WAIT_L(n) asm volatile("s_waitcnt lgkmcnt(" #n ")" ::: "memory")
; #define PG8_BAR __builtin_amdgcn_s_barrier()
; #define PG8_SCHED __builtin_amdgcn_sched_barrier(0)
;     ...
;         for (int t = 0; t < nt; t += 2) {
;             const bool last = (t == nt - 2);
;             const char* a1 = cA + (size_t)(t + 1) * kstep;
;             const char* a2 = last ? nA : cA + (size_t)(t + 2) * kstep; const char* b2 = last ? nB : cB + (size_t)(t + 2) * kstep;
;             const char* a3 = a2 + kstep; const char* b3 = b2 + kstep;
;             PG8_LDB(B0, 0, 0); PG8_LDB(B1, 0, 1); PG8_SCHED; PG8_LDA(At, 0, 0); PG8_STAGE(PG8_SA(1, 1), a1 + hstep, voffA);
;             PG8_WAIT_V(8); PG8_WAIT_L(0); PG8_BAR; PG8_MMA(0, 0, At, B0); PG8_MMA(0, 1, At, B1); PG8_BAR; PG8_SCHED;
;             PG8_LDA(At, 0, 1); PG8_STAGE(PG8_SB(0, 0), b2, voffB); PG8_STAGE(PG8_SB(0, 1), b2 + hstep, voffB); PG8_STAGE(PG8_SA(0, 0), a2, voffA);
;             PG8_WAIT_V(8); PG8_WAIT_L(0); PG8_BAR; PG8_MMA(1, 0, At, B0); PG8_MMA(1, 1, At, B1); PG8_BAR; PG8_SCHED;
.LBB0_4502:
	ds_read_b128 v[24:27], v187
	ds_read_b128 v[28:31], v187 offset:1024
	ds_read_b128 v[16:19], v187 offset:2048
	ds_read_b128 v[20:23], v187 offset:3072
	ds_read_b128 v[8:11], v188
	ds_read_b128 v[12:15], v188 offset:1024
	ds_read_b128 v[0:3], v188 offset:2048
	ds_read_b128 v[4:7], v188 offset:3072
	s_add_u32 s44, s42, 0xfffc0080
	s_addc_u32 s45, s43, -1
	s_cmp_eq_u32 s67, 12
	s_cselect_b32 s47, s37, s45
	s_cselect_b32 s46, s63, s44
	s_cselect_b32 s45, s31, s66
	s_cselect_b32 s44, s64, s65
	v_lshl_add_u64 v[216:217], s[42:43], 0, v[168:169]
	s_add_i32 m0, s48, 0xc000
	ds_read_b128 v[176:179], v189
	ds_read_b128 v[180:183], v189 offset:1024
	ds_read_b128 v[192:195], v189 offset:2048
	ds_read_b128 v[196:199], v189 offset:3072
	ds_read_b128 v[200:203], v189 offset:4096
	ds_read_b128 v[204:207], v189 offset:5120
	ds_read_b128 v[208:211], v189 offset:6144
	ds_read_b128 v[212:215], v189 offset:7168
	global_load_lds_dwordx4 v[216:217], off
	v_lshl_add_u64 v[216:217], s[42:43], 0, v[170:171]
	s_add_i32 m0, s48, 0xe000
	s_nop 0
	global_load_lds_dwordx4 v[216:217], off
	s_waitcnt vmcnt(8)
	s_waitcnt lgkmcnt(0)
	s_setprio 1
	s_waitcnt lgkmcnt(0)
	v_mfma_scale_f32_16x16x128_f8f6f4 v[156:159], v[24:31], v[176:183], v[156:159], v190, v190 op_sel_hi:[0,0,0]
	v_mfma_scale_f32_16x16x128_f8f6f4 v[152:155], v[16:23], v[176:183], v[152:155], v190, v190 op_sel_hi:[0,0,0]
	v_mfma_scale_f32_16x16x128_f8f6f4 v[140:143], v[24:31], v[192:199], v[140:143], v190, v190 op_sel_hi:[0,0,0]
	v_mfma_scale_f32_16x16x128_f8f6f4 v[136:139], v[16:23], v[192:199], v[136:139], v190, v190 op_sel_hi:[0,0,0]
	s_barrier
	v_mfma_scale_f32_16x16x128_f8f6f4 v[124:127], v[24:31], v[200:207], v[124:127], v190, v190 op_sel_hi:[0,0,0]
	v_mfma_scale_f32_16x16x128_f8f6f4 v[120:123], v[16:23], v[200:207], v[120:123], v190, v190 op_sel_hi:[0,0,0]
	v_mfma_scale_f32_16x16x128_f8f6f4 v[108:111], v[24:31], v[208:215], v[108:111], v190, v190 op_sel_hi:[0,0,0]
	v_mfma_scale_f32_16x16x128_f8f6f4 v[104:107], v[16:23], v[208:215], v[104:107], v190, v190 op_sel_hi:[0,0,0]
	s_setprio 0
	s_setprio 1
	v_mfma_scale_f32_16x16x128_f8f6f4 v[148:151], v[8:15], v[176:183], v[148:151], v190, v190 op_sel_hi:[0,0,0]
	v_mfma_scale_f32_16x16x128_f8f6f4 v[144:147], v[0:7], v[176:183], v[144:147], v190, v190 op_sel_hi:[0,0,0]
	v_mfma_scale_f32_16x16x128_f8f6f4 v[132:135], v[8:15], v[192:199], v[132:135], v190, v190 op_sel_hi:[0,0,0]
	v_mfma_scale_f32_16x16x128_f8f6f4 v[128:131], v[0:7], v[192:199], v[128:131], v190, v190 op_sel_hi:[0,0,0]
	v_mfma_scale_f32_16x16x128_f8f6f4 v[116:119], v[8:15], v[200:207], v[116:119], v190, v190 op_sel_hi:[0,0,0]
	v_mfma_scale_f32_16x16x128_f8f6f4 v[112:115], v[0:7], v[200:207], v[112:115], v190, v190 op_sel_hi:[0,0,0]
	v_mfma_scale_f32_16x16x128_f8f6f4 v[100:103], v[8:15], v[208:215], v[100:103], v190, v190 op_sel_hi:[0,0,0]
	v_mfma_scale_f32_16x16x128_f8f6f4 v[96:99], v[0:7], v[208:215], v[96:99], v190, v190 op_sel_hi:[0,0,0]
	s_setprio 0
	s_barrier
	s_add_i32 s68, s60, s35
	v_lshl_add_u64 v[176:177], s[44:45], 0, v[162:163]
	s_mov_b32 m0, s68
	ds_read_b128 v[192:195], v189 offset:16384
	ds_read_b128 v[196:199], v189 offset:17408
	ds_read_b128 v[200:203], v189 offset:18432
	ds_read_b128 v[204:207], v189 offset:19456
	ds_read_b128 v[208:211], v189 offset:20480
	ds_read_b128 v[212:215], v189 offset:21504
	ds_read_b128 v[216:219], v189 offset:22528
	ds_read_b128 v[220:223], v189 offset:23552
	global_load_lds_dwordx4 v[176:177], off
	s_add_i32 m0, s68, 0x2000
	s_add_u32 s68, s44, 0x40000
	v_lshl_add_u64 v[178:179], s[44:45], 0, v[166:167]
	s_addc_u32 s69, s45, 0
	s_add_i32 s70, s61, s35
	global_load_lds_dwordx4 v[178:179], off
	v_lshl_add_u64 v[180:181], s[68:69], 0, v[162:163]
	s_mov_b32 m0, s70
	v_lshl_add_u64 v[182:183], s[46:47], 0, v[164:165]
	global_load_lds_dwordx4 v[180:181], off
	v_lshl_add_u64 v[180:181], s[68:69], 0, v[166:167]
	s_add_i32 m0, s70, 0x2000
	s_nop 0
	global_load_lds_dwordx4 v[180:181], off
	v_lshl_add_u64 v[180:181], s[46:47], 0, v[160:161]
	s_mov_b32 m0, s48
	s_nop 0
	global_load_lds_dwordx4 v[180:181], off
	s_mov_b32 m0, s49
	s_nop 0
	global_load_lds_dwordx4 v[182:183], off
	s_waitcnt vmcnt(8)
	s_waitcnt lgkmcnt(0)
	s_setprio 1
	s_waitcnt lgkmcnt(0)
	v_mfma_scale_f32_16x16x128_f8f6f4 v[92:95], v[24:31], v[192:199], v[92:95], v190, v190 op_sel_hi:[0,0,0]
	v_mfma_scale_f32_16x16x128_f8f6f4 v[88:91], v[16:23], v[192:199], v[88:91], v190, v190 op_sel_hi:[0,0,0]
	v_mfma_scale_f32_16x16x128_f8f6f4 v[76:79], v[24:31], v[200:207], v[76:79], v190, v190 op_sel_hi:[0,0,0]
	v_mfma_scale_f32_16x16x128_f8f6f4 v[72:75], v[16:23], v[200:207], v[72:75], v190, v190 op_sel_hi:[0,0,0]
	s_barrier
	v_mfma_scale_f32_16x16x128_f8f6f4 v[60:63], v[24:31], v[208:215], v[60:63], v190, v190 op_sel_hi:[0,0,0]
	v_mfma_scale_f32_16x16x128_f8f6f4 v[56:59], v[16:23], v[208:215], v[56:59], v190, v190 op_sel_hi:[0,0,0]
	v_mfma_scale_f32_16x16x128_f8f6f4 v[44:47], v[24:31], v[216:223], v[44:47], v190, v190 op_sel_hi:[0,0,0]
	v_mfma_scale_f32_16x16x128_f8f6f4 v[40:43], v[16:23], v[216:223], v[40:43], v190, v190 op_sel_hi:[0,0,0]
	s_setprio 0
	s_setprio 1
	v_mfma_scale_f32_16x16x128_f8f6f4 v[84:87], v[8:15], v[192:199], v[84:87], v190, v190 op_sel_hi:[0,0,0]
	v_mfma_scale_f32_16x16x128_f8f6f4 v[80:83], v[0:7], v[192:199], v[80:83], v190, v190 op_sel_hi:[0,0,0]
	v_mfma_scale_f32_16x16x128_f8f6f4 v[68:71], v[8:15], v[200:207], v[68:71], v190, v190 op_sel_hi:[0,0,0]
	v_mfma_scale_f32_16x16x128_f8f6f4 v[64:67], v[0:7], v[200:207], v[64:67], v190, v190 op_sel_hi:[0,0,0]
	v_mfma_scale_f32_16x16x128_f8f6f4 v[52:55], v[8:15], v[208:215], v[52:55], v190, v190 op_sel_hi:[0,0,0]
	v_mfma_scale_f32_16x16x128_f8f6f4 v[48:51], v[0:7], v[208:215], v[48:51], v190, v190 op_sel_hi:[0,0,0]
	v_mfma_scale_f32_16x16x128_f8f6f4 v[36:39], v[8:15], v[216:223], v[36:39], v190, v190 op_sel_hi:[0,0,0]
	v_mfma_scale_f32_16x16x128_f8f6f4 v[32:35], v[0:7], v[216:223], v[32:35], v190, v190 op_sel_hi:[0,0,0]
	s_setprio 0
	s_barrier
; #define PG8_STAGE(bufoff, gbase, voff) do { _Pragma("unroll") for (int _i = 0; _i < 2; ++_i) \
;         __builtin_amdgcn_global_load_lds((const unsigned*)((const char*)(gbase) + (voff)[_i]), (LAS unsigned*)(lds + (bufoff) + ldsw + _i * 8192), 16, 0, 0); } while (0)
; #define PG8_LDA(dst, b, h) do { _Pragma("unroll") for (int m = 0; m < 4; ++m) _Pragma("unroll") for (int k = 0; k < 2; ++k) dst[m][k] = *(const LAS bf16x8*)(lds + PG8_SA(b, h) + aoff + m * 2048 + k * 1024); } while (0)
; #define PG8_LDB(dst, b, h) do { _Pragma("unroll") for (int n = 0; n < 2; ++n) _Pragma("unroll") for (int k = 0; k < 2; ++k) dst[n][k] = *(const LAS bf16x8*)(lds + PG8_SB(b, h) + boff + n * 2048 + k * 1024); } while (0)
; #define PG8_WAIT_V(n) asm volatile("s_waitcnt vmcnt(" #n ")" ::: "memory")
; #define PG8_WAIT_L(n) asm volatile("s_waitcnt lgkmcnt(" #n ")" ::: "memory")
; #define PG8_BAR __builtin_amdgcn_s_barrier()
; #define PG8_SCHED __builtin_amdgcn_sched_barrier(0)
;     __device__ __forceinline__ float qscale(const Unit& u) const { return ((u.pn >= 8 && u.pn <= 11) || u.pn == 17) ? 0.5f : 1.0f; }
;     ...
;             PG8_LDB(B0, 1, 0); PG8_LDB(B1, 1, 1); PG8_SCHED; PG8_LDA(At, 1, 0); PG8_STAGE(PG8_SA(0, 1), a2 + hstep, voffA);
;             PG8_WAIT_V(8); PG8_WAIT_L(0); PG8_BAR; PG8_MMA(0, 0, At, B0); PG8_MMA(0, 1, At, B1); PG8_BAR; PG8_SCHED;
;             PG8_LDA(At, 1, 1); PG8_STAGE(PG8_SB(1, 0), b3, voffB); PG8_STAGE(PG8_SB(1, 1), b3 + hstep, voffB); PG8_STAGE(PG8_SA(1, 0), a3, voffA);
;             PG8_WAIT_V(8); PG8_WAIT_L(0); PG8_BAR; PG8_MMA(1, 0, At, B0); PG8_MMA(1, 1, At, B1); PG8_BAR; PG8_SCHED;
;         }
;         if constexpr (QM == 2) { const float qs0_ = g.qs * E.qscale(cur), qs1_ = qs0_ * g.qs_b1; _Pragma("unroll") for (int a = 0; a < 2; ++a) _Pragma("unroll") for (int b = 0; b < 2; ++b) _Pragma("unroll") for (int m = 0; m < 4; ++m) _Pragma("unroll") for (int n = 0; n < 2; ++n) { const v4i t_ = __builtin_bit_cast(v4i, acc[a][b][m][n]); acc[a][b][m][n] = (f32x4){(float)t_[0], (float)t_[1], (float)t_[2], (float)t_[3]} * (b == 0 ? qs0_ : qs1_); } }
;         if constexpr (QM == 1) asm volatile("s_nop 15\n\ts_nop 15\n\ts_nop 15" ::: "memory");
;         if (wr == 0) PG8_BAR;
	s_add_i32 s68, 0, 0x18000
	s_add_i32 s69, 0, 0x1c000
	v_add_u32_e32 v12, s68, v185
	v_add_u32_e32 v28, s69, v185
	ds_read_b128 v[0:3], v12
	ds_read_b128 v[4:7], v12 offset:1024
	ds_read_b128 v[8:11], v12 offset:2048
	ds_read_b128 v[12:15], v12 offset:3072
	ds_read_b128 v[16:19], v28
	ds_read_b128 v[20:23], v28 offset:1024
	ds_read_b128 v[24:27], v28 offset:2048
	ds_read_b128 v[28:31], v28 offset:3072
	s_add_u32 s46, s46, 0x40000
	s_addc_u32 s47, s47, 0
	s_mov_b32 m0, s50
	v_lshl_add_u64 v[224:225], s[46:47], 0, v[160:161]
	ds_read_b128 v[192:195], v189 offset:32768
	ds_read_b128 v[196:199], v189 offset:33792
	ds_read_b128 v[200:203], v189 offset:34816
	ds_read_b128 v[204:207], v189 offset:35840
	ds_read_b128 v[208:211], v189 offset:36864
	ds_read_b128 v[212:215], v189 offset:37888
	ds_read_b128 v[216:219], v189 offset:38912
	ds_read_b128 v[220:223], v189 offset:39936
	global_load_lds_dwordx4 v[224:225], off
	v_lshl_add_u64 v[224:225], s[46:47], 0, v[164:165]
	s_mov_b32 m0, s51
	s_nop 0
	global_load_lds_dwordx4 v[224:225], off
	s_waitcnt vmcnt(8)
	s_waitcnt lgkmcnt(0)
	s_setprio 1
	s_waitcnt lgkmcnt(0)
	v_mfma_scale_f32_16x16x128_f8f6f4 v[156:159], v[0:7], v[192:199], v[156:159], v190, v190 op_sel_hi:[0,0,0]
	v_mfma_scale_f32_16x16x128_f8f6f4 v[152:155], v[8:15], v[192:199], v[152:155], v190, v190 op_sel_hi:[0,0,0]
	v_mfma_scale_f32_16x16x128_f8f6f4 v[140:143], v[0:7], v[200:207], v[140:143], v190, v190 op_sel_hi:[0,0,0]
	v_mfma_scale_f32_16x16x128_f8f6f4 v[136:139], v[8:15], v[200:207], v[136:139], v190, v190 op_sel_hi:[0,0,0]
	s_barrier
	v_mfma_scale_f32_16x16x128_f8f6f4 v[124:127], v[0:7], v[208:215], v[124:127], v190, v190 op_sel_hi:[0,0,0]
	v_mfma_scale_f32_16x16x128_f8f6f4 v[120:123], v[8:15], v[208:215], v[120:123], v190, v190 op_sel_hi:[0,0,0]
	v_mfma_scale_f32_16x16x128_f8f6f4 v[108:111], v[0:7], v[216:223], v[108:111], v190, v190 op_sel_hi:[0,0,0]
	v_mfma_scale_f32_16x16x128_f8f6f4 v[104:107], v[8:15], v[216:223], v[104:107], v190, v190 op_sel_hi:[0,0,0]
	s_setprio 0
	s_setprio 1
	v_mfma_scale_f32_16x16x128_f8f6f4 v[148:151], v[16:23], v[192:199], v[148:151], v190, v190 op_sel_hi:[0,0,0]
	v_mfma_scale_f32_16x16x128_f8f6f4 v[144:147], v[24:31], v[192:199], v[144:147], v190, v190 op_sel_hi:[0,0,0]
	v_mfma_scale_f32_16x16x128_f8f6f4 v[132:135], v[16:23], v[200:207], v[132:135], v190, v190 op_sel_hi:[0,0,0]
	v_mfma_scale_f32_16x16x128_f8f6f4 v[128:131], v[24:31], v[200:207], v[128:131], v190, v190 op_sel_hi:[0,0,0]
	v_mfma_scale_f32_16x16x128_f8f6f4 v[116:119], v[16:23], v[208:215], v[116:119], v190, v190 op_sel_hi:[0,0,0]
	v_mfma_scale_f32_16x16x128_f8f6f4 v[112:115], v[24:31], v[208:215], v[112:115], v190, v190 op_sel_hi:[0,0,0]
	v_mfma_scale_f32_16x16x128_f8f6f4 v[100:103], v[16:23], v[216:223], v[100:103], v190, v190 op_sel_hi:[0,0,0]
	v_mfma_scale_f32_16x16x128_f8f6f4 v[96:99], v[24:31], v[216:223], v[96:99], v190, v190 op_sel_hi:[0,0,0]
	s_setprio 0
	s_barrier
	s_add_i32 s46, s68, s35
	v_lshl_add_u64 v[176:177], v[176:177], 0, s[18:19]
	s_mov_b32 m0, s46
	ds_read_b128 v[192:195], v189 offset:49152
	ds_read_b128 v[196:199], v189 offset:50176
	ds_read_b128 v[200:203], v189 offset:51200
	ds_read_b128 v[204:207], v189 offset:52224
	ds_read_b128 v[208:211], v189 offset:53248
	ds_read_b128 v[212:215], v189 offset:54272
	ds_read_b128 v[216:219], v189 offset:55296
	ds_read_b128 v[220:223], v189 offset:56320
	global_load_lds_dwordx4 v[176:177], off
	s_add_i32 m0, s46, 0x2000
	s_add_u32 s44, s44, 0x40080
	v_lshl_add_u64 v[176:177], v[178:179], 0, s[18:19]
	s_addc_u32 s45, s45, 0
	s_add_i32 s46, s69, s35
	global_load_lds_dwordx4 v[176:177], off
	v_lshl_add_u64 v[176:177], s[44:45], 0, v[162:163]
	s_mov_b32 m0, s46
	s_nop 0
	global_load_lds_dwordx4 v[176:177], off
	v_lshl_add_u64 v[176:177], s[44:45], 0, v[166:167]
	s_add_i32 m0, s46, 0x2000
	s_nop 0
	global_load_lds_dwordx4 v[176:177], off
	v_lshl_add_u64 v[176:177], v[180:181], 0, s[18:19]
	s_mov_b32 m0, s55
	s_nop 0
	global_load_lds_dwordx4 v[176:177], off
	v_lshl_add_u64 v[176:177], v[182:183], 0, s[18:19]
	s_mov_b32 m0, s58
	s_nop 0
	global_load_lds_dwordx4 v[176:177], off
	s_waitcnt vmcnt(8)
	s_waitcnt lgkmcnt(0)
	s_setprio 1
	s_waitcnt lgkmcnt(0)
	v_mfma_scale_f32_16x16x128_f8f6f4 v[92:95], v[0:7], v[192:199], v[92:95], v190, v190 op_sel_hi:[0,0,0]
	v_mfma_scale_f32_16x16x128_f8f6f4 v[88:91], v[8:15], v[192:199], v[88:91], v190, v190 op_sel_hi:[0,0,0]
	v_mfma_scale_f32_16x16x128_f8f6f4 v[76:79], v[0:7], v[200:207], v[76:79], v190, v190 op_sel_hi:[0,0,0]
	v_mfma_scale_f32_16x16x128_f8f6f4 v[72:75], v[8:15], v[200:207], v[72:75], v190, v190 op_sel_hi:[0,0,0]
	s_barrier
	v_mfma_scale_f32_16x16x128_f8f6f4 v[60:63], v[0:7], v[208:215], v[60:63], v190, v190 op_sel_hi:[0,0,0]
	v_mfma_scale_f32_16x16x128_f8f6f4 v[56:59], v[8:15], v[208:215], v[56:59], v190, v190 op_sel_hi:[0,0,0]
	v_mfma_scale_f32_16x16x128_f8f6f4 v[44:47], v[0:7], v[216:223], v[44:47], v190, v190 op_sel_hi:[0,0,0]
	v_mfma_scale_f32_16x16x128_f8f6f4 v[40:43], v[8:15], v[216:223], v[40:43], v190, v190 op_sel_hi:[0,0,0]
	s_setprio 0
	s_setprio 1
	v_mfma_scale_f32_16x16x128_f8f6f4 v[84:87], v[16:23], v[192:199], v[84:87], v190, v190 op_sel_hi:[0,0,0]
	v_mfma_scale_f32_16x16x128_f8f6f4 v[80:83], v[24:31], v[192:199], v[80:83], v190, v190 op_sel_hi:[0,0,0]
	v_mfma_scale_f32_16x16x128_f8f6f4 v[68:71], v[16:23], v[200:207], v[68:71], v190, v190 op_sel_hi:[0,0,0]
	v_mfma_scale_f32_16x16x128_f8f6f4 v[64:67], v[24:31], v[200:207], v[64:67], v190, v190 op_sel_hi:[0,0,0]
	v_mfma_scale_f32_16x16x128_f8f6f4 v[52:55], v[16:23], v[208:215], v[52:55], v190, v190 op_sel_hi:[0,0,0]
	v_mfma_scale_f32_16x16x128_f8f6f4 v[48:51], v[24:31], v[208:215], v[48:51], v190, v190 op_sel_hi:[0,0,0]
	v_mfma_scale_f32_16x16x128_f8f6f4 v[36:39], v[16:23], v[216:223], v[36:39], v190, v190 op_sel_hi:[0,0,0]
	v_mfma_scale_f32_16x16x128_f8f6f4 v[32:35], v[24:31], v[216:223], v[32:35], v190, v190 op_sel_hi:[0,0,0]
	s_setprio 0
	s_barrier
	s_add_i32 s67, s67, 2
	s_add_u32 s42, s42, 0x100
	s_addc_u32 s43, s43, 0
	s_add_u32 s65, s65, 0x100
	s_addc_u32 s66, s66, 0
	s_cmp_gt_u32 s67, 13
	s_cbranch_scc0 .LBB0_4502
	s_nop 15
	s_nop 15
	s_nop 15
	s_and_b64 vcc, exec, s[20:21]
	s_cbranch_vccz .LBB0_4505
	s_barrier

; #define PG8_STAGE(bufoff, gbase, voff) do { _Pragma("unroll") for (int _i = 0; _i < 2; ++_i) \
;         __builtin_amdgcn_global_load_lds((const unsigned*)((const char*)(gbase) + (voff)[_i]), (LAS unsigned*)(lds + (bufoff) + ldsw + _i * 8192), 16, 0, 0); } while (0)
; #define PG8_WAIT_V(n) asm volatile("s_waitcnt vmcnt(" #n ")" ::: "memory")
; #define PG8_BAR __builtin_amdgcn_s_barrier()
;     __device__ __forceinline__ bool next(int i, Unit& u) const {
;     ...
;         if (ts) { int e = 0;
; #pragma unroll
;             for (int j = 1; j < 8; ++j) e += (u.pm >= ts[j]) ? 1 : 0;
;             u.e = e; }
;     ...
;     const int aoff = lds_byte(wr * 64 + fr, fq * 8), boff = lds_byte(wc * 32 + fr, fq * 8);
;     ...
;     Unit cur, nxt; int ui = 0;
;     if (!S.next(0, cur)) return;
;     const int sc1_ = 0x7F7F7F7F; (void)sc1_;
;     f32x4 acc[2][2][4][2];
; #pragma unroll
;     for (int a = 0; a < 2; ++a)
; #pragma unroll
;         for (int b = 0; b < 2; ++b)
; #pragma unroll
;             for (int m = 0; m < 4; ++m)
; #pragma unroll
;                 for (int n = 0; n < 2; ++n) acc[a][b][m][n] = (f32x4){0.f, 0.f, 0.f, 0.f};
;     bf16x8 At[4][2], B0[2][2], B1[2][2];
;     const char* cA = (const char*)g.A + (size_t)cur.pm * tstep + (size_t)cur.kt0 * kstep; const char* cB = (const char*)g.Bt + (size_t)cur.e * g.estride + (size_t)cur.pn * tstep + (size_t)cur.kt0 * kstep;
;     PG8_STAGE(PG8_SB(0, 0), cB, voffB); PG8_STAGE(PG8_SB(0, 1), cB + hstep, voffB); PG8_STAGE(PG8_SA(0, 0), cA, voffA); PG8_STAGE(PG8_SA(0, 1), cA + hstep, voffA);
;     if (wr == 1) PG8_BAR;
;     PG8_WAIT_V(2); PG8_BAR;
;     PG8_STAGE(PG8_SB(1, 0), cB + kstep, voffB); PG8_STAGE(PG8_SA(1, 0), cA + kstep, voffA); PG8_STAGE(PG8_SB(1, 1), cB + hstep + kstep, voffB);
;     PG8_WAIT_V(6); PG8_BAR;
.LBB0_4730:
	s_add_u32 s16, s56, 0x4b000000
	s_mov_b64 s[18:19], 0x80
	s_addc_u32 s17, s57, 0
	s_add_i32 m0, s43, 0x18000
	v_lshl_add_u64 v[8:9], v[8:9], 0, s[18:19]
	s_waitcnt vmcnt(2)
	s_barrier
	global_load_lds_dwordx4 v[8:9], off
	v_lshl_add_u64 v[6:7], v[6:7], 0, s[18:19]
	s_add_i32 m0, s43, 0x1a000
	s_add_i32 s58, s43, 0x8000
	global_load_lds_dwordx4 v[6:7], off
	v_lshl_add_u64 v[2:3], v[2:3], 0, s[18:19]
	s_mov_b32 m0, s58
	s_add_i32 s59, s43, 0xa000
	global_load_lds_dwordx4 v[2:3], off
	v_lshl_add_u64 v[2:3], v[4:5], 0, s[18:19]
	s_mov_b32 m0, s59
	s_mov_b64 s[20:21], 0x40080
	global_load_lds_dwordx4 v[2:3], off
	v_lshl_add_u64 v[2:3], v[0:1], 0, s[20:21]
	s_add_i32 m0, s43, 0x1c000
	v_lshl_add_u64 v[4:5], v[2:3], 0, v[128:129]
	global_load_lds_dwordx4 v[4:5], off
	v_lshl_add_u64 v[2:3], v[2:3], 0, v[134:135]
	s_add_i32 m0, s43, 0x1e000
	s_lshl_b32 s3, s3, 5
	global_load_lds_dwordx4 v[2:3], off
	v_lshrrev_b32_e32 v3, 1, v10
	v_and_b32_e32 v3, 24, v3
	v_and_b32_e32 v2, 15, v10
	v_lshlrev_b32_e32 v4, 1, v3
	v_lshl_or_b32 v148, s4, 6, v2
	v_lshl_or_b32 v2, v2, 6, v4
	v_lshlrev_b32_e32 v4, 2, v10
	s_lshl_b32 s4, s4, 13
	v_and_b32_e32 v4, 32, v4
	s_and_b32 s3, s3, 0x60
	v_bitop3_b32 v5, v2, s4, v4 bitop3:0xde
	s_lshl_b32 s4, s3, 7
	v_bitop3_b32 v149, s4, v2, v4 bitop3:0xf6
	v_lshlrev_b32_e32 v2, 14, v12
	v_and_b32_e32 v2, 0xffff8000, v2
	v_or_b32_e32 v150, s3, v3
	v_lshl_add_u32 v2, v13, 11, v2
	v_and_b32_e32 v3, 1, v12
	v_lshl_or_b32 v2, v3, 6, v2
	v_lshl_add_u32 v138, v15, 1, v2
	v_lshlrev_b32_e32 v2, 14, v11
	v_and_b32_e32 v2, 0xffff8000, v2
	s_waitcnt vmcnt(6)
	s_cmpk_lt_u32 s2, 0x100
	v_lshl_add_u32 v2, v14, 11, v2
	v_and_b32_e32 v3, 1, v11
	s_cselect_b64 s[24:25], -1, 0
	v_mov_b32_e32 v139, 0
	v_lshl_or_b32 v2, v3, 6, v2
	s_add_i32 s61, 0, 0x10000
	s_add_i32 s62, 0, 0x14000
	s_ashr_i32 s60, s33, 31
	v_ashrrev_i32_e32 v131, 31, v130
	v_lshl_add_u32 v140, v16, 1, v2
	v_mov_b32_e32 v141, v139
	s_mov_b64 s[26:27], 0x100
	v_add_u32_e32 v151, s61, v149
	v_add_u32_e32 v152, s62, v149
	v_add_u32_e32 v153, 0, v5
	s_mov_b32 s28, 0x3773ad84
	s_mov_b32 s30, 0x3973ad84
	s_mov_b32 s63, 0xc3e00000
	s_movk_i32 s64, 0x1c00
	v_mov_b32_e32 v154, 0x43e00000
	global_load_dwordx4 v[230:233], v139, s[10:11]
	global_load_dwordx3 v[234:236], v139, s[10:11] offset:16
	s_waitcnt vmcnt(0)
	s_barrier
	s_branch .LBB0_4733

;     __device__ __forceinline__ bool next(int i, Unit& u) const {
;         const long L = (long)i * G + c; if (L >= nwg) return false;
;         int wgid = (int)L; { const int q = nwg / NXCD, r = nwg % NXCD, xcd = wgid % NXCD, off = wgid / NXCD; wgid = (xcd < r ? xcd * (q + 1) : r * (q + 1) + (xcd - r) * q) + off; }
;         const int nig = WGM * nN, gid = wgid / nig, fm = gid * WGM, gsz = (nM - fm) < WGM ? (nM - fm) : WGM;
;         u.pm = fm + ((wgid % nig) % gsz); u.pn = (wgid % nig) / gsz; u.e = 0; u.kt0 = 0; u.nkt = nt; u.buf = 0;
;         if (ts) { int e = 0;
; #pragma unroll
;             for (int j = 1; j < 8; ++j) e += (u.pm >= ts[j]) ? 1 : 0;
;             u.e = e; }
.LBB0_4733:
	s_add_i32 s55, s55, 1
	s_mul_i32 s2, s55, s60
	s_mul_hi_u32 s3, s55, s33
	s_add_i32 s3, s3, s2
	s_mul_i32 s2, s55, s33
	s_add_u32 s2, s2, s22
	s_addc_u32 s3, s3, s48
	v_cmp_ge_i64_e32 vcc, s[2:3], v[130:131]
	v_cmp_lt_i64_e64 s[4:5], s[2:3], v[130:131]
	s_cbranch_vccnz .LBB0_4735
	s_ashr_i32 s3, s2, 31
	s_lshr_b32 s3, s3, 29
	s_add_i32 s3, s2, s3
	s_ashr_i32 s36, s3, 3
	s_and_b32 s3, s3, -8
	s_sub_i32 s2, s2, s3
	s_cmp_lt_i32 s2, 0
	s_cselect_b32 s3, s49, s35
	s_mul_i32 s2, s3, s2
	s_add_i32 s2, s2, s36
	s_mul_hi_i32 s3, s2, 0x92492493
	s_add_i32 s3, s3, s2
	s_lshr_b32 s36, s3, 31
	s_ashr_i32 s3, s3, 8
	s_add_i32 s3, s3, s36
	s_lshl_b32 s37, s3, 3
	s_sub_i32 s36, s23, s37
	s_min_i32 s38, s36, 8
	s_abs_i32 s36, s38
	v_cvt_f32_u32_e32 v9, s36
	s_sub_i32 s40, 0, s36
	s_mulk_i32 s3, 0x1c0
	s_sub_i32 s2, s2, s3
	v_rcp_iflag_f32_e32 v9, v9
	s_abs_i32 s3, s2
	s_xor_b32 s39, s2, s38
	s_ashr_i32 s39, s39, 31
	v_mul_f32_e32 v9, 0x4f7ffffe, v9
	v_cvt_u32_f32_e32 v9, v9
	s_nop 0
	v_readfirstlane_b32 s41, v9
	s_mul_i32 s40, s40, s41
	s_mul_hi_u32 s40, s41, s40
	s_add_i32 s41, s41, s40
	s_mul_hi_u32 s40, s3, s41
	s_mul_i32 s41, s40, s36
	s_sub_i32 s3, s3, s41
	s_add_i32 s65, s40, 1
	s_sub_i32 s41, s3, s36
	s_cmp_ge_u32 s3, s36
	s_cselect_b32 s40, s65, s40
	s_cselect_b32 s3, s41, s3
	s_add_i32 s41, s40, 1
	s_cmp_ge_u32 s3, s36
	s_cselect_b32 s3, s41, s40
	s_xor_b32 s3, s3, s39
	s_sub_i32 s36, s3, s39
	s_mul_i32 s3, s36, s38
	s_sub_i32 s2, s2, s3
	s_add_i32 s38, s2, s37
	v_cmp_ge_i32_e32 vcc, s38, v230
	s_nop 1
	v_cndmask_b32_e64 v2, 0, 1, vcc
	v_cmp_ge_i32_e32 vcc, s38, v231
	s_nop 1
	v_cndmask_b32_e64 v3, 0, 1, vcc
	v_cmp_ge_i32_e32 vcc, s38, v233
	s_nop 1
	v_cndmask_b32_e64 v5, 0, 1, vcc
	v_cmp_ge_i32_e32 vcc, s38, v235
	s_nop 1
	v_cndmask_b32_e64 v7, 0, 1, vcc
	v_cmp_ge_i32_e32 vcc, s38, v232
	s_nop 1
	v_addc_co_u32_e32 v2, vcc, v3, v2, vcc
	v_cmp_ge_i32_e32 vcc, s38, v234
	s_nop 1
	v_addc_co_u32_e32 v2, vcc, v2, v5, vcc
	v_cmp_ge_i32_e32 vcc, s38, v236
	s_nop 1
	v_addc_co_u32_e32 v155, vcc, v2, v7, vcc

; #define PG8_STAGE(bufoff, gbase, voff) do { _Pragma("unroll") for (int _i = 0; _i < 2; ++_i) \
;         __builtin_amdgcn_global_load_lds((const unsigned*)((const char*)(gbase) + (voff)[_i]), (LAS unsigned*)(lds + (bufoff) + ldsw + _i * 8192), 16, 0, 0); } while (0)
; #define PG8_LDA(dst, b, h) do { _Pragma("unroll") for (int m = 0; m < 4; ++m) _Pragma("unroll") for (int k = 0; k < 2; ++k) dst[m][k] = *(const LAS bf16x8*)(lds + PG8_SA(b, h) + aoff + m * 2048 + k * 1024); } while (0)
; #define PG8_LDB(dst, b, h) do { _Pragma("unroll") for (int n = 0; n < 2; ++n) _Pragma("unroll") for (int k = 0; k < 2; ++k) dst[n][k] = *(const LAS bf16x8*)(lds + PG8_SB(b, h) + boff + n * 2048 + k * 1024); } while (0)
; #define PG8_WAIT_V(n) asm volatile("s_waitcnt vmcnt(" #n ")" ::: "memory")
; #define PG8_WAIT_L(n) asm volatile("s_waitcnt lgkmcnt(" #n ")" ::: "memory")
; #define PG8_BAR __builtin_amdgcn_s_barrier()
; #define PG8_SCHED __builtin_amdgcn_sched_barrier(0)
;     ...
;         for (int t = 0; t < nt; t += 2) {
;             const bool last = (t == nt - 2);
;             const char* a1 = cA + (size_t)(t + 1) * kstep;
;             const char* a2 = last ? nA : cA + (size_t)(t + 2) * kstep; const char* b2 = last ? nB : cB + (size_t)(t + 2) * kstep;
;             const char* a3 = a2 + kstep; const char* b3 = b2 + kstep;
;             PG8_LDB(B0, 0, 0); PG8_LDB(B1, 0, 1); PG8_SCHED; PG8_LDA(At, 0, 0); PG8_STAGE(PG8_SA(1, 1), a1 + hstep, voffA);
;             PG8_WAIT_V(8); PG8_WAIT_L(0); PG8_BAR; PG8_MMA(0, 0, At, B0); PG8_MMA(0, 1, At, B1); PG8_BAR; PG8_SCHED;
;             PG8_LDA(At, 0, 1); PG8_STAGE(PG8_SB(0, 0), b2, voffB); PG8_STAGE(PG8_SB(0, 1), b2 + hstep, voffB); PG8_STAGE(PG8_SA(0, 0), a2, voffA);
;             PG8_WAIT_V(8); PG8_WAIT_L(0); PG8_BAR; PG8_MMA(1, 0, At, B0); PG8_MMA(1, 1, At, B1); PG8_BAR; PG8_SCHED;
.LBB0_4738:
	ds_read_b128 v[156:159], v151
	ds_read_b128 v[160:163], v151 offset:1024
	ds_read_b128 v[164:167], v151 offset:2048
	ds_read_b128 v[168:171], v151 offset:3072
	ds_read_b128 v[172:175], v152
	ds_read_b128 v[176:179], v152 offset:1024
	ds_read_b128 v[180:183], v152 offset:2048
	ds_read_b128 v[184:187], v152 offset:3072
	s_add_u32 s46, s4, 0xfffc0080
	s_addc_u32 s47, s5, -1
	s_cmp_eq_u32 s65, 12
	s_cselect_b64 vcc, -1, 0
	s_cselect_b32 s47, s37, s47
	s_cselect_b32 s46, s39, s46
	v_cndmask_b32_e32 v147, v145, v143, vcc
	v_cndmask_b32_e32 v146, v144, v142, vcc
	v_lshl_add_u64 v[220:221], s[4:5], 0, v[138:139]
	s_add_i32 m0, s43, 0xc000
	ds_read_b128 v[188:191], v153
	ds_read_b128 v[192:195], v153 offset:1024
	ds_read_b128 v[196:199], v153 offset:2048
	ds_read_b128 v[200:203], v153 offset:3072
	ds_read_b128 v[204:207], v153 offset:4096
	ds_read_b128 v[208:211], v153 offset:5120
	ds_read_b128 v[212:215], v153 offset:6144
	ds_read_b128 v[216:219], v153 offset:7168
	global_load_lds_dwordx4 v[220:221], off
	v_lshl_add_u64 v[220:221], s[4:5], 0, v[140:141]
	s_add_i32 m0, s43, 0xe000
	s_nop 0
	global_load_lds_dwordx4 v[220:221], off
	s_waitcnt vmcnt(8)
	s_waitcnt lgkmcnt(0)
	s_setprio 1
	s_waitcnt lgkmcnt(0)
	v_mfma_i32_16x16x64_i8 v[124:127], v[156:159], v[188:191], v[124:127]
	v_mfma_i32_16x16x64_i8 v[120:123], v[164:167], v[188:191], v[120:123]
	v_mfma_i32_16x16x64_i8 v[116:119], v[156:159], v[196:199], v[116:119]
	v_mfma_i32_16x16x64_i8 v[112:115], v[164:167], v[196:199], v[112:115]
	v_mfma_i32_16x16x64_i8 v[108:111], v[156:159], v[204:207], v[108:111]
	v_mfma_i32_16x16x64_i8 v[104:107], v[164:167], v[204:207], v[104:107]
	v_mfma_i32_16x16x64_i8 v[100:103], v[156:159], v[212:215], v[100:103]
	v_mfma_i32_16x16x64_i8 v[96:99], v[164:167], v[212:215], v[96:99]
	s_barrier
	v_mfma_i32_16x16x64_i8 v[124:127], v[160:163], v[192:195], v[124:127]
	v_mfma_i32_16x16x64_i8 v[120:123], v[168:171], v[192:195], v[120:123]
	v_mfma_i32_16x16x64_i8 v[116:119], v[160:163], v[200:203], v[116:119]
	v_mfma_i32_16x16x64_i8 v[112:115], v[168:171], v[200:203], v[112:115]
	v_mfma_i32_16x16x64_i8 v[108:111], v[160:163], v[208:211], v[108:111]
	v_mfma_i32_16x16x64_i8 v[104:107], v[168:171], v[208:211], v[104:107]
	v_mfma_i32_16x16x64_i8 v[100:103], v[160:163], v[216:219], v[100:103]
	v_mfma_i32_16x16x64_i8 v[96:99], v[168:171], v[216:219], v[96:99]
	s_setprio 0
	s_setprio 1
	v_mfma_i32_16x16x64_i8 v[92:95], v[172:175], v[188:191], v[92:95]
	v_mfma_i32_16x16x64_i8 v[88:91], v[180:183], v[188:191], v[88:91]
	v_mfma_i32_16x16x64_i8 v[84:87], v[172:175], v[196:199], v[84:87]
	v_mfma_i32_16x16x64_i8 v[80:83], v[180:183], v[196:199], v[80:83]
	v_mfma_i32_16x16x64_i8 v[76:79], v[172:175], v[204:207], v[76:79]
	v_mfma_i32_16x16x64_i8 v[72:75], v[180:183], v[204:207], v[72:75]
	v_mfma_i32_16x16x64_i8 v[68:71], v[172:175], v[212:215], v[68:71]
	v_mfma_i32_16x16x64_i8 v[64:67], v[180:183], v[212:215], v[64:67]
	v_mfma_i32_16x16x64_i8 v[92:95], v[176:179], v[192:195], v[92:95]
	v_mfma_i32_16x16x64_i8 v[88:91], v[184:187], v[192:195], v[88:91]
	v_mfma_i32_16x16x64_i8 v[84:87], v[176:179], v[200:203], v[84:87]
	v_mfma_i32_16x16x64_i8 v[80:83], v[184:187], v[200:203], v[80:83]
	v_mfma_i32_16x16x64_i8 v[76:79], v[176:179], v[208:211], v[76:79]
	v_mfma_i32_16x16x64_i8 v[72:75], v[184:187], v[208:211], v[72:75]
	v_mfma_i32_16x16x64_i8 v[68:71], v[176:179], v[216:219], v[68:71]
	v_mfma_i32_16x16x64_i8 v[64:67], v[184:187], v[216:219], v[64:67]
	s_setprio 0
	s_barrier
	s_add_i32 s66, s61, s34
	v_lshl_add_u64 v[220:221], v[146:147], 0, v[128:129]
	s_mov_b32 m0, s66
	ds_read_b128 v[188:191], v153 offset:16384
	ds_read_b128 v[192:195], v153 offset:17408
	ds_read_b128 v[196:199], v153 offset:18432
	ds_read_b128 v[200:203], v153 offset:19456
	ds_read_b128 v[204:207], v153 offset:20480
	ds_read_b128 v[208:211], v153 offset:21504
	ds_read_b128 v[212:215], v153 offset:22528
	ds_read_b128 v[216:219], v153 offset:23552
	global_load_lds_dwordx4 v[220:221], off
	v_lshl_add_u64 v[222:223], v[146:147], 0, v[134:135]
	s_add_i32 m0, s66, 0x2000
	v_lshl_add_u64 v[224:225], v[146:147], 0, s[12:13]
	s_add_i32 s66, s62, s34
	global_load_lds_dwordx4 v[222:223], off
	v_lshl_add_u64 v[226:227], v[224:225], 0, v[128:129]
	s_mov_b32 m0, s66
	v_lshl_add_u64 v[224:225], v[224:225], 0, v[134:135]
	global_load_lds_dwordx4 v[226:227], off
	s_add_i32 m0, s66, 0x2000
	v_lshl_add_u64 v[226:227], s[46:47], 0, v[136:137]
	global_load_lds_dwordx4 v[224:225], off
	v_lshl_add_u64 v[224:225], s[46:47], 0, v[132:133]
	s_mov_b32 m0, s43
	s_nop 0
	global_load_lds_dwordx4 v[224:225], off
	s_mov_b32 m0, s45
	s_nop 0
	global_load_lds_dwordx4 v[226:227], off
	s_waitcnt vmcnt(8)
	s_waitcnt lgkmcnt(0)
	s_setprio 1
	s_waitcnt lgkmcnt(0)
	v_mfma_i32_16x16x64_i8 v[60:63], v[156:159], v[188:191], v[60:63]
	v_mfma_i32_16x16x64_i8 v[56:59], v[164:167], v[188:191], v[56:59]
	v_mfma_i32_16x16x64_i8 v[52:55], v[156:159], v[196:199], v[52:55]
	v_mfma_i32_16x16x64_i8 v[48:51], v[164:167], v[196:199], v[48:51]
	v_mfma_i32_16x16x64_i8 v[44:47], v[156:159], v[204:207], v[44:47]
	v_mfma_i32_16x16x64_i8 v[40:43], v[164:167], v[204:207], v[40:43]
	v_mfma_i32_16x16x64_i8 v[36:39], v[156:159], v[212:215], v[36:39]
	v_mfma_i32_16x16x64_i8 v[32:35], v[164:167], v[212:215], v[32:35]
	s_barrier
; #define PG8_STAGE(bufoff, gbase, voff) do { _Pragma("unroll") for (int _i = 0; _i < 2; ++_i) \
;         __builtin_amdgcn_global_load_lds((const unsigned*)((const char*)(gbase) + (voff)[_i]), (LAS unsigned*)(lds + (bufoff) + ldsw + _i * 8192), 16, 0, 0); } while (0)
; #define PG8_LDA(dst, b, h) do { _Pragma("unroll") for (int m = 0; m < 4; ++m) _Pragma("unroll") for (int k = 0; k < 2; ++k) dst[m][k] = *(const LAS bf16x8*)(lds + PG8_SA(b, h) + aoff + m * 2048 + k * 1024); } while (0)
; #define PG8_LDB(dst, b, h) do { _Pragma("unroll") for (int n = 0; n < 2; ++n) _Pragma("unroll") for (int k = 0; k < 2; ++k) dst[n][k] = *(const LAS bf16x8*)(lds + PG8_SB(b, h) + boff + n * 2048 + k * 1024); } while (0)
; #define PG8_WAIT_V(n) asm volatile("s_waitcnt vmcnt(" #n ")" ::: "memory")
; #define PG8_WAIT_L(n) asm volatile("s_waitcnt lgkmcnt(" #n ")" ::: "memory")
; #define PG8_BAR __builtin_amdgcn_s_barrier()
; #define PG8_SCHED __builtin_amdgcn_sched_barrier(0)
;     ...
;             PG8_WAIT_V(8); PG8_WAIT_L(0); PG8_BAR; PG8_MMA(1, 0, At, B0); PG8_MMA(1, 1, At, B1); PG8_BAR; PG8_SCHED;
;             PG8_LDB(B0, 1, 0); PG8_LDB(B1, 1, 1); PG8_SCHED; PG8_LDA(At, 1, 0); PG8_STAGE(PG8_SA(0, 1), a2 + hstep, voffA);
;             PG8_WAIT_V(8); PG8_WAIT_L(0); PG8_BAR; PG8_MMA(0, 0, At, B0); PG8_MMA(0, 1, At, B1); PG8_BAR; PG8_SCHED;
	v_mfma_i32_16x16x64_i8 v[60:63], v[160:163], v[192:195], v[60:63]
	v_mfma_i32_16x16x64_i8 v[56:59], v[168:171], v[192:195], v[56:59]
	v_mfma_i32_16x16x64_i8 v[52:55], v[160:163], v[200:203], v[52:55]
	v_mfma_i32_16x16x64_i8 v[48:51], v[168:171], v[200:203], v[48:51]
	v_mfma_i32_16x16x64_i8 v[44:47], v[160:163], v[208:211], v[44:47]
	v_mfma_i32_16x16x64_i8 v[40:43], v[168:171], v[208:211], v[40:43]
	v_mfma_i32_16x16x64_i8 v[36:39], v[160:163], v[216:219], v[36:39]
	v_mfma_i32_16x16x64_i8 v[32:35], v[168:171], v[216:219], v[32:35]
	s_setprio 0
	s_setprio 1
	v_mfma_i32_16x16x64_i8 v[28:31], v[172:175], v[188:191], v[28:31]
	v_mfma_i32_16x16x64_i8 v[24:27], v[180:183], v[188:191], v[24:27]
	v_mfma_i32_16x16x64_i8 v[20:23], v[172:175], v[196:199], v[20:23]
	v_mfma_i32_16x16x64_i8 v[16:19], v[180:183], v[196:199], v[16:19]
	v_mfma_i32_16x16x64_i8 v[12:15], v[172:175], v[204:207], v[12:15]
	v_mfma_i32_16x16x64_i8 v[8:11], v[180:183], v[204:207], v[8:11]
	v_mfma_i32_16x16x64_i8 v[4:7], v[172:175], v[212:215], v[4:7]
	v_mfma_i32_16x16x64_i8 v[0:3], v[180:183], v[212:215], v[0:3]
	v_mfma_i32_16x16x64_i8 v[28:31], v[176:179], v[192:195], v[28:31]
	v_mfma_i32_16x16x64_i8 v[24:27], v[184:187], v[192:195], v[24:27]
	v_mfma_i32_16x16x64_i8 v[20:23], v[176:179], v[200:203], v[20:23]
	v_mfma_i32_16x16x64_i8 v[16:19], v[184:187], v[200:203], v[16:19]
	v_mfma_i32_16x16x64_i8 v[12:15], v[176:179], v[208:211], v[12:15]
	v_mfma_i32_16x16x64_i8 v[8:11], v[184:187], v[208:211], v[8:11]
	v_mfma_i32_16x16x64_i8 v[4:7], v[176:179], v[216:219], v[4:7]
	v_mfma_i32_16x16x64_i8 v[0:3], v[184:187], v[216:219], v[0:3]
	s_setprio 0
	s_barrier
	s_add_i32 s66, 0, 0x18000
	s_add_i32 s67, 0, 0x1c000
	v_add_u32_e32 v168, s66, v149
	v_add_u32_e32 v184, s67, v149
	ds_read_b128 v[156:159], v168
	ds_read_b128 v[160:163], v168 offset:1024
	ds_read_b128 v[164:167], v168 offset:2048
	ds_read_b128 v[168:171], v168 offset:3072
	ds_read_b128 v[172:175], v184
	ds_read_b128 v[176:179], v184 offset:1024
	ds_read_b128 v[180:183], v184 offset:2048
	ds_read_b128 v[184:187], v184 offset:3072
	s_add_u32 s46, s46, 0x40000
	s_addc_u32 s47, s47, 0
	s_mov_b32 m0, s51
	v_lshl_add_u64 v[228:229], s[46:47], 0, v[132:133]
	ds_read_b128 v[188:191], v153 offset:32768
	ds_read_b128 v[192:195], v153 offset:33792
	ds_read_b128 v[196:199], v153 offset:34816
	ds_read_b128 v[200:203], v153 offset:35840
	ds_read_b128 v[204:207], v153 offset:36864
	ds_read_b128 v[208:211], v153 offset:37888
	ds_read_b128 v[212:215], v153 offset:38912
	ds_read_b128 v[216:219], v153 offset:39936
	global_load_lds_dwordx4 v[228:229], off
	v_lshl_add_u64 v[228:229], s[46:47], 0, v[136:137]
	s_mov_b32 m0, s54
	s_nop 0
	global_load_lds_dwordx4 v[228:229], off
	s_waitcnt vmcnt(8)
	s_waitcnt lgkmcnt(0)
	s_setprio 1
	s_waitcnt lgkmcnt(0)
	v_mfma_i32_16x16x64_i8 v[124:127], v[156:159], v[188:191], v[124:127]
	v_mfma_i32_16x16x64_i8 v[120:123], v[164:167], v[188:191], v[120:123]
	v_mfma_i32_16x16x64_i8 v[116:119], v[156:159], v[196:199], v[116:119]
	v_mfma_i32_16x16x64_i8 v[112:115], v[164:167], v[196:199], v[112:115]
	v_mfma_i32_16x16x64_i8 v[108:111], v[156:159], v[204:207], v[108:111]
	v_mfma_i32_16x16x64_i8 v[104:107], v[164:167], v[204:207], v[104:107]
	v_mfma_i32_16x16x64_i8 v[100:103], v[156:159], v[212:215], v[100:103]
	v_mfma_i32_16x16x64_i8 v[96:99], v[164:167], v[212:215], v[96:99]
	s_barrier
	v_mfma_i32_16x16x64_i8 v[124:127], v[160:163], v[192:195], v[124:127]
	v_mfma_i32_16x16x64_i8 v[120:123], v[168:171], v[192:195], v[120:123]
	v_mfma_i32_16x16x64_i8 v[116:119], v[160:163], v[200:203], v[116:119]
	v_mfma_i32_16x16x64_i8 v[112:115], v[168:171], v[200:203], v[112:115]
	v_mfma_i32_16x16x64_i8 v[108:111], v[160:163], v[208:211], v[108:111]
	v_mfma_i32_16x16x64_i8 v[104:107], v[168:171], v[208:211], v[104:107]
	v_mfma_i32_16x16x64_i8 v[100:103], v[160:163], v[216:219], v[100:103]
	v_mfma_i32_16x16x64_i8 v[96:99], v[168:171], v[216:219], v[96:99]
	s_setprio 0
	s_setprio 1
	v_mfma_i32_16x16x64_i8 v[92:95], v[172:175], v[188:191], v[92:95]
	v_mfma_i32_16x16x64_i8 v[88:91], v[180:183], v[188:191], v[88:91]
	v_mfma_i32_16x16x64_i8 v[84:87], v[172:175], v[196:199], v[84:87]
	v_mfma_i32_16x16x64_i8 v[80:83], v[180:183], v[196:199], v[80:83]
	v_mfma_i32_16x16x64_i8 v[76:79], v[172:175], v[204:207], v[76:79]
	v_mfma_i32_16x16x64_i8 v[72:75], v[180:183], v[204:207], v[72:75]
	v_mfma_i32_16x16x64_i8 v[68:71], v[172:175], v[212:215], v[68:71]
	v_mfma_i32_16x16x64_i8 v[64:67], v[180:183], v[212:215], v[64:67]
	v_mfma_i32_16x16x64_i8 v[92:95], v[176:179], v[192:195], v[92:95]
	v_mfma_i32_16x16x64_i8 v[88:91], v[184:187], v[192:195], v[88:91]
	v_mfma_i32_16x16x64_i8 v[84:87], v[176:179], v[200:203], v[84:87]
	v_mfma_i32_16x16x64_i8 v[80:83], v[184:187], v[200:203], v[80:83]
	v_mfma_i32_16x16x64_i8 v[76:79], v[176:179], v[208:211], v[76:79]
	v_mfma_i32_16x16x64_i8 v[72:75], v[184:187], v[208:211], v[72:75]
	v_mfma_i32_16x16x64_i8 v[68:71], v[176:179], v[216:219], v[68:71]
	v_mfma_i32_16x16x64_i8 v[64:67], v[184:187], v[216:219], v[64:67]
	s_setprio 0
	s_barrier
; #define PG8_STAGE(bufoff, gbase, voff) do { _Pragma("unroll") for (int _i = 0; _i < 2; ++_i) \
;         __builtin_amdgcn_global_load_lds((const unsigned*)((const char*)(gbase) + (voff)[_i]), (LAS unsigned*)(lds + (bufoff) + ldsw + _i * 8192), 16, 0, 0); } while (0)
; #define PG8_LDA(dst, b, h) do { _Pragma("unroll") for (int m = 0; m < 4; ++m) _Pragma("unroll") for (int k = 0; k < 2; ++k) dst[m][k] = *(const LAS bf16x8*)(lds + PG8_SA(b, h) + aoff + m * 2048 + k * 1024); } while (0)
; #define PG8_WAIT_V(n) asm volatile("s_waitcnt vmcnt(" #n ")" ::: "memory")
; #define PG8_WAIT_L(n) asm volatile("s_waitcnt lgkmcnt(" #n ")" ::: "memory")
; #define PG8_BAR __builtin_amdgcn_s_barrier()
; #define PG8_SCHED __builtin_amdgcn_sched_barrier(0)
;     __device__ __forceinline__ float qscale(const Unit& u) const { return ((u.pn >= 8 && u.pn <= 11) || u.pn == 17) ? 0.5f : 1.0f; }
;     ...
;             PG8_LDA(At, 1, 1); PG8_STAGE(PG8_SB(1, 0), b3, voffB); PG8_STAGE(PG8_SB(1, 1), b3 + hstep, voffB); PG8_STAGE(PG8_SA(1, 0), a3, voffA);
;             PG8_WAIT_V(8); PG8_WAIT_L(0); PG8_BAR; PG8_MMA(1, 0, At, B0); PG8_MMA(1, 1, At, B1); PG8_BAR; PG8_SCHED;
;         }
;         if constexpr (QM == 2) { const float qs0_ = g.qs * E.qscale(cur), qs1_ = qs0_ * g.qs_b1; _Pragma("unroll") for (int a = 0; a < 2; ++a) _Pragma("unroll") for (int b = 0; b < 2; ++b) _Pragma("unroll") for (int m = 0; m < 4; ++m) _Pragma("unroll") for (int n = 0; n < 2; ++n) { const v4i t_ = __builtin_bit_cast(v4i, acc[a][b][m][n]); acc[a][b][m][n] = (f32x4){(float)t_[0], (float)t_[1], (float)t_[2], (float)t_[3]} * (b == 0 ? qs0_ : qs1_); } }
;         if constexpr (QM == 1) asm volatile("s_nop 15\n\ts_nop 15\n\ts_nop 15" ::: "memory");
;         if (wr == 0) PG8_BAR;
	s_add_i32 s46, s66, s34
	v_lshl_add_u64 v[220:221], v[220:221], 0, s[18:19]
	s_mov_b32 m0, s46
	ds_read_b128 v[188:191], v153 offset:49152
	ds_read_b128 v[192:195], v153 offset:50176
	ds_read_b128 v[196:199], v153 offset:51200
	ds_read_b128 v[200:203], v153 offset:52224
	ds_read_b128 v[204:207], v153 offset:53248
	ds_read_b128 v[208:211], v153 offset:54272
	ds_read_b128 v[212:215], v153 offset:55296
	ds_read_b128 v[216:219], v153 offset:56320
	global_load_lds_dwordx4 v[220:221], off
	v_lshl_add_u64 v[220:221], v[222:223], 0, s[18:19]
	s_add_i32 m0, s46, 0x2000
	v_lshl_add_u64 v[146:147], v[146:147], 0, s[20:21]
	s_add_i32 s46, s67, s34
	global_load_lds_dwordx4 v[220:221], off
	v_lshl_add_u64 v[220:221], v[146:147], 0, v[128:129]
	s_mov_b32 m0, s46
	v_lshl_add_u64 v[146:147], v[146:147], 0, v[134:135]
	global_load_lds_dwordx4 v[220:221], off
	s_add_i32 m0, s46, 0x2000
	s_nop 0
	global_load_lds_dwordx4 v[146:147], off
	v_lshl_add_u64 v[146:147], v[224:225], 0, s[18:19]
	s_mov_b32 m0, s58
	s_nop 0
	global_load_lds_dwordx4 v[146:147], off
	v_lshl_add_u64 v[146:147], v[226:227], 0, s[18:19]
	s_mov_b32 m0, s59
	s_nop 0
	global_load_lds_dwordx4 v[146:147], off
	s_waitcnt vmcnt(8)
	s_waitcnt lgkmcnt(0)
	s_setprio 1
	s_waitcnt lgkmcnt(0)
	v_mfma_i32_16x16x64_i8 v[60:63], v[156:159], v[188:191], v[60:63]
	v_mfma_i32_16x16x64_i8 v[56:59], v[164:167], v[188:191], v[56:59]
	v_mfma_i32_16x16x64_i8 v[52:55], v[156:159], v[196:199], v[52:55]
	v_mfma_i32_16x16x64_i8 v[48:51], v[164:167], v[196:199], v[48:51]
	v_mfma_i32_16x16x64_i8 v[44:47], v[156:159], v[204:207], v[44:47]
	v_mfma_i32_16x16x64_i8 v[40:43], v[164:167], v[204:207], v[40:43]
	v_mfma_i32_16x16x64_i8 v[36:39], v[156:159], v[212:215], v[36:39]
	v_mfma_i32_16x16x64_i8 v[32:35], v[164:167], v[212:215], v[32:35]
	s_barrier
	v_mfma_i32_16x16x64_i8 v[60:63], v[160:163], v[192:195], v[60:63]
	v_mfma_i32_16x16x64_i8 v[56:59], v[168:171], v[192:195], v[56:59]
	v_mfma_i32_16x16x64_i8 v[52:55], v[160:163], v[200:203], v[52:55]
	v_mfma_i32_16x16x64_i8 v[48:51], v[168:171], v[200:203], v[48:51]
	v_mfma_i32_16x16x64_i8 v[44:47], v[160:163], v[208:211], v[44:47]
	v_mfma_i32_16x16x64_i8 v[40:43], v[168:171], v[208:211], v[40:43]
	v_mfma_i32_16x16x64_i8 v[36:39], v[160:163], v[216:219], v[36:39]
	v_mfma_i32_16x16x64_i8 v[32:35], v[168:171], v[216:219], v[32:35]
	s_setprio 0
	s_setprio 1
	v_mfma_i32_16x16x64_i8 v[28:31], v[172:175], v[188:191], v[28:31]
	v_mfma_i32_16x16x64_i8 v[24:27], v[180:183], v[188:191], v[24:27]
	v_mfma_i32_16x16x64_i8 v[20:23], v[172:175], v[196:199], v[20:23]
	v_mfma_i32_16x16x64_i8 v[16:19], v[180:183], v[196:199], v[16:19]
	v_mfma_i32_16x16x64_i8 v[12:15], v[172:175], v[204:207], v[12:15]
	v_mfma_i32_16x16x64_i8 v[8:11], v[180:183], v[204:207], v[8:11]
	v_mfma_i32_16x16x64_i8 v[4:7], v[172:175], v[212:215], v[4:7]
	v_mfma_i32_16x16x64_i8 v[0:3], v[180:183], v[212:215], v[0:3]
	v_mfma_i32_16x16x64_i8 v[28:31], v[176:179], v[192:195], v[28:31]
	v_mfma_i32_16x16x64_i8 v[24:27], v[184:187], v[192:195], v[24:27]
	v_mfma_i32_16x16x64_i8 v[20:23], v[176:179], v[200:203], v[20:23]
	v_mfma_i32_16x16x64_i8 v[16:19], v[184:187], v[200:203], v[16:19]
	v_mfma_i32_16x16x64_i8 v[12:15], v[176:179], v[208:211], v[12:15]
	v_mfma_i32_16x16x64_i8 v[8:11], v[184:187], v[208:211], v[8:11]
	v_mfma_i32_16x16x64_i8 v[4:7], v[176:179], v[216:219], v[4:7]
	v_mfma_i32_16x16x64_i8 v[0:3], v[184:187], v[216:219], v[0:3]
	s_setprio 0
	s_barrier
	s_add_i32 s65, s65, 2
	s_add_u32 s4, s4, 0x100
	s_addc_u32 s5, s5, 0
	s_cmp_gt_u32 s65, 13
	v_lshl_add_u64 v[144:145], v[144:145], 0, s[26:27]
	s_cbranch_scc0 .LBB0_4738
	s_and_b64 vcc, exec, s[24:25]
	s_cbranch_vccz .LBB0_4741
	s_barrier

; #define PG8_STAGE(bufoff, gbase, voff) do { _Pragma("unroll") for (int _i = 0; _i < 2; ++_i) \
;         __builtin_amdgcn_global_load_lds((const unsigned*)((const char*)(gbase) + (voff)[_i]), (LAS unsigned*)(lds + (bufoff) + ldsw + _i * 8192), 16, 0, 0); } while (0)
; #define PG8_LDA(dst, b, h) do { _Pragma("unroll") for (int m = 0; m < 4; ++m) _Pragma("unroll") for (int k = 0; k < 2; ++k) dst[m][k] = *(const LAS bf16x8*)(lds + PG8_SA(b, h) + aoff + m * 2048 + k * 1024); } while (0)
; #define PG8_LDB(dst, b, h) do { _Pragma("unroll") for (int n = 0; n < 2; ++n) _Pragma("unroll") for (int k = 0; k < 2; ++k) dst[n][k] = *(const LAS bf16x8*)(lds + PG8_SB(b, h) + boff + n * 2048 + k * 1024); } while (0)
; #define PG8_WAIT_V(n) asm volatile("s_waitcnt vmcnt(" #n ")" ::: "memory")
; #define PG8_WAIT_L(n) asm volatile("s_waitcnt lgkmcnt(" #n ")" ::: "memory")
; #define PG8_BAR __builtin_amdgcn_s_barrier()
; #define PG8_SCHED __builtin_amdgcn_sched_barrier(0)
;     ...
;         for (int t = 0; t < nt; t += 2) {
;             const bool last = (t == nt - 2);
;             const char* a1 = cA + (size_t)(t + 1) * kstep;
;             const char* a2 = last ? nA : cA + (size_t)(t + 2) * kstep; const char* b2 = last ? nB : cB + (size_t)(t + 2) * kstep;
;             const char* a3 = a2 + kstep; const char* b3 = b2 + kstep;
;             PG8_LDB(B0, 0, 0); PG8_LDB(B1, 0, 1); PG8_SCHED; PG8_LDA(At, 0, 0); PG8_STAGE(PG8_SA(1, 1), a1 + hstep, voffA);
;             PG8_WAIT_V(8); PG8_WAIT_L(0); PG8_BAR; PG8_MMA(0, 0, At, B0); PG8_MMA(0, 1, At, B1); PG8_BAR; PG8_SCHED;
;             PG8_LDA(At, 0, 1); PG8_STAGE(PG8_SB(0, 0), b2, voffB); PG8_STAGE(PG8_SB(0, 1), b2 + hstep, voffB); PG8_STAGE(PG8_SA(0, 0), a2, voffA);
;             PG8_WAIT_V(8); PG8_WAIT_L(0); PG8_BAR; PG8_MMA(1, 0, At, B0); PG8_MMA(1, 1, At, B1); PG8_BAR; PG8_SCHED;
.LBB0_4813:
	ds_read_b128 v[24:27], v168
	ds_read_b128 v[28:31], v168 offset:1024
	ds_read_b128 v[16:19], v168 offset:2048
	ds_read_b128 v[20:23], v168 offset:3072
	ds_read_b128 v[8:11], v193
	ds_read_b128 v[12:15], v193 offset:1024
	ds_read_b128 v[0:3], v193 offset:2048
	ds_read_b128 v[4:7], v193 offset:3072
	s_add_u32 s36, s30, 0x100
	s_addc_u32 s37, s31, 0
	s_cmp_eq_u32 s66, 52
	s_cselect_b64 vcc, -1, 0
	s_cselect_b32 s39, s5, s37
	s_cselect_b32 s38, s4, s36
	v_cndmask_b32_e32 v181, v179, v177, vcc
	v_cndmask_b32_e32 v180, v178, v176, vcc
	v_lshl_add_u64 v[222:223], s[30:31], 0, v[170:171]
	s_add_i32 m0, s44, 0xc000
	ds_read_b128 v[182:185], v194
	ds_read_b128 v[186:189], v194 offset:1024
	ds_read_b128 v[198:201], v194 offset:2048
	ds_read_b128 v[202:205], v194 offset:3072
	ds_read_b128 v[206:209], v194 offset:4096
	ds_read_b128 v[210:213], v194 offset:5120
	ds_read_b128 v[214:217], v194 offset:6144
	ds_read_b128 v[218:221], v194 offset:7168
	global_load_lds_dwordx4 v[222:223], off
	v_lshl_add_u64 v[222:223], s[30:31], 0, v[172:173]
	s_add_i32 m0, s44, 0xe000
	s_nop 0
	global_load_lds_dwordx4 v[222:223], off
	s_waitcnt vmcnt(8)
	s_waitcnt lgkmcnt(0)
	s_setprio 1
	s_waitcnt lgkmcnt(0)
	v_mfma_scale_f32_16x16x128_f8f6f4 v[156:159], v[24:31], v[182:189], v[156:159], v195, v195 op_sel_hi:[0,0,0]
	v_mfma_scale_f32_16x16x128_f8f6f4 v[152:155], v[16:23], v[182:189], v[152:155], v195, v195 op_sel_hi:[0,0,0]
	v_mfma_scale_f32_16x16x128_f8f6f4 v[140:143], v[24:31], v[198:205], v[140:143], v195, v195 op_sel_hi:[0,0,0]
	v_mfma_scale_f32_16x16x128_f8f6f4 v[136:139], v[16:23], v[198:205], v[136:139], v195, v195 op_sel_hi:[0,0,0]
	s_barrier
	v_mfma_scale_f32_16x16x128_f8f6f4 v[124:127], v[24:31], v[206:213], v[124:127], v195, v195 op_sel_hi:[0,0,0]
	v_mfma_scale_f32_16x16x128_f8f6f4 v[120:123], v[16:23], v[206:213], v[120:123], v195, v195 op_sel_hi:[0,0,0]
	v_mfma_scale_f32_16x16x128_f8f6f4 v[108:111], v[24:31], v[214:221], v[108:111], v195, v195 op_sel_hi:[0,0,0]
	v_mfma_scale_f32_16x16x128_f8f6f4 v[104:107], v[16:23], v[214:221], v[104:107], v195, v195 op_sel_hi:[0,0,0]
	s_setprio 0
	s_setprio 1
	v_mfma_scale_f32_16x16x128_f8f6f4 v[148:151], v[8:15], v[182:189], v[148:151], v195, v195 op_sel_hi:[0,0,0]
	v_mfma_scale_f32_16x16x128_f8f6f4 v[144:147], v[0:7], v[182:189], v[144:147], v195, v195 op_sel_hi:[0,0,0]
	v_mfma_scale_f32_16x16x128_f8f6f4 v[132:135], v[8:15], v[198:205], v[132:135], v195, v195 op_sel_hi:[0,0,0]
	v_mfma_scale_f32_16x16x128_f8f6f4 v[128:131], v[0:7], v[198:205], v[128:131], v195, v195 op_sel_hi:[0,0,0]
	v_mfma_scale_f32_16x16x128_f8f6f4 v[116:119], v[8:15], v[206:213], v[116:119], v195, v195 op_sel_hi:[0,0,0]
	v_mfma_scale_f32_16x16x128_f8f6f4 v[112:115], v[0:7], v[206:213], v[112:115], v195, v195 op_sel_hi:[0,0,0]
	v_mfma_scale_f32_16x16x128_f8f6f4 v[100:103], v[8:15], v[214:221], v[100:103], v195, v195 op_sel_hi:[0,0,0]
	v_mfma_scale_f32_16x16x128_f8f6f4 v[96:99], v[0:7], v[214:221], v[96:99], v195, v195 op_sel_hi:[0,0,0]
	s_setprio 0
	s_barrier
	s_add_i32 s30, s54, s42
	v_lshl_add_u64 v[182:183], v[180:181], 0, v[160:161]
	s_mov_b32 m0, s30
	ds_read_b128 v[198:201], v194 offset:16384
	ds_read_b128 v[202:205], v194 offset:17408
	ds_read_b128 v[206:209], v194 offset:18432
	ds_read_b128 v[210:213], v194 offset:19456
	ds_read_b128 v[214:217], v194 offset:20480
	ds_read_b128 v[218:221], v194 offset:21504
	ds_read_b128 v[222:225], v194 offset:22528
	ds_read_b128 v[226:229], v194 offset:23552
	global_load_lds_dwordx4 v[182:183], off
	v_lshl_add_u64 v[184:185], v[180:181], 0, v[166:167]
	s_add_i32 m0, s30, 0x2000
	v_lshl_add_u64 v[186:187], v[180:181], 0, s[12:13]
	s_add_i32 s30, s55, s42
	global_load_lds_dwordx4 v[184:185], off
	v_lshl_add_u64 v[188:189], v[186:187], 0, v[160:161]
	s_mov_b32 m0, s30
	v_lshl_add_u64 v[186:187], v[186:187], 0, v[166:167]
	global_load_lds_dwordx4 v[188:189], off
	s_add_i32 m0, s30, 0x2000
	v_lshl_add_u64 v[188:189], s[38:39], 0, v[164:165]
	global_load_lds_dwordx4 v[186:187], off
	v_lshl_add_u64 v[186:187], s[38:39], 0, v[162:163]
	s_mov_b32 m0, s44
	s_nop 0
	global_load_lds_dwordx4 v[186:187], off
	s_mov_b32 m0, s45
	s_nop 0
	global_load_lds_dwordx4 v[188:189], off
	s_waitcnt vmcnt(8)
	s_waitcnt lgkmcnt(0)
	s_setprio 1
	s_waitcnt lgkmcnt(0)
	v_mfma_scale_f32_16x16x128_f8f6f4 v[92:95], v[24:31], v[198:205], v[92:95], v195, v195 op_sel_hi:[0,0,0]
	v_mfma_scale_f32_16x16x128_f8f6f4 v[88:91], v[16:23], v[198:205], v[88:91], v195, v195 op_sel_hi:[0,0,0]
	v_mfma_scale_f32_16x16x128_f8f6f4 v[76:79], v[24:31], v[206:213], v[76:79], v195, v195 op_sel_hi:[0,0,0]
	v_mfma_scale_f32_16x16x128_f8f6f4 v[72:75], v[16:23], v[206:213], v[72:75], v195, v195 op_sel_hi:[0,0,0]
	s_barrier
	v_mfma_scale_f32_16x16x128_f8f6f4 v[60:63], v[24:31], v[214:221], v[60:63], v195, v195 op_sel_hi:[0,0,0]
	v_mfma_scale_f32_16x16x128_f8f6f4 v[56:59], v[16:23], v[214:221], v[56:59], v195, v195 op_sel_hi:[0,0,0]
	v_mfma_scale_f32_16x16x128_f8f6f4 v[44:47], v[24:31], v[222:229], v[44:47], v195, v195 op_sel_hi:[0,0,0]
	v_mfma_scale_f32_16x16x128_f8f6f4 v[40:43], v[16:23], v[222:229], v[40:43], v195, v195 op_sel_hi:[0,0,0]
	s_setprio 0
	s_setprio 1
	v_mfma_scale_f32_16x16x128_f8f6f4 v[84:87], v[8:15], v[198:205], v[84:87], v195, v195 op_sel_hi:[0,0,0]
	v_mfma_scale_f32_16x16x128_f8f6f4 v[80:83], v[0:7], v[198:205], v[80:83], v195, v195 op_sel_hi:[0,0,0]
	v_mfma_scale_f32_16x16x128_f8f6f4 v[68:71], v[8:15], v[206:213], v[68:71], v195, v195 op_sel_hi:[0,0,0]
	v_mfma_scale_f32_16x16x128_f8f6f4 v[64:67], v[0:7], v[206:213], v[64:67], v195, v195 op_sel_hi:[0,0,0]
	v_mfma_scale_f32_16x16x128_f8f6f4 v[52:55], v[8:15], v[214:221], v[52:55], v195, v195 op_sel_hi:[0,0,0]
	v_mfma_scale_f32_16x16x128_f8f6f4 v[48:51], v[0:7], v[214:221], v[48:51], v195, v195 op_sel_hi:[0,0,0]
	v_mfma_scale_f32_16x16x128_f8f6f4 v[36:39], v[8:15], v[222:229], v[36:39], v195, v195 op_sel_hi:[0,0,0]
	v_mfma_scale_f32_16x16x128_f8f6f4 v[32:35], v[0:7], v[222:229], v[32:35], v195, v195 op_sel_hi:[0,0,0]
	s_setprio 0
	s_barrier
; #define PG8_STAGE(bufoff, gbase, voff) do { _Pragma("unroll") for (int _i = 0; _i < 2; ++_i) \
;         __builtin_amdgcn_global_load_lds((const unsigned*)((const char*)(gbase) + (voff)[_i]), (LAS unsigned*)(lds + (bufoff) + ldsw + _i * 8192), 16, 0, 0); } while (0)
; #define PG8_LDA(dst, b, h) do { _Pragma("unroll") for (int m = 0; m < 4; ++m) _Pragma("unroll") for (int k = 0; k < 2; ++k) dst[m][k] = *(const LAS bf16x8*)(lds + PG8_SA(b, h) + aoff + m * 2048 + k * 1024); } while (0)
; #define PG8_LDB(dst, b, h) do { _Pragma("unroll") for (int n = 0; n < 2; ++n) _Pragma("unroll") for (int k = 0; k < 2; ++k) dst[n][k] = *(const LAS bf16x8*)(lds + PG8_SB(b, h) + boff + n * 2048 + k * 1024); } while (0)
; #define PG8_WAIT_V(n) asm volatile("s_waitcnt vmcnt(" #n ")" ::: "memory")
; #define PG8_WAIT_L(n) asm volatile("s_waitcnt lgkmcnt(" #n ")" ::: "memory")
; #define PG8_BAR __builtin_amdgcn_s_barrier()
; #define PG8_SCHED __builtin_amdgcn_sched_barrier(0)
;     __device__ __forceinline__ float qscale(const Unit& u) const { return ((u.pn >= 8 && u.pn <= 11) || u.pn == 17) ? 0.5f : 1.0f; }
;     ...
;             PG8_LDB(B0, 1, 0); PG8_LDB(B1, 1, 1); PG8_SCHED; PG8_LDA(At, 1, 0); PG8_STAGE(PG8_SA(0, 1), a2 + hstep, voffA);
;             PG8_WAIT_V(8); PG8_WAIT_L(0); PG8_BAR; PG8_MMA(0, 0, At, B0); PG8_MMA(0, 1, At, B1); PG8_BAR; PG8_SCHED;
;             PG8_LDA(At, 1, 1); PG8_STAGE(PG8_SB(1, 0), b3, voffB); PG8_STAGE(PG8_SB(1, 1), b3 + hstep, voffB); PG8_STAGE(PG8_SA(1, 0), a3, voffA);
;             PG8_WAIT_V(8); PG8_WAIT_L(0); PG8_BAR; PG8_MMA(1, 0, At, B0); PG8_MMA(1, 1, At, B1); PG8_BAR; PG8_SCHED;
;         }
;         if constexpr (QM == 2) { const float qs0_ = g.qs * E.qscale(cur), qs1_ = qs0_ * g.qs_b1; _Pragma("unroll") for (int a = 0; a < 2; ++a) _Pragma("unroll") for (int b = 0; b < 2; ++b) _Pragma("unroll") for (int m = 0; m < 4; ++m) _Pragma("unroll") for (int n = 0; n < 2; ++n) { const v4i t_ = __builtin_bit_cast(v4i, acc[a][b][m][n]); acc[a][b][m][n] = (f32x4){(float)t_[0], (float)t_[1], (float)t_[2], (float)t_[3]} * (b == 0 ? qs0_ : qs1_); } }
;         if constexpr (QM == 1) asm volatile("s_nop 15\n\ts_nop 15\n\ts_nop 15" ::: "memory");
;         if (wr == 0) PG8_BAR;
	s_add_i32 s67, 0, 0x18000
	s_add_i32 s68, 0, 0x1c000
	v_add_u32_e32 v12, s67, v191
	v_add_u32_e32 v28, s68, v191
	ds_read_b128 v[0:3], v12
	ds_read_b128 v[4:7], v12 offset:1024
	ds_read_b128 v[8:11], v12 offset:2048
	ds_read_b128 v[12:15], v12 offset:3072
	ds_read_b128 v[16:19], v28
	ds_read_b128 v[20:23], v28 offset:1024
	ds_read_b128 v[24:27], v28 offset:2048
	ds_read_b128 v[28:31], v28 offset:3072
	s_add_u32 s30, s38, 0xe0000
	s_addc_u32 s31, s39, 0
	s_mov_b32 m0, s46
	v_lshl_add_u64 v[230:231], s[30:31], 0, v[162:163]
	ds_read_b128 v[198:201], v194 offset:32768
	ds_read_b128 v[202:205], v194 offset:33792
	ds_read_b128 v[206:209], v194 offset:34816
	ds_read_b128 v[210:213], v194 offset:35840
	ds_read_b128 v[214:217], v194 offset:36864
	ds_read_b128 v[218:221], v194 offset:37888
	ds_read_b128 v[222:225], v194 offset:38912
	ds_read_b128 v[226:229], v194 offset:39936
	global_load_lds_dwordx4 v[230:231], off
	v_lshl_add_u64 v[230:231], s[30:31], 0, v[164:165]
	s_mov_b32 m0, s47
	s_nop 0
	global_load_lds_dwordx4 v[230:231], off
	s_waitcnt vmcnt(8)
	s_waitcnt lgkmcnt(0)
	s_setprio 1
	s_waitcnt lgkmcnt(0)
	v_mfma_scale_f32_16x16x128_f8f6f4 v[156:159], v[0:7], v[198:205], v[156:159], v195, v195 op_sel_hi:[0,0,0]
	v_mfma_scale_f32_16x16x128_f8f6f4 v[152:155], v[8:15], v[198:205], v[152:155], v195, v195 op_sel_hi:[0,0,0]
	v_mfma_scale_f32_16x16x128_f8f6f4 v[140:143], v[0:7], v[206:213], v[140:143], v195, v195 op_sel_hi:[0,0,0]
	v_mfma_scale_f32_16x16x128_f8f6f4 v[136:139], v[8:15], v[206:213], v[136:139], v195, v195 op_sel_hi:[0,0,0]
	s_barrier
	v_mfma_scale_f32_16x16x128_f8f6f4 v[124:127], v[0:7], v[214:221], v[124:127], v195, v195 op_sel_hi:[0,0,0]
	v_mfma_scale_f32_16x16x128_f8f6f4 v[120:123], v[8:15], v[214:221], v[120:123], v195, v195 op_sel_hi:[0,0,0]
	v_mfma_scale_f32_16x16x128_f8f6f4 v[108:111], v[0:7], v[222:229], v[108:111], v195, v195 op_sel_hi:[0,0,0]
	v_mfma_scale_f32_16x16x128_f8f6f4 v[104:107], v[8:15], v[222:229], v[104:107], v195, v195 op_sel_hi:[0,0,0]
	s_setprio 0
	s_setprio 1
	v_mfma_scale_f32_16x16x128_f8f6f4 v[148:151], v[16:23], v[198:205], v[148:151], v195, v195 op_sel_hi:[0,0,0]
	v_mfma_scale_f32_16x16x128_f8f6f4 v[144:147], v[24:31], v[198:205], v[144:147], v195, v195 op_sel_hi:[0,0,0]
	v_mfma_scale_f32_16x16x128_f8f6f4 v[132:135], v[16:23], v[206:213], v[132:135], v195, v195 op_sel_hi:[0,0,0]
	v_mfma_scale_f32_16x16x128_f8f6f4 v[128:131], v[24:31], v[206:213], v[128:131], v195, v195 op_sel_hi:[0,0,0]
	v_mfma_scale_f32_16x16x128_f8f6f4 v[116:119], v[16:23], v[214:221], v[116:119], v195, v195 op_sel_hi:[0,0,0]
	v_mfma_scale_f32_16x16x128_f8f6f4 v[112:115], v[24:31], v[214:221], v[112:115], v195, v195 op_sel_hi:[0,0,0]
	v_mfma_scale_f32_16x16x128_f8f6f4 v[100:103], v[16:23], v[222:229], v[100:103], v195, v195 op_sel_hi:[0,0,0]
	v_mfma_scale_f32_16x16x128_f8f6f4 v[96:99], v[24:31], v[222:229], v[96:99], v195, v195 op_sel_hi:[0,0,0]
	s_setprio 0
	s_barrier
	s_add_i32 s30, s67, s42
	v_lshl_add_u64 v[182:183], v[182:183], 0, s[18:19]
	s_mov_b32 m0, s30
	ds_read_b128 v[198:201], v194 offset:49152
	ds_read_b128 v[202:205], v194 offset:50176
	ds_read_b128 v[206:209], v194 offset:51200
	ds_read_b128 v[210:213], v194 offset:52224
	ds_read_b128 v[214:217], v194 offset:53248
	ds_read_b128 v[218:221], v194 offset:54272
	ds_read_b128 v[222:225], v194 offset:55296
	ds_read_b128 v[226:229], v194 offset:56320
	global_load_lds_dwordx4 v[182:183], off
	v_lshl_add_u64 v[182:183], v[184:185], 0, s[18:19]
	s_add_i32 m0, s30, 0x2000
	v_lshl_add_u64 v[180:181], v[180:181], 0, s[20:21]
	s_add_i32 s30, s68, s42
	global_load_lds_dwordx4 v[182:183], off
	v_lshl_add_u64 v[182:183], v[180:181], 0, v[160:161]
	s_mov_b32 m0, s30
	v_lshl_add_u64 v[180:181], v[180:181], 0, v[166:167]
	global_load_lds_dwordx4 v[182:183], off
	s_add_i32 m0, s30, 0x2000
	s_nop 0
	global_load_lds_dwordx4 v[180:181], off
	v_lshl_add_u64 v[180:181], v[186:187], 0, s[18:19]
	s_mov_b32 m0, s48
	s_nop 0
	global_load_lds_dwordx4 v[180:181], off
	v_lshl_add_u64 v[180:181], v[188:189], 0, s[18:19]
	s_mov_b32 m0, s49
	s_nop 0
	global_load_lds_dwordx4 v[180:181], off
	s_waitcnt vmcnt(8)
	s_waitcnt lgkmcnt(0)
	s_setprio 1
	s_waitcnt lgkmcnt(0)
	v_mfma_scale_f32_16x16x128_f8f6f4 v[92:95], v[0:7], v[198:205], v[92:95], v195, v195 op_sel_hi:[0,0,0]
	v_mfma_scale_f32_16x16x128_f8f6f4 v[88:91], v[8:15], v[198:205], v[88:91], v195, v195 op_sel_hi:[0,0,0]
	v_mfma_scale_f32_16x16x128_f8f6f4 v[76:79], v[0:7], v[206:213], v[76:79], v195, v195 op_sel_hi:[0,0,0]
	v_mfma_scale_f32_16x16x128_f8f6f4 v[72:75], v[8:15], v[206:213], v[72:75], v195, v195 op_sel_hi:[0,0,0]
	s_barrier
	v_mfma_scale_f32_16x16x128_f8f6f4 v[60:63], v[0:7], v[214:221], v[60:63], v195, v195 op_sel_hi:[0,0,0]
	v_mfma_scale_f32_16x16x128_f8f6f4 v[56:59], v[8:15], v[214:221], v[56:59], v195, v195 op_sel_hi:[0,0,0]
	v_mfma_scale_f32_16x16x128_f8f6f4 v[44:47], v[0:7], v[222:229], v[44:47], v195, v195 op_sel_hi:[0,0,0]
	v_mfma_scale_f32_16x16x128_f8f6f4 v[40:43], v[8:15], v[222:229], v[40:43], v195, v195 op_sel_hi:[0,0,0]
	s_setprio 0
	s_setprio 1
	v_mfma_scale_f32_16x16x128_f8f6f4 v[84:87], v[16:23], v[198:205], v[84:87], v195, v195 op_sel_hi:[0,0,0]
	v_mfma_scale_f32_16x16x128_f8f6f4 v[80:83], v[24:31], v[198:205], v[80:83], v195, v195 op_sel_hi:[0,0,0]
	v_mfma_scale_f32_16x16x128_f8f6f4 v[68:71], v[16:23], v[206:213], v[68:71], v195, v195 op_sel_hi:[0,0,0]
	v_mfma_scale_f32_16x16x128_f8f6f4 v[64:67], v[24:31], v[206:213], v[64:67], v195, v195 op_sel_hi:[0,0,0]
	v_mfma_scale_f32_16x16x128_f8f6f4 v[52:55], v[16:23], v[214:221], v[52:55], v195, v195 op_sel_hi:[0,0,0]
	v_mfma_scale_f32_16x16x128_f8f6f4 v[48:51], v[24:31], v[214:221], v[48:51], v195, v195 op_sel_hi:[0,0,0]
	v_mfma_scale_f32_16x16x128_f8f6f4 v[36:39], v[16:23], v[222:229], v[36:39], v195, v195 op_sel_hi:[0,0,0]
	v_mfma_scale_f32_16x16x128_f8f6f4 v[32:35], v[24:31], v[222:229], v[32:35], v195, v195 op_sel_hi:[0,0,0]
	s_setprio 0
	s_barrier
	s_add_i32 s66, s66, 2
	v_lshl_add_u64 v[178:179], v[178:179], 0, s[26:27]
	s_cmp_gt_u32 s66, 53
	s_mov_b64 s[30:31], s[36:37]
	s_cbranch_scc0 .LBB0_4813
	s_nop 15
	s_nop 15
	s_nop 15
	s_and_b64 vcc, exec, s[24:25]
	s_cbranch_vccz .LBB0_4816
	s_barrier

; #define PG8_STAGE(bufoff, gbase, voff) do { _Pragma("unroll") for (int _i = 0; _i < 2; ++_i) \
;         __builtin_amdgcn_global_load_lds((const unsigned*)((const char*)(gbase) + (voff)[_i]), (LAS unsigned*)(lds + (bufoff) + ldsw + _i * 8192), 16, 0, 0); } while (0)
; #define PG8_LDA(dst, b, h) do { _Pragma("unroll") for (int m = 0; m < 4; ++m) _Pragma("unroll") for (int k = 0; k < 2; ++k) dst[m][k] = *(const LAS bf16x8*)(lds + PG8_SA(b, h) + aoff + m * 2048 + k * 1024); } while (0)
; #define PG8_LDB(dst, b, h) do { _Pragma("unroll") for (int n = 0; n < 2; ++n) _Pragma("unroll") for (int k = 0; k < 2; ++k) dst[n][k] = *(const LAS bf16x8*)(lds + PG8_SB(b, h) + boff + n * 2048 + k * 1024); } while (0)
; #define PG8_WAIT_V(n) asm volatile("s_waitcnt vmcnt(" #n ")" ::: "memory")
; #define PG8_WAIT_L(n) asm volatile("s_waitcnt lgkmcnt(" #n ")" ::: "memory")
; #define PG8_BAR __builtin_amdgcn_s_barrier()
; #define PG8_SCHED __builtin_amdgcn_sched_barrier(0)
;     ...
;         for (int t = 0; t < nt; t += 2) {
;             const bool last = (t == nt - 2);
;             const char* a1 = cA + (size_t)(t + 1) * kstep;
;             const char* a2 = last ? nA : cA + (size_t)(t + 2) * kstep; const char* b2 = last ? nB : cB + (size_t)(t + 2) * kstep;
;             const char* a3 = a2 + kstep; const char* b3 = b2 + kstep;
;             PG8_LDB(B0, 0, 0); PG8_LDB(B1, 0, 1); PG8_SCHED; PG8_LDA(At, 0, 0); PG8_STAGE(PG8_SA(1, 1), a1 + hstep, voffA);
;             PG8_WAIT_V(8); PG8_WAIT_L(0); PG8_BAR; PG8_MMA(0, 0, At, B0); PG8_MMA(0, 1, At, B1); PG8_BAR; PG8_SCHED;
;             PG8_LDA(At, 0, 1); PG8_STAGE(PG8_SB(0, 0), b2, voffB); PG8_STAGE(PG8_SB(0, 1), b2 + hstep, voffB); PG8_STAGE(PG8_SA(0, 0), a2, voffA);
;             PG8_WAIT_V(8); PG8_WAIT_L(0); PG8_BAR; PG8_MMA(1, 0, At, B0); PG8_MMA(1, 1, At, B1); PG8_BAR; PG8_SCHED;
.LBB0_4829:
	ds_read_b128 v[24:27], v183
	ds_read_b128 v[28:31], v183 offset:1024
	ds_read_b128 v[16:19], v183 offset:2048
	ds_read_b128 v[20:23], v183 offset:3072
	ds_read_b128 v[8:11], v184
	ds_read_b128 v[12:15], v184 offset:1024
	ds_read_b128 v[0:3], v184 offset:2048
	ds_read_b128 v[4:7], v184 offset:3072
	s_or_b32 s6, s12, 1
	s_lshl_b64 s[42:43], s[6:7], 7
	s_add_i32 s6, s12, 2
	s_lshl_b64 s[44:45], s[6:7], 7
	s_cmp_lg_u32 s12, s28
	s_cselect_b32 s44, s44, 0
	s_cselect_b32 s45, s45, 0
	s_add_u32 s12, s4, s44
	s_addc_u32 s13, s5, s45
	s_add_u32 s41, s4, s42
	v_lshl_add_u64 v[170:171], v[168:169], 0, s[44:45]
	s_addc_u32 s43, s5, s43
	s_add_u32 s42, s41, 0xe0000
	s_addc_u32 s43, s43, 0
	s_mov_b32 m0, s29
	v_lshl_add_u64 v[214:215], s[42:43], 0, v[166:167]
	ds_read_b128 v[172:175], v185
	ds_read_b128 v[176:179], v185 offset:1024
	ds_read_b128 v[190:193], v185 offset:2048
	ds_read_b128 v[194:197], v185 offset:3072
	ds_read_b128 v[198:201], v185 offset:4096
	ds_read_b128 v[202:205], v185 offset:5120
	ds_read_b128 v[206:209], v185 offset:6144
	ds_read_b128 v[210:213], v185 offset:7168
	global_load_lds_dwordx4 v[214:215], off
	v_lshl_add_u64 v[214:215], s[42:43], 0, v[164:165]
	s_mov_b32 m0, s30
	s_nop 0
	global_load_lds_dwordx4 v[214:215], off
	s_waitcnt vmcnt(8)
	s_waitcnt lgkmcnt(0)
	s_setprio 1
	s_waitcnt lgkmcnt(0)
	v_mfma_scale_f32_16x16x128_f8f6f4 v[156:159], v[24:31], v[172:179], v[156:159], v186, v186 op_sel_hi:[0,0,0]
	v_mfma_scale_f32_16x16x128_f8f6f4 v[152:155], v[16:23], v[172:179], v[152:155], v186, v186 op_sel_hi:[0,0,0]
	v_mfma_scale_f32_16x16x128_f8f6f4 v[140:143], v[24:31], v[190:197], v[140:143], v186, v186 op_sel_hi:[0,0,0]
	v_mfma_scale_f32_16x16x128_f8f6f4 v[136:139], v[16:23], v[190:197], v[136:139], v186, v186 op_sel_hi:[0,0,0]
	s_barrier
	v_mfma_scale_f32_16x16x128_f8f6f4 v[124:127], v[24:31], v[198:205], v[124:127], v186, v186 op_sel_hi:[0,0,0]
	v_mfma_scale_f32_16x16x128_f8f6f4 v[120:123], v[16:23], v[198:205], v[120:123], v186, v186 op_sel_hi:[0,0,0]
	v_mfma_scale_f32_16x16x128_f8f6f4 v[108:111], v[24:31], v[206:213], v[108:111], v186, v186 op_sel_hi:[0,0,0]
	v_mfma_scale_f32_16x16x128_f8f6f4 v[104:107], v[16:23], v[206:213], v[104:107], v186, v186 op_sel_hi:[0,0,0]
	s_setprio 0
	s_setprio 1
	v_mfma_scale_f32_16x16x128_f8f6f4 v[148:151], v[8:15], v[172:179], v[148:151], v186, v186 op_sel_hi:[0,0,0]
	v_mfma_scale_f32_16x16x128_f8f6f4 v[144:147], v[0:7], v[172:179], v[144:147], v186, v186 op_sel_hi:[0,0,0]
	v_mfma_scale_f32_16x16x128_f8f6f4 v[132:135], v[8:15], v[190:197], v[132:135], v186, v186 op_sel_hi:[0,0,0]
	v_mfma_scale_f32_16x16x128_f8f6f4 v[128:131], v[0:7], v[190:197], v[128:131], v186, v186 op_sel_hi:[0,0,0]
	v_mfma_scale_f32_16x16x128_f8f6f4 v[116:119], v[8:15], v[198:205], v[116:119], v186, v186 op_sel_hi:[0,0,0]
	v_mfma_scale_f32_16x16x128_f8f6f4 v[112:115], v[0:7], v[198:205], v[112:115], v186, v186 op_sel_hi:[0,0,0]
	v_mfma_scale_f32_16x16x128_f8f6f4 v[100:103], v[8:15], v[206:213], v[100:103], v186, v186 op_sel_hi:[0,0,0]
	v_mfma_scale_f32_16x16x128_f8f6f4 v[96:99], v[0:7], v[206:213], v[96:99], v186, v186 op_sel_hi:[0,0,0]
	s_setprio 0
	s_barrier
	s_mov_b32 m0, s31
	v_lshl_add_u64 v[172:173], v[170:171], 0, v[160:161]
	ds_read_b128 v[190:193], v185 offset:16384
	ds_read_b128 v[194:197], v185 offset:17408
	ds_read_b128 v[198:201], v185 offset:18432
	ds_read_b128 v[202:205], v185 offset:19456
	ds_read_b128 v[206:209], v185 offset:20480
	ds_read_b128 v[210:213], v185 offset:21504
	ds_read_b128 v[214:217], v185 offset:22528
	ds_read_b128 v[218:221], v185 offset:23552
	global_load_lds_dwordx4 v[172:173], off
	v_lshl_add_u64 v[174:175], v[170:171], 0, v[162:163]
	s_mov_b32 m0, s34
	v_lshl_add_u64 v[176:177], v[170:171], 0, s[2:3]
	global_load_lds_dwordx4 v[174:175], off
	v_lshl_add_u64 v[178:179], v[176:177], 0, v[160:161]
	s_mov_b32 m0, s35
	v_lshl_add_u64 v[176:177], v[176:177], 0, v[162:163]
	global_load_lds_dwordx4 v[178:179], off
	s_mov_b32 m0, s36
	v_lshl_add_u64 v[178:179], s[12:13], 0, v[164:165]
	global_load_lds_dwordx4 v[176:177], off
	v_lshl_add_u64 v[176:177], s[12:13], 0, v[166:167]
	s_mov_b32 m0, s19
	s_nop 0
	global_load_lds_dwordx4 v[176:177], off
	s_mov_b32 m0, s20
	s_nop 0
	global_load_lds_dwordx4 v[178:179], off
	s_waitcnt vmcnt(8)
	s_waitcnt lgkmcnt(0)
	s_setprio 1
	s_waitcnt lgkmcnt(0)
	v_mfma_scale_f32_16x16x128_f8f6f4 v[92:95], v[24:31], v[190:197], v[92:95], v186, v186 op_sel_hi:[0,0,0]
	v_mfma_scale_f32_16x16x128_f8f6f4 v[88:91], v[16:23], v[190:197], v[88:91], v186, v186 op_sel_hi:[0,0,0]
	v_mfma_scale_f32_16x16x128_f8f6f4 v[76:79], v[24:31], v[198:205], v[76:79], v186, v186 op_sel_hi:[0,0,0]
	v_mfma_scale_f32_16x16x128_f8f6f4 v[72:75], v[16:23], v[198:205], v[72:75], v186, v186 op_sel_hi:[0,0,0]
	s_barrier
	v_mfma_scale_f32_16x16x128_f8f6f4 v[60:63], v[24:31], v[206:213], v[60:63], v186, v186 op_sel_hi:[0,0,0]
	v_mfma_scale_f32_16x16x128_f8f6f4 v[56:59], v[16:23], v[206:213], v[56:59], v186, v186 op_sel_hi:[0,0,0]
	v_mfma_scale_f32_16x16x128_f8f6f4 v[44:47], v[24:31], v[214:221], v[44:47], v186, v186 op_sel_hi:[0,0,0]
	v_mfma_scale_f32_16x16x128_f8f6f4 v[40:43], v[16:23], v[214:221], v[40:43], v186, v186 op_sel_hi:[0,0,0]
	s_setprio 0
	s_setprio 1
	v_mfma_scale_f32_16x16x128_f8f6f4 v[84:87], v[8:15], v[190:197], v[84:87], v186, v186 op_sel_hi:[0,0,0]
	v_mfma_scale_f32_16x16x128_f8f6f4 v[80:83], v[0:7], v[190:197], v[80:83], v186, v186 op_sel_hi:[0,0,0]
	v_mfma_scale_f32_16x16x128_f8f6f4 v[68:71], v[8:15], v[198:205], v[68:71], v186, v186 op_sel_hi:[0,0,0]
	v_mfma_scale_f32_16x16x128_f8f6f4 v[64:67], v[0:7], v[198:205], v[64:67], v186, v186 op_sel_hi:[0,0,0]
	v_mfma_scale_f32_16x16x128_f8f6f4 v[52:55], v[8:15], v[206:213], v[52:55], v186, v186 op_sel_hi:[0,0,0]
	v_mfma_scale_f32_16x16x128_f8f6f4 v[48:51], v[0:7], v[206:213], v[48:51], v186, v186 op_sel_hi:[0,0,0]
	v_mfma_scale_f32_16x16x128_f8f6f4 v[36:39], v[8:15], v[214:221], v[36:39], v186, v186 op_sel_hi:[0,0,0]
	v_mfma_scale_f32_16x16x128_f8f6f4 v[32:35], v[0:7], v[214:221], v[32:35], v186, v186 op_sel_hi:[0,0,0]
	s_setprio 0
	s_barrier
; #define PG8_STAGE(bufoff, gbase, voff) do { _Pragma("unroll") for (int _i = 0; _i < 2; ++_i) \
;         __builtin_amdgcn_global_load_lds((const unsigned*)((const char*)(gbase) + (voff)[_i]), (LAS unsigned*)(lds + (bufoff) + ldsw + _i * 8192), 16, 0, 0); } while (0)
; #define PG8_LDA(dst, b, h) do { _Pragma("unroll") for (int m = 0; m < 4; ++m) _Pragma("unroll") for (int k = 0; k < 2; ++k) dst[m][k] = *(const LAS bf16x8*)(lds + PG8_SA(b, h) + aoff + m * 2048 + k * 1024); } while (0)
; #define PG8_LDB(dst, b, h) do { _Pragma("unroll") for (int n = 0; n < 2; ++n) _Pragma("unroll") for (int k = 0; k < 2; ++k) dst[n][k] = *(const LAS bf16x8*)(lds + PG8_SB(b, h) + boff + n * 2048 + k * 1024); } while (0)
; #define PG8_WAIT_V(n) asm volatile("s_waitcnt vmcnt(" #n ")" ::: "memory")
; #define PG8_WAIT_L(n) asm volatile("s_waitcnt lgkmcnt(" #n ")" ::: "memory")
; #define PG8_BAR __builtin_amdgcn_s_barrier()
; #define PG8_SCHED __builtin_amdgcn_sched_barrier(0)
;     __device__ __forceinline__ float qscale(const Unit& u) const { return ((u.pn >= 8 && u.pn <= 11) || u.pn == 17) ? 0.5f : 1.0f; }
;     ...
;             PG8_LDB(B0, 1, 0); PG8_LDB(B1, 1, 1); PG8_SCHED; PG8_LDA(At, 1, 0); PG8_STAGE(PG8_SA(0, 1), a2 + hstep, voffA);
;             PG8_WAIT_V(8); PG8_WAIT_L(0); PG8_BAR; PG8_MMA(0, 0, At, B0); PG8_MMA(0, 1, At, B1); PG8_BAR; PG8_SCHED;
;             PG8_LDA(At, 1, 1); PG8_STAGE(PG8_SB(1, 0), b3, voffB); PG8_STAGE(PG8_SB(1, 1), b3 + hstep, voffB); PG8_STAGE(PG8_SA(1, 0), a3, voffA);
;             PG8_WAIT_V(8); PG8_WAIT_L(0); PG8_BAR; PG8_MMA(1, 0, At, B0); PG8_MMA(1, 1, At, B1); PG8_BAR; PG8_SCHED;
;         }
;         if constexpr (QM == 2) { const float qs0_ = g.qs * E.qscale(cur), qs1_ = qs0_ * g.qs_b1; _Pragma("unroll") for (int a = 0; a < 2; ++a) _Pragma("unroll") for (int b = 0; b < 2; ++b) _Pragma("unroll") for (int m = 0; m < 4; ++m) _Pragma("unroll") for (int n = 0; n < 2; ++n) { const v4i t_ = __builtin_bit_cast(v4i, acc[a][b][m][n]); acc[a][b][m][n] = (f32x4){(float)t_[0], (float)t_[1], (float)t_[2], (float)t_[3]} * (b == 0 ? qs0_ : qs1_); } }
;         if constexpr (QM == 1) asm volatile("s_nop 15\n\ts_nop 15\n\ts_nop 15" ::: "memory");
;         if (wr == 0) PG8_BAR;
	ds_read_b128 v[0:3], v187
	ds_read_b128 v[4:7], v187 offset:1024
	ds_read_b128 v[8:11], v187 offset:2048
	ds_read_b128 v[12:15], v187 offset:3072
	ds_read_b128 v[16:19], v188
	ds_read_b128 v[20:23], v188 offset:1024
	ds_read_b128 v[24:27], v188 offset:2048
	ds_read_b128 v[28:31], v188 offset:3072
	s_add_u32 s12, s12, 0xe0000
	s_addc_u32 s13, s13, 0
	s_mov_b32 m0, s21
	v_lshl_add_u64 v[222:223], s[12:13], 0, v[166:167]
	ds_read_b128 v[190:193], v185 offset:32768
	ds_read_b128 v[194:197], v185 offset:33792
	ds_read_b128 v[198:201], v185 offset:34816
	ds_read_b128 v[202:205], v185 offset:35840
	ds_read_b128 v[206:209], v185 offset:36864
	ds_read_b128 v[210:213], v185 offset:37888
	ds_read_b128 v[214:217], v185 offset:38912
	ds_read_b128 v[218:221], v185 offset:39936
	global_load_lds_dwordx4 v[222:223], off
	v_lshl_add_u64 v[222:223], s[12:13], 0, v[164:165]
	s_mov_b32 m0, s24
	s_nop 0
	global_load_lds_dwordx4 v[222:223], off
	s_waitcnt vmcnt(8)
	s_waitcnt lgkmcnt(0)
	s_setprio 1
	s_waitcnt lgkmcnt(0)
	v_mfma_scale_f32_16x16x128_f8f6f4 v[156:159], v[0:7], v[190:197], v[156:159], v186, v186 op_sel_hi:[0,0,0]
	v_mfma_scale_f32_16x16x128_f8f6f4 v[152:155], v[8:15], v[190:197], v[152:155], v186, v186 op_sel_hi:[0,0,0]
	v_mfma_scale_f32_16x16x128_f8f6f4 v[140:143], v[0:7], v[198:205], v[140:143], v186, v186 op_sel_hi:[0,0,0]
	v_mfma_scale_f32_16x16x128_f8f6f4 v[136:139], v[8:15], v[198:205], v[136:139], v186, v186 op_sel_hi:[0,0,0]
	s_barrier
	v_mfma_scale_f32_16x16x128_f8f6f4 v[124:127], v[0:7], v[206:213], v[124:127], v186, v186 op_sel_hi:[0,0,0]
	v_mfma_scale_f32_16x16x128_f8f6f4 v[120:123], v[8:15], v[206:213], v[120:123], v186, v186 op_sel_hi:[0,0,0]
	v_mfma_scale_f32_16x16x128_f8f6f4 v[108:111], v[0:7], v[214:221], v[108:111], v186, v186 op_sel_hi:[0,0,0]
	v_mfma_scale_f32_16x16x128_f8f6f4 v[104:107], v[8:15], v[214:221], v[104:107], v186, v186 op_sel_hi:[0,0,0]
	s_setprio 0
	s_setprio 1
	v_mfma_scale_f32_16x16x128_f8f6f4 v[148:151], v[16:23], v[190:197], v[148:151], v186, v186 op_sel_hi:[0,0,0]
	v_mfma_scale_f32_16x16x128_f8f6f4 v[144:147], v[24:31], v[190:197], v[144:147], v186, v186 op_sel_hi:[0,0,0]
	v_mfma_scale_f32_16x16x128_f8f6f4 v[132:135], v[16:23], v[198:205], v[132:135], v186, v186 op_sel_hi:[0,0,0]
	v_mfma_scale_f32_16x16x128_f8f6f4 v[128:131], v[24:31], v[198:205], v[128:131], v186, v186 op_sel_hi:[0,0,0]
	v_mfma_scale_f32_16x16x128_f8f6f4 v[116:119], v[16:23], v[206:213], v[116:119], v186, v186 op_sel_hi:[0,0,0]
	v_mfma_scale_f32_16x16x128_f8f6f4 v[112:115], v[24:31], v[206:213], v[112:115], v186, v186 op_sel_hi:[0,0,0]
	v_mfma_scale_f32_16x16x128_f8f6f4 v[100:103], v[16:23], v[214:221], v[100:103], v186, v186 op_sel_hi:[0,0,0]
	v_mfma_scale_f32_16x16x128_f8f6f4 v[96:99], v[24:31], v[214:221], v[96:99], v186, v186 op_sel_hi:[0,0,0]
	s_setprio 0
	s_barrier
	s_mov_b32 m0, s37
	v_lshl_add_u64 v[172:173], v[172:173], 0, s[8:9]
	ds_read_b128 v[190:193], v185 offset:49152
	ds_read_b128 v[194:197], v185 offset:50176
	ds_read_b128 v[198:201], v185 offset:51200
	ds_read_b128 v[202:205], v185 offset:52224
	ds_read_b128 v[206:209], v185 offset:53248
	ds_read_b128 v[210:213], v185 offset:54272
	ds_read_b128 v[214:217], v185 offset:55296
	ds_read_b128 v[218:221], v185 offset:56320
	global_load_lds_dwordx4 v[172:173], off
	v_lshl_add_u64 v[172:173], v[174:175], 0, s[8:9]
	s_mov_b32 m0, s38
	v_lshl_add_u64 v[170:171], v[170:171], 0, s[10:11]
	global_load_lds_dwordx4 v[172:173], off
	v_lshl_add_u64 v[172:173], v[170:171], 0, v[160:161]
	s_mov_b32 m0, s39
	v_lshl_add_u64 v[170:171], v[170:171], 0, v[162:163]
	global_load_lds_dwordx4 v[172:173], off
	s_mov_b32 m0, s40
	s_nop 0
	global_load_lds_dwordx4 v[170:171], off
	v_lshl_add_u64 v[170:171], v[176:177], 0, s[8:9]
	s_mov_b32 m0, s26
	s_nop 0
	global_load_lds_dwordx4 v[170:171], off
	v_lshl_add_u64 v[170:171], v[178:179], 0, s[8:9]
	s_mov_b32 m0, s27
	s_nop 0
	global_load_lds_dwordx4 v[170:171], off
	s_waitcnt vmcnt(8)
	s_waitcnt lgkmcnt(0)
	s_setprio 1
	s_waitcnt lgkmcnt(0)
	v_mfma_scale_f32_16x16x128_f8f6f4 v[92:95], v[0:7], v[190:197], v[92:95], v186, v186 op_sel_hi:[0,0,0]
	v_mfma_scale_f32_16x16x128_f8f6f4 v[88:91], v[8:15], v[190:197], v[88:91], v186, v186 op_sel_hi:[0,0,0]
	v_mfma_scale_f32_16x16x128_f8f6f4 v[76:79], v[0:7], v[198:205], v[76:79], v186, v186 op_sel_hi:[0,0,0]
	v_mfma_scale_f32_16x16x128_f8f6f4 v[72:75], v[8:15], v[198:205], v[72:75], v186, v186 op_sel_hi:[0,0,0]
	s_barrier
	v_mfma_scale_f32_16x16x128_f8f6f4 v[60:63], v[0:7], v[206:213], v[60:63], v186, v186 op_sel_hi:[0,0,0]
	v_mfma_scale_f32_16x16x128_f8f6f4 v[56:59], v[8:15], v[206:213], v[56:59], v186, v186 op_sel_hi:[0,0,0]
	v_mfma_scale_f32_16x16x128_f8f6f4 v[44:47], v[0:7], v[214:221], v[44:47], v186, v186 op_sel_hi:[0,0,0]
	v_mfma_scale_f32_16x16x128_f8f6f4 v[40:43], v[8:15], v[214:221], v[40:43], v186, v186 op_sel_hi:[0,0,0]
	s_setprio 0
	s_setprio 1
	v_mfma_scale_f32_16x16x128_f8f6f4 v[84:87], v[16:23], v[190:197], v[84:87], v186, v186 op_sel_hi:[0,0,0]
	v_mfma_scale_f32_16x16x128_f8f6f4 v[80:83], v[24:31], v[190:197], v[80:83], v186, v186 op_sel_hi:[0,0,0]
	v_mfma_scale_f32_16x16x128_f8f6f4 v[68:71], v[16:23], v[198:205], v[68:71], v186, v186 op_sel_hi:[0,0,0]
	v_mfma_scale_f32_16x16x128_f8f6f4 v[64:67], v[24:31], v[198:205], v[64:67], v186, v186 op_sel_hi:[0,0,0]
	v_mfma_scale_f32_16x16x128_f8f6f4 v[52:55], v[16:23], v[206:213], v[52:55], v186, v186 op_sel_hi:[0,0,0]
	v_mfma_scale_f32_16x16x128_f8f6f4 v[48:51], v[24:31], v[206:213], v[48:51], v186, v186 op_sel_hi:[0,0,0]
	v_mfma_scale_f32_16x16x128_f8f6f4 v[36:39], v[16:23], v[214:221], v[36:39], v186, v186 op_sel_hi:[0,0,0]
	v_mfma_scale_f32_16x16x128_f8f6f4 v[32:35], v[24:31], v[214:221], v[32:35], v186, v186 op_sel_hi:[0,0,0]
	s_setprio 0
	s_barrier
	s_cmp_ge_u32 s6, s15
	s_mov_b32 s12, s6
	s_cbranch_scc0 .LBB0_4829
	s_nop 15
	s_nop 15
	s_nop 15
	s_cmpk_lt_u32 s14, 0x100
	s_cbranch_scc0 .LBB0_4832
	s_barrier
